# all loader-side VALU removed from GEMM main loops (saddr LDS-DMA with saved/ordered scalar bases)
# speedup vs baseline: 1.0088x; 1.0037x over previous
; #define PG8_STAGE(bufoff, gbase, voff) do { _Pragma("unroll") for (int _i = 0; _i < 2; ++_i) \
;         __builtin_amdgcn_global_load_lds((const unsigned*)((const char*)(gbase) + (voff)[_i]), (PG8_LAS unsigned*)(lds + (bufoff) + ldsw + _i * 8192), 16, 0, 0); } while (0)
; #define PG8_LDA(dst, b, h) do { _Pragma("unroll") for (int m = 0; m < 4; ++m) _Pragma("unroll") for (int k = 0; k < 2; ++k) dst[m][k] = *(const PG8_LAS bf16x8*)(lds + PG8_SA(b, h) + aoff + m * 2048 + k * 1024); } while (0)
; #define PG8_LDB(dst, b, h) do { _Pragma("unroll") for (int n = 0; n < 2; ++n) _Pragma("unroll") for (int k = 0; k < 2; ++k) dst[n][k] = *(const PG8_LAS bf16x8*)(lds + PG8_SB(b, h) + boff + n * 2048 + k * 1024); } while (0)
; #define PG8_MMA(ai, bj, At, Bt) do { __builtin_amdgcn_s_setprio(1); _Pragma("unroll") for (int m = 0; m < 4; ++m) _Pragma("unroll") for (int n = 0; n < 2; ++n) _Pragma("unroll") for (int k = 0; k < 2; ++k) \
;         acc[ai][bj][m][n] = __builtin_amdgcn_mfma_f32_16x16x32_bf16(Bt[n][k], At[m][k], acc[ai][bj][m][n], 0, 0, 0); __builtin_amdgcn_s_setprio(0); } while (0)
; #define PG8_WAIT_V(n) asm volatile("s_waitcnt vmcnt(" #n ")" ::: "memory")
; #define PG8_WAIT_L(n) asm volatile("s_waitcnt lgkmcnt(" #n ")" ::: "memory")
; template <class Epi, class Sched, bool ALIGN_EPI = false, bool SP2 = false>
; __device__ __forceinline__ void gemm_phase(PG8_LAS unsigned char* lds, const Gemm g, const Sched& S, const Epi& E) {
;     ...
;             const bool last = (t == nt - 2);
;             const char* a1 = cA + (size_t)(t + 1) * kstep;
;             const char* a2 = last ? nA : cA + (size_t)(t + 2) * kstep; const char* b2 = last ? nB : cB + (size_t)(t + 2) * kstep;
;             const char* a3 = a2 + kstep; const char* b3 = b2 + kstep;
;             if (last && has_next) S.a_ready(nxt);
;             if constexpr (SP2) {
;             PG8_LDB(B0, 0, 0); PG8_LDB(B1, 0, 1); PG8_SCHED; PG8_LDA(At, 0, 0); PG8_STAGE(PG8_SA(1, 1), a1 + hstep, voffA);
;             PG8_WAIT_V(8); PG8_WAIT_L(0); PG8_BAR; PG8_MMA(0, 0, At, B0); PG8_MMA(0, 1, At, B1); PG8_BAR; PG8_SCHED;
;             PG8_LDA(At, 0, 1); PG8_STAGE(PG8_SB(0, 0), b2, voffB); PG8_STAGE(PG8_SB(0, 1), b2 + hstep, voffB); PG8_STAGE(PG8_SA(0, 0), a2, voffA);
;             PG8_WAIT_V(8); PG8_WAIT_L(0); PG8_BAR; PG8_MMA(1, 0, At, B0); PG8_MMA(1, 1, At, B1); PG8_BAR; PG8_SCHED;
.LBB0_673:
	ds_read_b128 v[148:151], v241 offset:0
	ds_read_b128 v[156:159], v241 offset:1024
	ds_read_b128 v[166:169], v241 offset:2048
	ds_read_b128 v[170:173], v241 offset:3072
	ds_read_b128 v[174:177], v241 offset:16384
	ds_read_b128 v[178:181], v241 offset:17408
	ds_read_b128 v[182:185], v241 offset:18432
	ds_read_b128 v[186:189], v241 offset:19456
	s_add_u32 s20, s22, 0xfff00080
	s_addc_u32 s21, s23, -1
	s_cmp_eq_u32 s35, 60
	s_cselect_b32 s25, s11, s21
	s_cselect_b32 s24, s52, s20
	s_cselect_b32 s21, s13, s34
	s_cselect_b32 s20, s53, s62
	s_add_i32 m0, s19, 0xc000
	ds_read_b128 v[190:193], v161
	ds_read_b128 v[194:197], v161 offset:1024
	ds_read_b128 v[198:201], v161 offset:2048
	ds_read_b128 v[202:205], v161 offset:3072
	ds_read_b128 v[206:209], v161 offset:4096
	ds_read_b128 v[210:213], v161 offset:5120
	ds_read_b128 v[214:217], v161 offset:6144
	ds_read_b128 v[218:221], v161 offset:7168
	global_load_lds_dwordx4 v138, s[22:23]
	s_add_i32 m0, s19, 0xe000
	s_nop 0
	global_load_lds_dwordx4 v140, s[22:23]
	s_waitcnt vmcnt(8)
	s_waitcnt lgkmcnt(0)
	s_barrier
	s_waitcnt lgkmcnt(0)
	v_mfma_f32_16x16x32_bf16 v[118:121], v[148:151], v[190:193], v[118:121]
	v_mfma_f32_16x16x32_bf16 v[114:117], v[166:169], v[190:193], v[114:117]
	v_mfma_f32_16x16x32_bf16 v[102:105], v[148:151], v[198:201], v[102:105]
	v_mfma_f32_16x16x32_bf16 v[98:101], v[166:169], v[198:201], v[98:101]
	v_mfma_f32_16x16x32_bf16 v[86:89], v[148:151], v[206:209], v[86:89]
	v_mfma_f32_16x16x32_bf16 v[82:85], v[166:169], v[206:209], v[82:85]
	v_mfma_f32_16x16x32_bf16 v[70:73], v[148:151], v[214:217], v[70:73]
	v_mfma_f32_16x16x32_bf16 v[66:69], v[166:169], v[214:217], v[66:69]
	v_mfma_f32_16x16x32_bf16 v[118:121], v[156:159], v[194:197], v[118:121]
	v_mfma_f32_16x16x32_bf16 v[114:117], v[170:173], v[194:197], v[114:117]
	v_mfma_f32_16x16x32_bf16 v[102:105], v[156:159], v[202:205], v[102:105]
	v_mfma_f32_16x16x32_bf16 v[98:101], v[170:173], v[202:205], v[98:101]
	v_mfma_f32_16x16x32_bf16 v[86:89], v[156:159], v[210:213], v[86:89]
	v_mfma_f32_16x16x32_bf16 v[82:85], v[170:173], v[210:213], v[82:85]
	v_mfma_f32_16x16x32_bf16 v[70:73], v[156:159], v[218:221], v[70:73]
	v_mfma_f32_16x16x32_bf16 v[66:69], v[170:173], v[218:221], v[66:69]
	v_mfma_f32_16x16x32_bf16 v[126:129], v[174:177], v[190:193], v[126:129]
	v_mfma_f32_16x16x32_bf16 v[122:125], v[182:185], v[190:193], v[122:125]
	v_mfma_f32_16x16x32_bf16 v[110:113], v[174:177], v[198:201], v[110:113]
	v_mfma_f32_16x16x32_bf16 v[106:109], v[182:185], v[198:201], v[106:109]
	v_mfma_f32_16x16x32_bf16 v[94:97], v[174:177], v[206:209], v[94:97]
	v_mfma_f32_16x16x32_bf16 v[90:93], v[182:185], v[206:209], v[90:93]
	v_mfma_f32_16x16x32_bf16 v[78:81], v[174:177], v[214:217], v[78:81]
	v_mfma_f32_16x16x32_bf16 v[74:77], v[182:185], v[214:217], v[74:77]
	v_mfma_f32_16x16x32_bf16 v[126:129], v[178:181], v[194:197], v[126:129]
	v_mfma_f32_16x16x32_bf16 v[122:125], v[186:189], v[194:197], v[122:125]
	v_mfma_f32_16x16x32_bf16 v[110:113], v[178:181], v[202:205], v[110:113]
	v_mfma_f32_16x16x32_bf16 v[106:109], v[186:189], v[202:205], v[106:109]
	v_mfma_f32_16x16x32_bf16 v[94:97], v[178:181], v[210:213], v[94:97]
	v_mfma_f32_16x16x32_bf16 v[90:93], v[186:189], v[210:213], v[90:93]
	v_mfma_f32_16x16x32_bf16 v[78:81], v[178:181], v[218:221], v[78:81]
	v_mfma_f32_16x16x32_bf16 v[74:77], v[186:189], v[218:221], v[74:77]
	s_barrier
	s_add_i32 s63, s43, s26
	s_mov_b32 m0, s63
	ds_read_b128 v[190:193], v161 offset:16384
	ds_read_b128 v[194:197], v161 offset:17408
	ds_read_b128 v[198:201], v161 offset:18432
	ds_read_b128 v[202:205], v161 offset:19456
	ds_read_b128 v[206:209], v161 offset:20480
	ds_read_b128 v[210:213], v161 offset:21504
	ds_read_b128 v[214:217], v161 offset:22528
	ds_read_b128 v[218:221], v161 offset:23552
	global_load_lds_dwordx4 v132, s[20:21]
	s_add_i32 m0, s63, 0x2000
	s_add_u32 s64, s20, 0x100000
	s_addc_u32 s65, s21, 0
	s_add_i32 s63, s46, s26
	global_load_lds_dwordx4 v136, s[20:21]
	s_mov_b32 m0, s63
	s_add_u32 s100, s24, 0x80
	s_addc_u32 s101, s25, 0
	global_load_lds_dwordx4 v132, s[64:65]
	s_add_i32 m0, s63, 0x2000
	s_nop 0
	global_load_lds_dwordx4 v136, s[64:65]
	s_mov_b32 m0, s19
	s_nop 0
	global_load_lds_dwordx4 v130, s[24:25]
	s_mov_b32 m0, s29
	s_nop 0
	global_load_lds_dwordx4 v134, s[24:25]
	s_waitcnt vmcnt(8)
	s_waitcnt lgkmcnt(0)
	s_barrier
	s_waitcnt lgkmcnt(0)
	v_mfma_f32_16x16x32_bf16 v[54:57], v[148:151], v[190:193], v[54:57]
	v_mfma_f32_16x16x32_bf16 v[50:53], v[166:169], v[190:193], v[50:53]
	v_mfma_f32_16x16x32_bf16 v[38:41], v[148:151], v[198:201], v[38:41]
	v_mfma_f32_16x16x32_bf16 v[34:37], v[166:169], v[198:201], v[34:37]
	v_mfma_f32_16x16x32_bf16 v[22:25], v[148:151], v[206:209], v[22:25]
	v_mfma_f32_16x16x32_bf16 v[18:21], v[166:169], v[206:209], v[18:21]
	v_mfma_f32_16x16x32_bf16 v[6:9], v[148:151], v[214:217], v[6:9]
	v_mfma_f32_16x16x32_bf16 v[2:5], v[166:169], v[214:217], v[2:5]
	v_mfma_f32_16x16x32_bf16 v[54:57], v[156:159], v[194:197], v[54:57]
	v_mfma_f32_16x16x32_bf16 v[50:53], v[170:173], v[194:197], v[50:53]
	v_mfma_f32_16x16x32_bf16 v[38:41], v[156:159], v[202:205], v[38:41]
	v_mfma_f32_16x16x32_bf16 v[34:37], v[170:173], v[202:205], v[34:37]
	v_mfma_f32_16x16x32_bf16 v[22:25], v[156:159], v[210:213], v[22:25]
	v_mfma_f32_16x16x32_bf16 v[18:21], v[170:173], v[210:213], v[18:21]
	v_mfma_f32_16x16x32_bf16 v[6:9], v[156:159], v[218:221], v[6:9]
	v_mfma_f32_16x16x32_bf16 v[2:5], v[170:173], v[218:221], v[2:5]
	v_mfma_f32_16x16x32_bf16 v[62:65], v[174:177], v[190:193], v[62:65]
	v_mfma_f32_16x16x32_bf16 v[58:61], v[182:185], v[190:193], v[58:61]
	v_mfma_f32_16x16x32_bf16 v[46:49], v[174:177], v[198:201], v[46:49]
	v_mfma_f32_16x16x32_bf16 v[42:45], v[182:185], v[198:201], v[42:45]
	v_mfma_f32_16x16x32_bf16 v[30:33], v[174:177], v[206:209], v[30:33]
	v_mfma_f32_16x16x32_bf16 v[26:29], v[182:185], v[206:209], v[26:29]
	v_mfma_f32_16x16x32_bf16 v[10:13], v[174:177], v[214:217], v[10:13]
	v_mfma_f32_16x16x32_bf16 v[14:17], v[182:185], v[214:217], v[14:17]
	v_mfma_f32_16x16x32_bf16 v[62:65], v[178:181], v[194:197], v[62:65]
	v_mfma_f32_16x16x32_bf16 v[58:61], v[186:189], v[194:197], v[58:61]
	v_mfma_f32_16x16x32_bf16 v[46:49], v[178:181], v[202:205], v[46:49]
	v_mfma_f32_16x16x32_bf16 v[42:45], v[186:189], v[202:205], v[42:45]
	v_mfma_f32_16x16x32_bf16 v[30:33], v[178:181], v[210:213], v[30:33]
	v_mfma_f32_16x16x32_bf16 v[26:29], v[186:189], v[210:213], v[26:29]
	v_mfma_f32_16x16x32_bf16 v[10:13], v[178:181], v[218:221], v[10:13]
	v_mfma_f32_16x16x32_bf16 v[14:17], v[186:189], v[218:221], v[14:17]
	s_barrier
; #define PG8_STAGE(bufoff, gbase, voff) do { _Pragma("unroll") for (int _i = 0; _i < 2; ++_i) \
;         __builtin_amdgcn_global_load_lds((const unsigned*)((const char*)(gbase) + (voff)[_i]), (PG8_LAS unsigned*)(lds + (bufoff) + ldsw + _i * 8192), 16, 0, 0); } while (0)
; #define PG8_LDA(dst, b, h) do { _Pragma("unroll") for (int m = 0; m < 4; ++m) _Pragma("unroll") for (int k = 0; k < 2; ++k) dst[m][k] = *(const PG8_LAS bf16x8*)(lds + PG8_SA(b, h) + aoff + m * 2048 + k * 1024); } while (0)
; #define PG8_LDB(dst, b, h) do { _Pragma("unroll") for (int n = 0; n < 2; ++n) _Pragma("unroll") for (int k = 0; k < 2; ++k) dst[n][k] = *(const PG8_LAS bf16x8*)(lds + PG8_SB(b, h) + boff + n * 2048 + k * 1024); } while (0)
; #define PG8_MMA(ai, bj, At, Bt) do { __builtin_amdgcn_s_setprio(1); _Pragma("unroll") for (int m = 0; m < 4; ++m) _Pragma("unroll") for (int n = 0; n < 2; ++n) _Pragma("unroll") for (int k = 0; k < 2; ++k) \
;         acc[ai][bj][m][n] = __builtin_amdgcn_mfma_f32_16x16x32_bf16(Bt[n][k], At[m][k], acc[ai][bj][m][n], 0, 0, 0); __builtin_amdgcn_s_setprio(0); } while (0)
; #define PG8_WAIT_V(n) asm volatile("s_waitcnt vmcnt(" #n ")" ::: "memory")
; #define PG8_WAIT_L(n) asm volatile("s_waitcnt lgkmcnt(" #n ")" ::: "memory")
; #define PG8_BAR __builtin_amdgcn_s_barrier()
; #define PG8_SCHED __builtin_amdgcn_sched_barrier(0)
; template <class Epi, class Sched, bool ALIGN_EPI = false, bool SP2 = false>
; __device__ __forceinline__ void gemm_phase(PG8_LAS unsigned char* lds, const Gemm g, const Sched& S, const Epi& E) {
;     ...
;         for (int t = 0; t < nt; t += 2) {
;             const bool last = (t == nt - 2);
;     ...
;             PG8_LDB(B0, 1, 0); PG8_LDB(B1, 1, 1); PG8_SCHED; PG8_LDA(At, 1, 0); PG8_STAGE(PG8_SA(0, 1), a2 + hstep, voffA);
;             PG8_WAIT_V(8); PG8_WAIT_L(0); PG8_BAR; PG8_MMA(0, 0, At, B0); PG8_MMA(0, 1, At, B1); PG8_BAR; PG8_SCHED;
;             PG8_LDA(At, 1, 1); PG8_STAGE(PG8_SB(1, 0), b3, voffB); PG8_STAGE(PG8_SB(1, 1), b3 + hstep, voffB); PG8_STAGE(PG8_SA(1, 0), a3, voffA);
;             PG8_WAIT_V(8); PG8_WAIT_L(0); PG8_BAR; PG8_MMA(1, 0, At, B0); PG8_MMA(1, 1, At, B1); PG8_BAR; PG8_SCHED;
	s_add_i32 s63, 0, 0x18000
	s_add_i32 s64, 0, 0x1c000
	ds_read_b128 v[148:151], v241 offset:32768
	ds_read_b128 v[156:159], v241 offset:33792
	ds_read_b128 v[166:169], v241 offset:34816
	ds_read_b128 v[170:173], v241 offset:35840
	ds_read_b128 v[174:177], v241 offset:49152
	ds_read_b128 v[178:181], v241 offset:50176
	ds_read_b128 v[182:185], v241 offset:51200
	ds_read_b128 v[186:189], v241 offset:52224
	s_add_u32 s24, s24, 0x100000
	s_addc_u32 s25, s25, 0
	s_mov_b32 m0, s30
	ds_read_b128 v[190:193], v161 offset:32768
	ds_read_b128 v[194:197], v161 offset:33792
	ds_read_b128 v[198:201], v161 offset:34816
	ds_read_b128 v[202:205], v161 offset:35840
	ds_read_b128 v[206:209], v161 offset:36864
	ds_read_b128 v[210:213], v161 offset:37888
	ds_read_b128 v[214:217], v161 offset:38912
	ds_read_b128 v[218:221], v161 offset:39936
	global_load_lds_dwordx4 v130, s[24:25]
	s_mov_b32 m0, s31
	s_nop 0
	global_load_lds_dwordx4 v134, s[24:25]
	s_waitcnt vmcnt(8)
	s_waitcnt lgkmcnt(0)
	s_barrier
	s_waitcnt lgkmcnt(0)
	v_mfma_f32_16x16x32_bf16 v[118:121], v[148:151], v[190:193], v[118:121]
	v_mfma_f32_16x16x32_bf16 v[114:117], v[166:169], v[190:193], v[114:117]
	v_mfma_f32_16x16x32_bf16 v[102:105], v[148:151], v[198:201], v[102:105]
	v_mfma_f32_16x16x32_bf16 v[98:101], v[166:169], v[198:201], v[98:101]
	v_mfma_f32_16x16x32_bf16 v[86:89], v[148:151], v[206:209], v[86:89]
	v_mfma_f32_16x16x32_bf16 v[82:85], v[166:169], v[206:209], v[82:85]
	v_mfma_f32_16x16x32_bf16 v[70:73], v[148:151], v[214:217], v[70:73]
	v_mfma_f32_16x16x32_bf16 v[66:69], v[166:169], v[214:217], v[66:69]
	v_mfma_f32_16x16x32_bf16 v[118:121], v[156:159], v[194:197], v[118:121]
	v_mfma_f32_16x16x32_bf16 v[114:117], v[170:173], v[194:197], v[114:117]
	v_mfma_f32_16x16x32_bf16 v[102:105], v[156:159], v[202:205], v[102:105]
	v_mfma_f32_16x16x32_bf16 v[98:101], v[170:173], v[202:205], v[98:101]
	v_mfma_f32_16x16x32_bf16 v[86:89], v[156:159], v[210:213], v[86:89]
	v_mfma_f32_16x16x32_bf16 v[82:85], v[170:173], v[210:213], v[82:85]
	v_mfma_f32_16x16x32_bf16 v[70:73], v[156:159], v[218:221], v[70:73]
	v_mfma_f32_16x16x32_bf16 v[66:69], v[170:173], v[218:221], v[66:69]
	v_mfma_f32_16x16x32_bf16 v[126:129], v[174:177], v[190:193], v[126:129]
	v_mfma_f32_16x16x32_bf16 v[122:125], v[182:185], v[190:193], v[122:125]
	v_mfma_f32_16x16x32_bf16 v[110:113], v[174:177], v[198:201], v[110:113]
	v_mfma_f32_16x16x32_bf16 v[106:109], v[182:185], v[198:201], v[106:109]
	v_mfma_f32_16x16x32_bf16 v[94:97], v[174:177], v[206:209], v[94:97]
	v_mfma_f32_16x16x32_bf16 v[90:93], v[182:185], v[206:209], v[90:93]
	v_mfma_f32_16x16x32_bf16 v[78:81], v[174:177], v[214:217], v[78:81]
	v_mfma_f32_16x16x32_bf16 v[74:77], v[182:185], v[214:217], v[74:77]
	v_mfma_f32_16x16x32_bf16 v[126:129], v[178:181], v[194:197], v[126:129]
	v_mfma_f32_16x16x32_bf16 v[122:125], v[186:189], v[194:197], v[122:125]
	v_mfma_f32_16x16x32_bf16 v[110:113], v[178:181], v[202:205], v[110:113]
	v_mfma_f32_16x16x32_bf16 v[106:109], v[186:189], v[202:205], v[106:109]
	v_mfma_f32_16x16x32_bf16 v[94:97], v[178:181], v[210:213], v[94:97]
	v_mfma_f32_16x16x32_bf16 v[90:93], v[186:189], v[210:213], v[90:93]
	v_mfma_f32_16x16x32_bf16 v[78:81], v[178:181], v[218:221], v[78:81]
	v_mfma_f32_16x16x32_bf16 v[74:77], v[186:189], v[218:221], v[74:77]
	s_barrier
	s_add_i32 s24, s63, s26
	s_add_i32 m0, s24, 0xffffff80
	ds_read_b128 v[190:193], v161 offset:49152
	ds_read_b128 v[194:197], v161 offset:50176
	ds_read_b128 v[198:201], v161 offset:51200
	ds_read_b128 v[202:205], v161 offset:52224
	ds_read_b128 v[206:209], v161 offset:53248
	ds_read_b128 v[210:213], v161 offset:54272
	ds_read_b128 v[214:217], v161 offset:55296
	ds_read_b128 v[218:221], v161 offset:56320
	global_load_lds_dwordx4 v132, s[20:21] offset:128
	s_add_i32 m0, s24, 0x1f80
	s_add_i32 s24, s64, s26
	global_load_lds_dwordx4 v136, s[20:21] offset:128
	s_add_u32 s20, s20, 0x100080
	s_addc_u32 s21, s21, 0
	s_mov_b32 m0, s24
	s_nop 0
	global_load_lds_dwordx4 v132, s[20:21]
	s_add_i32 m0, s24, 0x2000
	s_nop 0
	global_load_lds_dwordx4 v136, s[20:21]
	s_mov_b32 m0, s40
	s_nop 0
	global_load_lds_dwordx4 v130, s[100:101]
	s_mov_b32 m0, s41
	s_nop 0
	global_load_lds_dwordx4 v134, s[100:101]
	s_waitcnt vmcnt(8)
	s_waitcnt lgkmcnt(0)
	s_barrier
	s_waitcnt lgkmcnt(0)
	v_mfma_f32_16x16x32_bf16 v[54:57], v[148:151], v[190:193], v[54:57]
	v_mfma_f32_16x16x32_bf16 v[50:53], v[166:169], v[190:193], v[50:53]
	v_mfma_f32_16x16x32_bf16 v[38:41], v[148:151], v[198:201], v[38:41]
	v_mfma_f32_16x16x32_bf16 v[34:37], v[166:169], v[198:201], v[34:37]
	v_mfma_f32_16x16x32_bf16 v[22:25], v[148:151], v[206:209], v[22:25]
	v_mfma_f32_16x16x32_bf16 v[18:21], v[166:169], v[206:209], v[18:21]
	v_mfma_f32_16x16x32_bf16 v[6:9], v[148:151], v[214:217], v[6:9]
	v_mfma_f32_16x16x32_bf16 v[2:5], v[166:169], v[214:217], v[2:5]
	v_mfma_f32_16x16x32_bf16 v[54:57], v[156:159], v[194:197], v[54:57]
	v_mfma_f32_16x16x32_bf16 v[50:53], v[170:173], v[194:197], v[50:53]
	v_mfma_f32_16x16x32_bf16 v[38:41], v[156:159], v[202:205], v[38:41]
	v_mfma_f32_16x16x32_bf16 v[34:37], v[170:173], v[202:205], v[34:37]
	v_mfma_f32_16x16x32_bf16 v[22:25], v[156:159], v[210:213], v[22:25]
	v_mfma_f32_16x16x32_bf16 v[18:21], v[170:173], v[210:213], v[18:21]
	v_mfma_f32_16x16x32_bf16 v[6:9], v[156:159], v[218:221], v[6:9]
	v_mfma_f32_16x16x32_bf16 v[2:5], v[170:173], v[218:221], v[2:5]
	v_mfma_f32_16x16x32_bf16 v[62:65], v[174:177], v[190:193], v[62:65]
	v_mfma_f32_16x16x32_bf16 v[58:61], v[182:185], v[190:193], v[58:61]
	v_mfma_f32_16x16x32_bf16 v[46:49], v[174:177], v[198:201], v[46:49]
	v_mfma_f32_16x16x32_bf16 v[42:45], v[182:185], v[198:201], v[42:45]
	v_mfma_f32_16x16x32_bf16 v[30:33], v[174:177], v[206:209], v[30:33]
	v_mfma_f32_16x16x32_bf16 v[26:29], v[182:185], v[206:209], v[26:29]
	v_mfma_f32_16x16x32_bf16 v[10:13], v[174:177], v[214:217], v[10:13]
	v_mfma_f32_16x16x32_bf16 v[14:17], v[182:185], v[214:217], v[14:17]
	v_mfma_f32_16x16x32_bf16 v[62:65], v[178:181], v[194:197], v[62:65]
	v_mfma_f32_16x16x32_bf16 v[58:61], v[186:189], v[194:197], v[58:61]
	v_mfma_f32_16x16x32_bf16 v[46:49], v[178:181], v[202:205], v[46:49]
	v_mfma_f32_16x16x32_bf16 v[42:45], v[186:189], v[202:205], v[42:45]
	v_mfma_f32_16x16x32_bf16 v[30:33], v[178:181], v[210:213], v[30:33]
	v_mfma_f32_16x16x32_bf16 v[26:29], v[186:189], v[210:213], v[26:29]
	v_mfma_f32_16x16x32_bf16 v[10:13], v[178:181], v[218:221], v[10:13]
	v_mfma_f32_16x16x32_bf16 v[14:17], v[186:189], v[218:221], v[14:17]
	s_barrier
	s_add_i32 s35, s35, 2
	s_add_u32 s22, s22, 0x100
	s_addc_u32 s23, s23, 0
	s_add_u32 s62, s62, 0x100
	s_addc_u32 s34, s34, 0
	s_cmp_gt_u32 s35, 61
	s_cbranch_scc0 .LBB0_673


; #define PG8_BAR __builtin_amdgcn_s_barrier()
; template <class Epi, class Sched, bool ALIGN_EPI = false, bool SP2 = false>
; __device__ __forceinline__ void gemm_phase(PG8_LAS unsigned char* lds, const Gemm g, const Sched& S, const Epi& E) {
;     ...
;         if constexpr (ALIGN_EPI) { if (wr == 0) PG8_BAR; }
;         if constexpr (!Epi::AFTER_DRAIN) { E(acc, cur, wr, wc, fr, fq); S.done(cur); }
;         if (!has_next) break;
	s_and_b64 vcc, exec, s[8:9]
	s_cbranch_vccz .LBB0_676
	s_barrier

; #define PG8_STAGE(bufoff, gbase, voff) do { _Pragma("unroll") for (int _i = 0; _i < 2; ++_i) \
;         __builtin_amdgcn_global_load_lds((const unsigned*)((const char*)(gbase) + (voff)[_i]), (PG8_LAS unsigned*)(lds + (bufoff) + ldsw + _i * 8192), 16, 0, 0); } while (0)
; #define PG8_LDA(dst, b, h) do { _Pragma("unroll") for (int m = 0; m < 4; ++m) _Pragma("unroll") for (int k = 0; k < 2; ++k) dst[m][k] = *(const PG8_LAS bf16x8*)(lds + PG8_SA(b, h) + aoff + m * 2048 + k * 1024); } while (0)
; #define PG8_LDB(dst, b, h) do { _Pragma("unroll") for (int n = 0; n < 2; ++n) _Pragma("unroll") for (int k = 0; k < 2; ++k) dst[n][k] = *(const PG8_LAS bf16x8*)(lds + PG8_SB(b, h) + boff + n * 2048 + k * 1024); } while (0)
; #define PG8_MMA(ai, bj, At, Bt) do { __builtin_amdgcn_s_setprio(1); _Pragma("unroll") for (int m = 0; m < 4; ++m) _Pragma("unroll") for (int n = 0; n < 2; ++n) _Pragma("unroll") for (int k = 0; k < 2; ++k) \
;         acc[ai][bj][m][n] = __builtin_amdgcn_mfma_f32_16x16x32_bf16(Bt[n][k], At[m][k], acc[ai][bj][m][n], 0, 0, 0); __builtin_amdgcn_s_setprio(0); } while (0)
; #define PG8_WAIT_V(n) asm volatile("s_waitcnt vmcnt(" #n ")" ::: "memory")
; #define PG8_WAIT_L(n) asm volatile("s_waitcnt lgkmcnt(" #n ")" ::: "memory")
; template <class Epi, class Sched, bool ALIGN_EPI = false, bool SP2 = false>
; __device__ __forceinline__ void gemm_phase(PG8_LAS unsigned char* lds, const Gemm g, const Sched& S, const Epi& E) {
;     ...
;             const bool last = (t == nt - 2);
;             const char* a1 = cA + (size_t)(t + 1) * kstep;
;             const char* a2 = last ? nA : cA + (size_t)(t + 2) * kstep; const char* b2 = last ? nB : cB + (size_t)(t + 2) * kstep;
;             const char* a3 = a2 + kstep; const char* b3 = b2 + kstep;
;             if (last && has_next) S.a_ready(nxt);
;             if constexpr (SP2) {
;             PG8_LDB(B0, 0, 0); PG8_LDB(B1, 0, 1); PG8_SCHED; PG8_LDA(At, 0, 0); PG8_STAGE(PG8_SA(1, 1), a1 + hstep, voffA);
;             PG8_WAIT_V(8); PG8_WAIT_L(0); PG8_BAR; PG8_MMA(0, 0, At, B0); PG8_MMA(0, 1, At, B1); PG8_BAR; PG8_SCHED;
;             PG8_LDA(At, 0, 1); PG8_STAGE(PG8_SB(0, 0), b2, voffB); PG8_STAGE(PG8_SB(0, 1), b2 + hstep, voffB); PG8_STAGE(PG8_SA(0, 0), a2, voffA);
;             PG8_WAIT_V(8); PG8_WAIT_L(0); PG8_BAR; PG8_MMA(1, 0, At, B0); PG8_MMA(1, 1, At, B1); PG8_BAR; PG8_SCHED;
.LBB0_1039:
	ds_read_b128 v[130:133], v241 offset:0
	ds_read_b128 v[134:137], v241 offset:1024
	ds_read_b128 v[138:141], v241 offset:2048
	ds_read_b128 v[142:145], v241 offset:3072
	ds_read_b128 v[146:149], v241 offset:16384
	ds_read_b128 v[150:153], v241 offset:17408
	ds_read_b128 v[172:175], v241 offset:18432
	ds_read_b128 v[176:179], v241 offset:19456
	s_add_u32 s24, s26, 0xfff00080
	s_addc_u32 s25, s27, -1
	s_cmp_eq_u32 s68, 60
	s_cselect_b32 s29, s15, s25
	s_cselect_b32 s28, s21, s24
	s_cselect_b32 s25, s13, s67
	s_cselect_b32 s24, s65, s66
	s_add_i32 m0, s23, 0xc000
	ds_read_b128 v[180:183], v185
	ds_read_b128 v[188:191], v185 offset:1024
	ds_read_b128 v[192:195], v185 offset:2048
	ds_read_b128 v[196:199], v185 offset:3072
	ds_read_b128 v[200:203], v185 offset:4096
	ds_read_b128 v[204:207], v185 offset:5120
	ds_read_b128 v[208:211], v185 offset:6144
	ds_read_b128 v[212:215], v185 offset:7168
	global_load_lds_dwordx4 v162, s[26:27]
	s_add_i32 m0, s23, 0xe000
	s_nop 0
	global_load_lds_dwordx4 v166, s[26:27]
	s_waitcnt vmcnt(8)
	s_waitcnt lgkmcnt(0)
	s_barrier
	s_waitcnt lgkmcnt(0)
	v_mfma_f32_16x16x32_bf16 v[114:117], v[130:133], v[180:183], v[114:117]
	v_mfma_f32_16x16x32_bf16 v[118:121], v[138:141], v[180:183], v[118:121]
	v_mfma_f32_16x16x32_bf16 v[106:109], v[130:133], v[192:195], v[106:109]
	v_mfma_f32_16x16x32_bf16 v[98:101], v[138:141], v[192:195], v[98:101]
	v_mfma_f32_16x16x32_bf16 v[90:93], v[130:133], v[200:203], v[90:93]
	v_mfma_f32_16x16x32_bf16 v[82:85], v[138:141], v[200:203], v[82:85]
	v_mfma_f32_16x16x32_bf16 v[74:77], v[130:133], v[208:211], v[74:77]
	v_mfma_f32_16x16x32_bf16 v[66:69], v[138:141], v[208:211], v[66:69]
	v_mfma_f32_16x16x32_bf16 v[114:117], v[134:137], v[188:191], v[114:117]
	v_mfma_f32_16x16x32_bf16 v[118:121], v[142:145], v[188:191], v[118:121]
	v_mfma_f32_16x16x32_bf16 v[106:109], v[134:137], v[196:199], v[106:109]
	v_mfma_f32_16x16x32_bf16 v[98:101], v[142:145], v[196:199], v[98:101]
	v_mfma_f32_16x16x32_bf16 v[90:93], v[134:137], v[204:207], v[90:93]
	v_mfma_f32_16x16x32_bf16 v[82:85], v[142:145], v[204:207], v[82:85]
	v_mfma_f32_16x16x32_bf16 v[74:77], v[134:137], v[212:215], v[74:77]
	v_mfma_f32_16x16x32_bf16 v[66:69], v[142:145], v[212:215], v[66:69]
	v_mfma_f32_16x16x32_bf16 v[122:125], v[146:149], v[180:183], v[122:125]
	v_mfma_f32_16x16x32_bf16 v[126:129], v[172:175], v[180:183], v[126:129]
	v_mfma_f32_16x16x32_bf16 v[110:113], v[146:149], v[192:195], v[110:113]
	v_mfma_f32_16x16x32_bf16 v[102:105], v[172:175], v[192:195], v[102:105]
	v_mfma_f32_16x16x32_bf16 v[94:97], v[146:149], v[200:203], v[94:97]
	v_mfma_f32_16x16x32_bf16 v[86:89], v[172:175], v[200:203], v[86:89]
	v_mfma_f32_16x16x32_bf16 v[78:81], v[146:149], v[208:211], v[78:81]
	v_mfma_f32_16x16x32_bf16 v[70:73], v[172:175], v[208:211], v[70:73]
	v_mfma_f32_16x16x32_bf16 v[122:125], v[150:153], v[188:191], v[122:125]
	v_mfma_f32_16x16x32_bf16 v[126:129], v[176:179], v[188:191], v[126:129]
	v_mfma_f32_16x16x32_bf16 v[110:113], v[150:153], v[196:199], v[110:113]
	v_mfma_f32_16x16x32_bf16 v[102:105], v[176:179], v[196:199], v[102:105]
	v_mfma_f32_16x16x32_bf16 v[94:97], v[150:153], v[204:207], v[94:97]
	v_mfma_f32_16x16x32_bf16 v[86:89], v[176:179], v[204:207], v[86:89]
	v_mfma_f32_16x16x32_bf16 v[78:81], v[150:153], v[212:215], v[78:81]
	v_mfma_f32_16x16x32_bf16 v[70:73], v[176:179], v[212:215], v[70:73]
	s_barrier
	s_add_i32 s33, s62, s36
	s_mov_b32 m0, s33
	ds_read_b128 v[180:183], v185 offset:16384
	ds_read_b128 v[188:191], v185 offset:17408
	ds_read_b128 v[192:195], v185 offset:18432
	ds_read_b128 v[196:199], v185 offset:19456
	ds_read_b128 v[200:203], v185 offset:20480
	ds_read_b128 v[204:207], v185 offset:21504
	ds_read_b128 v[208:211], v185 offset:22528
	ds_read_b128 v[212:215], v185 offset:23552
	global_load_lds_dwordx4 v156, s[24:25]
	s_add_i32 m0, s33, 0x2000
	s_add_u32 s72, s24, 0x100000
	s_addc_u32 s73, s25, 0
	s_add_i32 s33, s63, s36
	global_load_lds_dwordx4 v160, s[24:25]
	s_mov_b32 m0, s33
	s_add_u32 s100, s28, 0x80
	s_addc_u32 s101, s29, 0
	global_load_lds_dwordx4 v156, s[72:73]
	s_add_i32 m0, s33, 0x2000
	s_nop 0
	global_load_lds_dwordx4 v160, s[72:73]
	s_mov_b32 m0, s23
	s_nop 0
	global_load_lds_dwordx4 v154, s[28:29]
	s_mov_b32 m0, s37
	s_nop 0
	global_load_lds_dwordx4 v158, s[28:29]
	s_waitcnt vmcnt(8)
	s_waitcnt lgkmcnt(0)
	s_barrier
	s_waitcnt lgkmcnt(0)
	v_mfma_f32_16x16x32_bf16 v[58:61], v[130:133], v[180:183], v[58:61]
	v_mfma_f32_16x16x32_bf16 v[54:57], v[138:141], v[180:183], v[54:57]
	v_mfma_f32_16x16x32_bf16 v[42:45], v[130:133], v[192:195], v[42:45]
	v_mfma_f32_16x16x32_bf16 v[34:37], v[138:141], v[192:195], v[34:37]
	v_mfma_f32_16x16x32_bf16 v[26:29], v[130:133], v[200:203], v[26:29]
	v_mfma_f32_16x16x32_bf16 v[18:21], v[138:141], v[200:203], v[18:21]
	v_mfma_f32_16x16x32_bf16 v[6:9], v[130:133], v[208:211], v[6:9]
	v_mfma_f32_16x16x32_bf16 v[2:5], v[138:141], v[208:211], v[2:5]
	v_mfma_f32_16x16x32_bf16 v[58:61], v[134:137], v[188:191], v[58:61]
	v_mfma_f32_16x16x32_bf16 v[54:57], v[142:145], v[188:191], v[54:57]
	v_mfma_f32_16x16x32_bf16 v[42:45], v[134:137], v[196:199], v[42:45]
	v_mfma_f32_16x16x32_bf16 v[34:37], v[142:145], v[196:199], v[34:37]
	v_mfma_f32_16x16x32_bf16 v[26:29], v[134:137], v[204:207], v[26:29]
	v_mfma_f32_16x16x32_bf16 v[18:21], v[142:145], v[204:207], v[18:21]
	v_mfma_f32_16x16x32_bf16 v[6:9], v[134:137], v[212:215], v[6:9]
	v_mfma_f32_16x16x32_bf16 v[2:5], v[142:145], v[212:215], v[2:5]
	v_mfma_f32_16x16x32_bf16 v[62:65], v[146:149], v[180:183], v[62:65]
	v_mfma_f32_16x16x32_bf16 v[50:53], v[172:175], v[180:183], v[50:53]
	v_mfma_f32_16x16x32_bf16 v[46:49], v[146:149], v[192:195], v[46:49]
	v_mfma_f32_16x16x32_bf16 v[38:41], v[172:175], v[192:195], v[38:41]
	v_mfma_f32_16x16x32_bf16 v[30:33], v[146:149], v[200:203], v[30:33]
	v_mfma_f32_16x16x32_bf16 v[22:25], v[172:175], v[200:203], v[22:25]
	v_mfma_f32_16x16x32_bf16 v[10:13], v[146:149], v[208:211], v[10:13]
	v_mfma_f32_16x16x32_bf16 v[14:17], v[172:175], v[208:211], v[14:17]
	v_mfma_f32_16x16x32_bf16 v[62:65], v[150:153], v[188:191], v[62:65]
	v_mfma_f32_16x16x32_bf16 v[50:53], v[176:179], v[188:191], v[50:53]
	v_mfma_f32_16x16x32_bf16 v[46:49], v[150:153], v[196:199], v[46:49]
	v_mfma_f32_16x16x32_bf16 v[38:41], v[176:179], v[196:199], v[38:41]
	v_mfma_f32_16x16x32_bf16 v[30:33], v[150:153], v[204:207], v[30:33]
	v_mfma_f32_16x16x32_bf16 v[22:25], v[176:179], v[204:207], v[22:25]
	v_mfma_f32_16x16x32_bf16 v[10:13], v[150:153], v[212:215], v[10:13]
	v_mfma_f32_16x16x32_bf16 v[14:17], v[176:179], v[212:215], v[14:17]
	s_barrier
; #define PG8_STAGE(bufoff, gbase, voff) do { _Pragma("unroll") for (int _i = 0; _i < 2; ++_i) \
;         __builtin_amdgcn_global_load_lds((const unsigned*)((const char*)(gbase) + (voff)[_i]), (PG8_LAS unsigned*)(lds + (bufoff) + ldsw + _i * 8192), 16, 0, 0); } while (0)
; #define PG8_LDA(dst, b, h) do { _Pragma("unroll") for (int m = 0; m < 4; ++m) _Pragma("unroll") for (int k = 0; k < 2; ++k) dst[m][k] = *(const PG8_LAS bf16x8*)(lds + PG8_SA(b, h) + aoff + m * 2048 + k * 1024); } while (0)
; #define PG8_LDB(dst, b, h) do { _Pragma("unroll") for (int n = 0; n < 2; ++n) _Pragma("unroll") for (int k = 0; k < 2; ++k) dst[n][k] = *(const PG8_LAS bf16x8*)(lds + PG8_SB(b, h) + boff + n * 2048 + k * 1024); } while (0)
; #define PG8_MMA(ai, bj, At, Bt) do { __builtin_amdgcn_s_setprio(1); _Pragma("unroll") for (int m = 0; m < 4; ++m) _Pragma("unroll") for (int n = 0; n < 2; ++n) _Pragma("unroll") for (int k = 0; k < 2; ++k) \
;         acc[ai][bj][m][n] = __builtin_amdgcn_mfma_f32_16x16x32_bf16(Bt[n][k], At[m][k], acc[ai][bj][m][n], 0, 0, 0); __builtin_amdgcn_s_setprio(0); } while (0)
; #define PG8_WAIT_V(n) asm volatile("s_waitcnt vmcnt(" #n ")" ::: "memory")
; #define PG8_WAIT_L(n) asm volatile("s_waitcnt lgkmcnt(" #n ")" ::: "memory")
; #define PG8_BAR __builtin_amdgcn_s_barrier()
; #define PG8_SCHED __builtin_amdgcn_sched_barrier(0)
; template <class Epi, class Sched, bool ALIGN_EPI = false, bool SP2 = false>
; __device__ __forceinline__ void gemm_phase(PG8_LAS unsigned char* lds, const Gemm g, const Sched& S, const Epi& E) {
;     ...
;         for (int t = 0; t < nt; t += 2) {
;             const bool last = (t == nt - 2);
;     ...
;             PG8_LDB(B0, 1, 0); PG8_LDB(B1, 1, 1); PG8_SCHED; PG8_LDA(At, 1, 0); PG8_STAGE(PG8_SA(0, 1), a2 + hstep, voffA);
;             PG8_WAIT_V(8); PG8_WAIT_L(0); PG8_BAR; PG8_MMA(0, 0, At, B0); PG8_MMA(0, 1, At, B1); PG8_BAR; PG8_SCHED;
;             PG8_LDA(At, 1, 1); PG8_STAGE(PG8_SB(1, 0), b3, voffB); PG8_STAGE(PG8_SB(1, 1), b3 + hstep, voffB); PG8_STAGE(PG8_SA(1, 0), a3, voffA);
;             PG8_WAIT_V(8); PG8_WAIT_L(0); PG8_BAR; PG8_MMA(1, 0, At, B0); PG8_MMA(1, 1, At, B1); PG8_BAR; PG8_SCHED;
	s_add_i32 s33, 0, 0x18000
	s_add_i32 s42, 0, 0x1c000
	ds_read_b128 v[130:133], v241 offset:32768
	ds_read_b128 v[134:137], v241 offset:33792
	ds_read_b128 v[138:141], v241 offset:34816
	ds_read_b128 v[142:145], v241 offset:35840
	ds_read_b128 v[146:149], v241 offset:49152
	ds_read_b128 v[150:153], v241 offset:50176
	ds_read_b128 v[172:175], v241 offset:51200
	ds_read_b128 v[176:179], v241 offset:52224
	s_add_u32 s28, s28, 0x100000
	s_addc_u32 s29, s29, 0
	s_mov_b32 m0, s40
	ds_read_b128 v[180:183], v185 offset:32768
	ds_read_b128 v[188:191], v185 offset:33792
	ds_read_b128 v[192:195], v185 offset:34816
	ds_read_b128 v[196:199], v185 offset:35840
	ds_read_b128 v[200:203], v185 offset:36864
	ds_read_b128 v[204:207], v185 offset:37888
	ds_read_b128 v[208:211], v185 offset:38912
	ds_read_b128 v[212:215], v185 offset:39936
	global_load_lds_dwordx4 v154, s[28:29]
	s_mov_b32 m0, s41
	s_nop 0
	global_load_lds_dwordx4 v158, s[28:29]
	s_waitcnt vmcnt(8)
	s_waitcnt lgkmcnt(0)
	s_barrier
	s_waitcnt lgkmcnt(0)
	v_mfma_f32_16x16x32_bf16 v[114:117], v[130:133], v[180:183], v[114:117]
	v_mfma_f32_16x16x32_bf16 v[118:121], v[138:141], v[180:183], v[118:121]
	v_mfma_f32_16x16x32_bf16 v[106:109], v[130:133], v[192:195], v[106:109]
	v_mfma_f32_16x16x32_bf16 v[98:101], v[138:141], v[192:195], v[98:101]
	v_mfma_f32_16x16x32_bf16 v[90:93], v[130:133], v[200:203], v[90:93]
	v_mfma_f32_16x16x32_bf16 v[82:85], v[138:141], v[200:203], v[82:85]
	v_mfma_f32_16x16x32_bf16 v[74:77], v[130:133], v[208:211], v[74:77]
	v_mfma_f32_16x16x32_bf16 v[66:69], v[138:141], v[208:211], v[66:69]
	v_mfma_f32_16x16x32_bf16 v[114:117], v[134:137], v[188:191], v[114:117]
	v_mfma_f32_16x16x32_bf16 v[118:121], v[142:145], v[188:191], v[118:121]
	v_mfma_f32_16x16x32_bf16 v[106:109], v[134:137], v[196:199], v[106:109]
	v_mfma_f32_16x16x32_bf16 v[98:101], v[142:145], v[196:199], v[98:101]
	v_mfma_f32_16x16x32_bf16 v[90:93], v[134:137], v[204:207], v[90:93]
	v_mfma_f32_16x16x32_bf16 v[82:85], v[142:145], v[204:207], v[82:85]
	v_mfma_f32_16x16x32_bf16 v[74:77], v[134:137], v[212:215], v[74:77]
	v_mfma_f32_16x16x32_bf16 v[66:69], v[142:145], v[212:215], v[66:69]
	v_mfma_f32_16x16x32_bf16 v[122:125], v[146:149], v[180:183], v[122:125]
	v_mfma_f32_16x16x32_bf16 v[126:129], v[172:175], v[180:183], v[126:129]
	v_mfma_f32_16x16x32_bf16 v[110:113], v[146:149], v[192:195], v[110:113]
	v_mfma_f32_16x16x32_bf16 v[102:105], v[172:175], v[192:195], v[102:105]
	v_mfma_f32_16x16x32_bf16 v[94:97], v[146:149], v[200:203], v[94:97]
	v_mfma_f32_16x16x32_bf16 v[86:89], v[172:175], v[200:203], v[86:89]
	v_mfma_f32_16x16x32_bf16 v[78:81], v[146:149], v[208:211], v[78:81]
	v_mfma_f32_16x16x32_bf16 v[70:73], v[172:175], v[208:211], v[70:73]
	v_mfma_f32_16x16x32_bf16 v[122:125], v[150:153], v[188:191], v[122:125]
	v_mfma_f32_16x16x32_bf16 v[126:129], v[176:179], v[188:191], v[126:129]
	v_mfma_f32_16x16x32_bf16 v[110:113], v[150:153], v[196:199], v[110:113]
	v_mfma_f32_16x16x32_bf16 v[102:105], v[176:179], v[196:199], v[102:105]
	v_mfma_f32_16x16x32_bf16 v[94:97], v[150:153], v[204:207], v[94:97]
	v_mfma_f32_16x16x32_bf16 v[86:89], v[176:179], v[204:207], v[86:89]
	v_mfma_f32_16x16x32_bf16 v[78:81], v[150:153], v[212:215], v[78:81]
	v_mfma_f32_16x16x32_bf16 v[70:73], v[176:179], v[212:215], v[70:73]
	s_barrier
	s_add_i32 s28, s33, s36
	s_add_i32 m0, s28, 0xffffff80
	ds_read_b128 v[180:183], v185 offset:49152
	ds_read_b128 v[188:191], v185 offset:50176
	ds_read_b128 v[192:195], v185 offset:51200
	ds_read_b128 v[196:199], v185 offset:52224
	ds_read_b128 v[200:203], v185 offset:53248
	ds_read_b128 v[204:207], v185 offset:54272
	ds_read_b128 v[208:211], v185 offset:55296
	ds_read_b128 v[212:215], v185 offset:56320
	global_load_lds_dwordx4 v156, s[24:25] offset:128
	s_add_i32 m0, s28, 0x1f80
	s_add_i32 s28, s42, s36
	global_load_lds_dwordx4 v160, s[24:25] offset:128
	s_add_u32 s24, s24, 0x100080
	s_addc_u32 s25, s25, 0
	s_mov_b32 m0, s28
	s_nop 0
	global_load_lds_dwordx4 v156, s[24:25]
	s_add_i32 m0, s28, 0x2000
	s_nop 0
	global_load_lds_dwordx4 v160, s[24:25]
	s_mov_b32 m0, s46
	s_nop 0
	global_load_lds_dwordx4 v154, s[100:101]
	s_mov_b32 m0, s47
	s_nop 0
	global_load_lds_dwordx4 v158, s[100:101]
	s_waitcnt vmcnt(8)
	s_waitcnt lgkmcnt(0)
	s_barrier
	s_waitcnt lgkmcnt(0)
	v_mfma_f32_16x16x32_bf16 v[58:61], v[130:133], v[180:183], v[58:61]
	v_mfma_f32_16x16x32_bf16 v[54:57], v[138:141], v[180:183], v[54:57]
	v_mfma_f32_16x16x32_bf16 v[42:45], v[130:133], v[192:195], v[42:45]
	v_mfma_f32_16x16x32_bf16 v[34:37], v[138:141], v[192:195], v[34:37]
	v_mfma_f32_16x16x32_bf16 v[26:29], v[130:133], v[200:203], v[26:29]
	v_mfma_f32_16x16x32_bf16 v[18:21], v[138:141], v[200:203], v[18:21]
	v_mfma_f32_16x16x32_bf16 v[6:9], v[130:133], v[208:211], v[6:9]
	v_mfma_f32_16x16x32_bf16 v[2:5], v[138:141], v[208:211], v[2:5]
	v_mfma_f32_16x16x32_bf16 v[58:61], v[134:137], v[188:191], v[58:61]
	v_mfma_f32_16x16x32_bf16 v[54:57], v[142:145], v[188:191], v[54:57]
	v_mfma_f32_16x16x32_bf16 v[42:45], v[134:137], v[196:199], v[42:45]
	v_mfma_f32_16x16x32_bf16 v[34:37], v[142:145], v[196:199], v[34:37]
	v_mfma_f32_16x16x32_bf16 v[26:29], v[134:137], v[204:207], v[26:29]
	v_mfma_f32_16x16x32_bf16 v[18:21], v[142:145], v[204:207], v[18:21]
	v_mfma_f32_16x16x32_bf16 v[6:9], v[134:137], v[212:215], v[6:9]
	v_mfma_f32_16x16x32_bf16 v[2:5], v[142:145], v[212:215], v[2:5]
	v_mfma_f32_16x16x32_bf16 v[62:65], v[146:149], v[180:183], v[62:65]
	v_mfma_f32_16x16x32_bf16 v[50:53], v[172:175], v[180:183], v[50:53]
	v_mfma_f32_16x16x32_bf16 v[46:49], v[146:149], v[192:195], v[46:49]
	v_mfma_f32_16x16x32_bf16 v[38:41], v[172:175], v[192:195], v[38:41]
	v_mfma_f32_16x16x32_bf16 v[30:33], v[146:149], v[200:203], v[30:33]
	v_mfma_f32_16x16x32_bf16 v[22:25], v[172:175], v[200:203], v[22:25]
	v_mfma_f32_16x16x32_bf16 v[10:13], v[146:149], v[208:211], v[10:13]
	v_mfma_f32_16x16x32_bf16 v[14:17], v[172:175], v[208:211], v[14:17]
	v_mfma_f32_16x16x32_bf16 v[62:65], v[150:153], v[188:191], v[62:65]
	v_mfma_f32_16x16x32_bf16 v[50:53], v[176:179], v[188:191], v[50:53]
	v_mfma_f32_16x16x32_bf16 v[46:49], v[150:153], v[196:199], v[46:49]
	v_mfma_f32_16x16x32_bf16 v[38:41], v[176:179], v[196:199], v[38:41]
	v_mfma_f32_16x16x32_bf16 v[30:33], v[150:153], v[204:207], v[30:33]
	v_mfma_f32_16x16x32_bf16 v[22:25], v[176:179], v[204:207], v[22:25]
	v_mfma_f32_16x16x32_bf16 v[10:13], v[150:153], v[212:215], v[10:13]
	v_mfma_f32_16x16x32_bf16 v[14:17], v[176:179], v[212:215], v[14:17]
	s_barrier
	s_add_i32 s68, s68, 2
	s_add_u32 s26, s26, 0x100
	s_addc_u32 s27, s27, 0
	s_add_u32 s66, s66, 0x100
	s_addc_u32 s67, s67, 0
	s_cmp_gt_u32 s68, 61
	s_cbranch_scc0 .LBB0_1039


; #define PG8_BAR __builtin_amdgcn_s_barrier()
; template <class Epi, class Sched, bool ALIGN_EPI = false, bool SP2 = false>
; __device__ __forceinline__ void gemm_phase(PG8_LAS unsigned char* lds, const Gemm g, const Sched& S, const Epi& E) {
;     ...
;         if constexpr (ALIGN_EPI) { if (wr == 0) PG8_BAR; }
;         if constexpr (!Epi::AFTER_DRAIN) { E(acc, cur, wr, wc, fr, fq); S.done(cur); }
;         if (!has_next) break;
	s_and_b64 vcc, exec, s[10:11]
	s_cbranch_vccz .LBB0_1042
	s_barrier

; #define PG8_STAGE(bufoff, gbase, voff) do { _Pragma("unroll") for (int _i = 0; _i < 2; ++_i) \
;         __builtin_amdgcn_global_load_lds((const unsigned*)((const char*)(gbase) + (voff)[_i]), (PG8_LAS unsigned*)(lds + (bufoff) + ldsw + _i * 8192), 16, 0, 0); } while (0)
; #define PG8_LDA(dst, b, h) do { _Pragma("unroll") for (int m = 0; m < 4; ++m) _Pragma("unroll") for (int k = 0; k < 2; ++k) dst[m][k] = *(const PG8_LAS bf16x8*)(lds + PG8_SA(b, h) + aoff + m * 2048 + k * 1024); } while (0)
; #define PG8_LDB(dst, b, h) do { _Pragma("unroll") for (int n = 0; n < 2; ++n) _Pragma("unroll") for (int k = 0; k < 2; ++k) dst[n][k] = *(const PG8_LAS bf16x8*)(lds + PG8_SB(b, h) + boff + n * 2048 + k * 1024); } while (0)
; #define PG8_MMA(ai, bj, At, Bt) do { __builtin_amdgcn_s_setprio(1); _Pragma("unroll") for (int m = 0; m < 4; ++m) _Pragma("unroll") for (int n = 0; n < 2; ++n) _Pragma("unroll") for (int k = 0; k < 2; ++k) \
;         acc[ai][bj][m][n] = __builtin_amdgcn_mfma_f32_16x16x32_bf16(Bt[n][k], At[m][k], acc[ai][bj][m][n], 0, 0, 0); __builtin_amdgcn_s_setprio(0); } while (0)
; #define PG8_WAIT_V(n) asm volatile("s_waitcnt vmcnt(" #n ")" ::: "memory")
; #define PG8_WAIT_L(n) asm volatile("s_waitcnt lgkmcnt(" #n ")" ::: "memory")
; template <class Epi, class Sched, bool ALIGN_EPI = false, bool SP2 = false>
; __device__ __forceinline__ void gemm_phase(PG8_LAS unsigned char* lds, const Gemm g, const Sched& S, const Epi& E) {
;     ...
;             const bool last = (t == nt - 2);
;             const char* a1 = cA + (size_t)(t + 1) * kstep;
;             const char* a2 = last ? nA : cA + (size_t)(t + 2) * kstep; const char* b2 = last ? nB : cB + (size_t)(t + 2) * kstep;
;             const char* a3 = a2 + kstep; const char* b3 = b2 + kstep;
;             if (last && has_next) S.a_ready(nxt);
;             if constexpr (SP2) {
;             PG8_LDB(B0, 0, 0); PG8_LDB(B1, 0, 1); PG8_SCHED; PG8_LDA(At, 0, 0); PG8_STAGE(PG8_SA(1, 1), a1 + hstep, voffA);
;             PG8_WAIT_V(8); PG8_WAIT_L(0); PG8_BAR; PG8_MMA(0, 0, At, B0); PG8_MMA(0, 1, At, B1); PG8_BAR; PG8_SCHED;
;             PG8_LDA(At, 0, 1); PG8_STAGE(PG8_SB(0, 0), b2, voffB); PG8_STAGE(PG8_SB(0, 1), b2 + hstep, voffB); PG8_STAGE(PG8_SA(0, 0), a2, voffA);
;             PG8_WAIT_V(8); PG8_WAIT_L(0); PG8_BAR; PG8_MMA(1, 0, At, B0); PG8_MMA(1, 1, At, B1); PG8_BAR; PG8_SCHED;
.LBB0_1126:
	ds_read_b128 v[160:163], v241 offset:0
	ds_read_b128 v[166:169], v241 offset:1024
	ds_read_b128 v[170:173], v241 offset:2048
	ds_read_b128 v[174:177], v241 offset:3072
	ds_read_b128 v[178:181], v241 offset:16384
	ds_read_b128 v[182:185], v241 offset:17408
	ds_read_b128 v[186:189], v241 offset:18432
	ds_read_b128 v[190:193], v241 offset:19456
	s_add_u32 s22, s24, 0xfff00080
	s_addc_u32 s23, s25, -1
	s_cmp_eq_u32 s68, 60
	s_cselect_b32 s27, s15, s23
	s_cselect_b32 s26, s64, s22
	s_cselect_b32 s23, s13, s67
	s_cselect_b32 s22, s65, s66
	s_add_i32 m0, s21, 0xc000
	ds_read_b128 v[194:197], v155
	ds_read_b128 v[198:201], v155 offset:1024
	ds_read_b128 v[202:205], v155 offset:2048
	ds_read_b128 v[206:209], v155 offset:3072
	ds_read_b128 v[210:213], v155 offset:4096
	ds_read_b128 v[214:217], v155 offset:5120
	ds_read_b128 v[218:221], v155 offset:6144
	ds_read_b128 v[222:225], v155 offset:7168
	global_load_lds_dwordx4 v138, s[24:25]
	s_add_i32 m0, s21, 0xe000
	s_nop 0
	global_load_lds_dwordx4 v140, s[24:25]
	s_waitcnt vmcnt(8)
	s_waitcnt lgkmcnt(0)
	s_barrier
	s_waitcnt lgkmcnt(0)
	v_mfma_f32_16x16x32_bf16 v[122:125], v[160:163], v[194:197], v[122:125]
	v_mfma_f32_16x16x32_bf16 v[114:117], v[170:173], v[194:197], v[114:117]
	v_mfma_f32_16x16x32_bf16 v[106:109], v[160:163], v[202:205], v[106:109]
	v_mfma_f32_16x16x32_bf16 v[98:101], v[170:173], v[202:205], v[98:101]
	v_mfma_f32_16x16x32_bf16 v[90:93], v[160:163], v[210:213], v[90:93]
	v_mfma_f32_16x16x32_bf16 v[82:85], v[170:173], v[210:213], v[82:85]
	v_mfma_f32_16x16x32_bf16 v[74:77], v[160:163], v[218:221], v[74:77]
	v_mfma_f32_16x16x32_bf16 v[62:65], v[170:173], v[218:221], v[62:65]
	v_mfma_f32_16x16x32_bf16 v[122:125], v[166:169], v[198:201], v[122:125]
	v_mfma_f32_16x16x32_bf16 v[114:117], v[174:177], v[198:201], v[114:117]
	v_mfma_f32_16x16x32_bf16 v[106:109], v[166:169], v[206:209], v[106:109]
	v_mfma_f32_16x16x32_bf16 v[98:101], v[174:177], v[206:209], v[98:101]
	v_mfma_f32_16x16x32_bf16 v[90:93], v[166:169], v[214:217], v[90:93]
	v_mfma_f32_16x16x32_bf16 v[82:85], v[174:177], v[214:217], v[82:85]
	v_mfma_f32_16x16x32_bf16 v[74:77], v[166:169], v[222:225], v[74:77]
	v_mfma_f32_16x16x32_bf16 v[62:65], v[174:177], v[222:225], v[62:65]
	v_mfma_f32_16x16x32_bf16 v[126:129], v[178:181], v[194:197], v[126:129]
	v_mfma_f32_16x16x32_bf16 v[118:121], v[186:189], v[194:197], v[118:121]
	v_mfma_f32_16x16x32_bf16 v[110:113], v[178:181], v[202:205], v[110:113]
	v_mfma_f32_16x16x32_bf16 v[102:105], v[186:189], v[202:205], v[102:105]
	v_mfma_f32_16x16x32_bf16 v[94:97], v[178:181], v[210:213], v[94:97]
	v_mfma_f32_16x16x32_bf16 v[86:89], v[186:189], v[210:213], v[86:89]
	v_mfma_f32_16x16x32_bf16 v[78:81], v[178:181], v[218:221], v[78:81]
	v_mfma_f32_16x16x32_bf16 v[70:73], v[186:189], v[218:221], v[70:73]
	v_mfma_f32_16x16x32_bf16 v[126:129], v[182:185], v[198:201], v[126:129]
	v_mfma_f32_16x16x32_bf16 v[118:121], v[190:193], v[198:201], v[118:121]
	v_mfma_f32_16x16x32_bf16 v[110:113], v[182:185], v[206:209], v[110:113]
	v_mfma_f32_16x16x32_bf16 v[102:105], v[190:193], v[206:209], v[102:105]
	v_mfma_f32_16x16x32_bf16 v[94:97], v[182:185], v[214:217], v[94:97]
	v_mfma_f32_16x16x32_bf16 v[86:89], v[190:193], v[214:217], v[86:89]
	v_mfma_f32_16x16x32_bf16 v[78:81], v[182:185], v[222:225], v[78:81]
	v_mfma_f32_16x16x32_bf16 v[70:73], v[190:193], v[222:225], v[70:73]
	s_barrier
	s_add_i32 s33, s52, s29
	s_mov_b32 m0, s33
	ds_read_b128 v[194:197], v155 offset:16384
	ds_read_b128 v[198:201], v155 offset:17408
	ds_read_b128 v[202:205], v155 offset:18432
	ds_read_b128 v[206:209], v155 offset:19456
	ds_read_b128 v[210:213], v155 offset:20480
	ds_read_b128 v[214:217], v155 offset:21504
	ds_read_b128 v[218:221], v155 offset:22528
	ds_read_b128 v[222:225], v155 offset:23552
	global_load_lds_dwordx4 v132, s[22:23]
	s_add_i32 m0, s33, 0x2000
	s_add_u32 s72, s22, 0x100000
	s_addc_u32 s73, s23, 0
	s_add_i32 s33, s53, s29
	global_load_lds_dwordx4 v136, s[22:23]
	s_mov_b32 m0, s33
	s_add_u32 s100, s26, 0x80
	s_addc_u32 s101, s27, 0
	global_load_lds_dwordx4 v132, s[72:73]
	s_add_i32 m0, s33, 0x2000
	s_nop 0
	global_load_lds_dwordx4 v136, s[72:73]
	s_mov_b32 m0, s21
	s_nop 0
	global_load_lds_dwordx4 v130, s[26:27]
	s_mov_b32 m0, s36
	s_nop 0
	global_load_lds_dwordx4 v134, s[26:27]
	s_waitcnt vmcnt(8)
	s_waitcnt lgkmcnt(0)
	s_barrier
	s_waitcnt lgkmcnt(0)
	v_mfma_f32_16x16x32_bf16 v[58:61], v[160:163], v[194:197], v[58:61]
	v_mfma_f32_16x16x32_bf16 v[50:53], v[170:173], v[194:197], v[50:53]
	v_mfma_f32_16x16x32_bf16 v[42:45], v[160:163], v[202:205], v[42:45]
	v_mfma_f32_16x16x32_bf16 v[34:37], v[170:173], v[202:205], v[34:37]
	v_mfma_f32_16x16x32_bf16 v[26:29], v[160:163], v[210:213], v[26:29]
	v_mfma_f32_16x16x32_bf16 v[18:21], v[170:173], v[210:213], v[18:21]
	v_mfma_f32_16x16x32_bf16 v[10:13], v[160:163], v[218:221], v[10:13]
	v_mfma_f32_16x16x32_bf16 v[2:5], v[170:173], v[218:221], v[2:5]
	v_mfma_f32_16x16x32_bf16 v[58:61], v[166:169], v[198:201], v[58:61]
	v_mfma_f32_16x16x32_bf16 v[50:53], v[174:177], v[198:201], v[50:53]
	v_mfma_f32_16x16x32_bf16 v[42:45], v[166:169], v[206:209], v[42:45]
	v_mfma_f32_16x16x32_bf16 v[34:37], v[174:177], v[206:209], v[34:37]
	v_mfma_f32_16x16x32_bf16 v[26:29], v[166:169], v[214:217], v[26:29]
	v_mfma_f32_16x16x32_bf16 v[18:21], v[174:177], v[214:217], v[18:21]
	v_mfma_f32_16x16x32_bf16 v[10:13], v[166:169], v[222:225], v[10:13]
	v_mfma_f32_16x16x32_bf16 v[2:5], v[174:177], v[222:225], v[2:5]
	v_mfma_f32_16x16x32_bf16 v[66:69], v[178:181], v[194:197], v[66:69]
	v_mfma_f32_16x16x32_bf16 v[54:57], v[186:189], v[194:197], v[54:57]
	v_mfma_f32_16x16x32_bf16 v[46:49], v[178:181], v[202:205], v[46:49]
	v_mfma_f32_16x16x32_bf16 v[38:41], v[186:189], v[202:205], v[38:41]
	v_mfma_f32_16x16x32_bf16 v[30:33], v[178:181], v[210:213], v[30:33]
	v_mfma_f32_16x16x32_bf16 v[22:25], v[186:189], v[210:213], v[22:25]
	v_mfma_f32_16x16x32_bf16 v[14:17], v[178:181], v[218:221], v[14:17]
	v_mfma_f32_16x16x32_bf16 v[6:9], v[186:189], v[218:221], v[6:9]
	v_mfma_f32_16x16x32_bf16 v[66:69], v[182:185], v[198:201], v[66:69]
	v_mfma_f32_16x16x32_bf16 v[54:57], v[190:193], v[198:201], v[54:57]
	v_mfma_f32_16x16x32_bf16 v[46:49], v[182:185], v[206:209], v[46:49]
	v_mfma_f32_16x16x32_bf16 v[38:41], v[190:193], v[206:209], v[38:41]
	v_mfma_f32_16x16x32_bf16 v[30:33], v[182:185], v[214:217], v[30:33]
	v_mfma_f32_16x16x32_bf16 v[22:25], v[190:193], v[214:217], v[22:25]
	v_mfma_f32_16x16x32_bf16 v[14:17], v[182:185], v[222:225], v[14:17]
	v_mfma_f32_16x16x32_bf16 v[6:9], v[190:193], v[222:225], v[6:9]
	s_barrier
; #define PG8_STAGE(bufoff, gbase, voff) do { _Pragma("unroll") for (int _i = 0; _i < 2; ++_i) \
;         __builtin_amdgcn_global_load_lds((const unsigned*)((const char*)(gbase) + (voff)[_i]), (PG8_LAS unsigned*)(lds + (bufoff) + ldsw + _i * 8192), 16, 0, 0); } while (0)
; #define PG8_LDA(dst, b, h) do { _Pragma("unroll") for (int m = 0; m < 4; ++m) _Pragma("unroll") for (int k = 0; k < 2; ++k) dst[m][k] = *(const PG8_LAS bf16x8*)(lds + PG8_SA(b, h) + aoff + m * 2048 + k * 1024); } while (0)
; #define PG8_LDB(dst, b, h) do { _Pragma("unroll") for (int n = 0; n < 2; ++n) _Pragma("unroll") for (int k = 0; k < 2; ++k) dst[n][k] = *(const PG8_LAS bf16x8*)(lds + PG8_SB(b, h) + boff + n * 2048 + k * 1024); } while (0)
; #define PG8_MMA(ai, bj, At, Bt) do { __builtin_amdgcn_s_setprio(1); _Pragma("unroll") for (int m = 0; m < 4; ++m) _Pragma("unroll") for (int n = 0; n < 2; ++n) _Pragma("unroll") for (int k = 0; k < 2; ++k) \
;         acc[ai][bj][m][n] = __builtin_amdgcn_mfma_f32_16x16x32_bf16(Bt[n][k], At[m][k], acc[ai][bj][m][n], 0, 0, 0); __builtin_amdgcn_s_setprio(0); } while (0)
; #define PG8_WAIT_V(n) asm volatile("s_waitcnt vmcnt(" #n ")" ::: "memory")
; #define PG8_WAIT_L(n) asm volatile("s_waitcnt lgkmcnt(" #n ")" ::: "memory")
; #define PG8_BAR __builtin_amdgcn_s_barrier()
; #define PG8_SCHED __builtin_amdgcn_sched_barrier(0)
; template <class Epi, class Sched, bool ALIGN_EPI = false, bool SP2 = false>
; __device__ __forceinline__ void gemm_phase(PG8_LAS unsigned char* lds, const Gemm g, const Sched& S, const Epi& E) {
;     ...
;         for (int t = 0; t < nt; t += 2) {
;             const bool last = (t == nt - 2);
;     ...
;             PG8_LDB(B0, 1, 0); PG8_LDB(B1, 1, 1); PG8_SCHED; PG8_LDA(At, 1, 0); PG8_STAGE(PG8_SA(0, 1), a2 + hstep, voffA);
;             PG8_WAIT_V(8); PG8_WAIT_L(0); PG8_BAR; PG8_MMA(0, 0, At, B0); PG8_MMA(0, 1, At, B1); PG8_BAR; PG8_SCHED;
;             PG8_LDA(At, 1, 1); PG8_STAGE(PG8_SB(1, 0), b3, voffB); PG8_STAGE(PG8_SB(1, 1), b3 + hstep, voffB); PG8_STAGE(PG8_SA(1, 0), a3, voffA);
;             PG8_WAIT_V(8); PG8_WAIT_L(0); PG8_BAR; PG8_MMA(1, 0, At, B0); PG8_MMA(1, 1, At, B1); PG8_BAR; PG8_SCHED;
	s_add_i32 s33, 0, 0x18000
	s_add_i32 s42, 0, 0x1c000
	ds_read_b128 v[160:163], v241 offset:32768
	ds_read_b128 v[166:169], v241 offset:33792
	ds_read_b128 v[170:173], v241 offset:34816
	ds_read_b128 v[174:177], v241 offset:35840
	ds_read_b128 v[178:181], v241 offset:49152
	ds_read_b128 v[182:185], v241 offset:50176
	ds_read_b128 v[186:189], v241 offset:51200
	ds_read_b128 v[190:193], v241 offset:52224
	s_add_u32 s26, s26, 0x100000
	s_addc_u32 s27, s27, 0
	s_mov_b32 m0, s37
	ds_read_b128 v[194:197], v155 offset:32768
	ds_read_b128 v[198:201], v155 offset:33792
	ds_read_b128 v[202:205], v155 offset:34816
	ds_read_b128 v[206:209], v155 offset:35840
	ds_read_b128 v[210:213], v155 offset:36864
	ds_read_b128 v[214:217], v155 offset:37888
	ds_read_b128 v[218:221], v155 offset:38912
	ds_read_b128 v[222:225], v155 offset:39936
	global_load_lds_dwordx4 v130, s[26:27]
	s_mov_b32 m0, s40
	s_nop 0
	global_load_lds_dwordx4 v134, s[26:27]
	s_waitcnt vmcnt(8)
	s_waitcnt lgkmcnt(0)
	s_barrier
	s_waitcnt lgkmcnt(0)
	v_mfma_f32_16x16x32_bf16 v[122:125], v[160:163], v[194:197], v[122:125]
	v_mfma_f32_16x16x32_bf16 v[114:117], v[170:173], v[194:197], v[114:117]
	v_mfma_f32_16x16x32_bf16 v[106:109], v[160:163], v[202:205], v[106:109]
	v_mfma_f32_16x16x32_bf16 v[98:101], v[170:173], v[202:205], v[98:101]
	v_mfma_f32_16x16x32_bf16 v[90:93], v[160:163], v[210:213], v[90:93]
	v_mfma_f32_16x16x32_bf16 v[82:85], v[170:173], v[210:213], v[82:85]
	v_mfma_f32_16x16x32_bf16 v[74:77], v[160:163], v[218:221], v[74:77]
	v_mfma_f32_16x16x32_bf16 v[62:65], v[170:173], v[218:221], v[62:65]
	v_mfma_f32_16x16x32_bf16 v[122:125], v[166:169], v[198:201], v[122:125]
	v_mfma_f32_16x16x32_bf16 v[114:117], v[174:177], v[198:201], v[114:117]
	v_mfma_f32_16x16x32_bf16 v[106:109], v[166:169], v[206:209], v[106:109]
	v_mfma_f32_16x16x32_bf16 v[98:101], v[174:177], v[206:209], v[98:101]
	v_mfma_f32_16x16x32_bf16 v[90:93], v[166:169], v[214:217], v[90:93]
	v_mfma_f32_16x16x32_bf16 v[82:85], v[174:177], v[214:217], v[82:85]
	v_mfma_f32_16x16x32_bf16 v[74:77], v[166:169], v[222:225], v[74:77]
	v_mfma_f32_16x16x32_bf16 v[62:65], v[174:177], v[222:225], v[62:65]
	v_mfma_f32_16x16x32_bf16 v[126:129], v[178:181], v[194:197], v[126:129]
	v_mfma_f32_16x16x32_bf16 v[118:121], v[186:189], v[194:197], v[118:121]
	v_mfma_f32_16x16x32_bf16 v[110:113], v[178:181], v[202:205], v[110:113]
	v_mfma_f32_16x16x32_bf16 v[102:105], v[186:189], v[202:205], v[102:105]
	v_mfma_f32_16x16x32_bf16 v[94:97], v[178:181], v[210:213], v[94:97]
	v_mfma_f32_16x16x32_bf16 v[86:89], v[186:189], v[210:213], v[86:89]
	v_mfma_f32_16x16x32_bf16 v[78:81], v[178:181], v[218:221], v[78:81]
	v_mfma_f32_16x16x32_bf16 v[70:73], v[186:189], v[218:221], v[70:73]
	v_mfma_f32_16x16x32_bf16 v[126:129], v[182:185], v[198:201], v[126:129]
	v_mfma_f32_16x16x32_bf16 v[118:121], v[190:193], v[198:201], v[118:121]
	v_mfma_f32_16x16x32_bf16 v[110:113], v[182:185], v[206:209], v[110:113]
	v_mfma_f32_16x16x32_bf16 v[102:105], v[190:193], v[206:209], v[102:105]
	v_mfma_f32_16x16x32_bf16 v[94:97], v[182:185], v[214:217], v[94:97]
	v_mfma_f32_16x16x32_bf16 v[86:89], v[190:193], v[214:217], v[86:89]
	v_mfma_f32_16x16x32_bf16 v[78:81], v[182:185], v[222:225], v[78:81]
	v_mfma_f32_16x16x32_bf16 v[70:73], v[190:193], v[222:225], v[70:73]
	s_barrier
	s_add_i32 s26, s33, s29
	s_add_i32 m0, s26, 0xffffff80
	ds_read_b128 v[194:197], v155 offset:49152
	ds_read_b128 v[198:201], v155 offset:50176
	ds_read_b128 v[202:205], v155 offset:51200
	ds_read_b128 v[206:209], v155 offset:52224
	ds_read_b128 v[210:213], v155 offset:53248
	ds_read_b128 v[214:217], v155 offset:54272
	ds_read_b128 v[218:221], v155 offset:55296
	ds_read_b128 v[222:225], v155 offset:56320
	global_load_lds_dwordx4 v132, s[22:23] offset:128
	s_add_i32 m0, s26, 0x1f80
	s_add_i32 s26, s42, s29
	global_load_lds_dwordx4 v136, s[22:23] offset:128
	s_add_u32 s22, s22, 0x100080
	s_addc_u32 s23, s23, 0
	s_mov_b32 m0, s26
	s_nop 0
	global_load_lds_dwordx4 v132, s[22:23]
	s_add_i32 m0, s26, 0x2000
	s_nop 0
	global_load_lds_dwordx4 v136, s[22:23]
	s_mov_b32 m0, s46
	s_nop 0
	global_load_lds_dwordx4 v130, s[100:101]
	s_mov_b32 m0, s47
	s_nop 0
	global_load_lds_dwordx4 v134, s[100:101]
	s_waitcnt vmcnt(8)
	s_waitcnt lgkmcnt(0)
	s_barrier
	s_waitcnt lgkmcnt(0)
	v_mfma_f32_16x16x32_bf16 v[58:61], v[160:163], v[194:197], v[58:61]
	v_mfma_f32_16x16x32_bf16 v[50:53], v[170:173], v[194:197], v[50:53]
	v_mfma_f32_16x16x32_bf16 v[42:45], v[160:163], v[202:205], v[42:45]
	v_mfma_f32_16x16x32_bf16 v[34:37], v[170:173], v[202:205], v[34:37]
	v_mfma_f32_16x16x32_bf16 v[26:29], v[160:163], v[210:213], v[26:29]
	v_mfma_f32_16x16x32_bf16 v[18:21], v[170:173], v[210:213], v[18:21]
	v_mfma_f32_16x16x32_bf16 v[10:13], v[160:163], v[218:221], v[10:13]
	v_mfma_f32_16x16x32_bf16 v[2:5], v[170:173], v[218:221], v[2:5]
	v_mfma_f32_16x16x32_bf16 v[58:61], v[166:169], v[198:201], v[58:61]
	v_mfma_f32_16x16x32_bf16 v[50:53], v[174:177], v[198:201], v[50:53]
	v_mfma_f32_16x16x32_bf16 v[42:45], v[166:169], v[206:209], v[42:45]
	v_mfma_f32_16x16x32_bf16 v[34:37], v[174:177], v[206:209], v[34:37]
	v_mfma_f32_16x16x32_bf16 v[26:29], v[166:169], v[214:217], v[26:29]
	v_mfma_f32_16x16x32_bf16 v[18:21], v[174:177], v[214:217], v[18:21]
	v_mfma_f32_16x16x32_bf16 v[10:13], v[166:169], v[222:225], v[10:13]
	v_mfma_f32_16x16x32_bf16 v[2:5], v[174:177], v[222:225], v[2:5]
	v_mfma_f32_16x16x32_bf16 v[66:69], v[178:181], v[194:197], v[66:69]
	v_mfma_f32_16x16x32_bf16 v[54:57], v[186:189], v[194:197], v[54:57]
	v_mfma_f32_16x16x32_bf16 v[46:49], v[178:181], v[202:205], v[46:49]
	v_mfma_f32_16x16x32_bf16 v[38:41], v[186:189], v[202:205], v[38:41]
	v_mfma_f32_16x16x32_bf16 v[30:33], v[178:181], v[210:213], v[30:33]
	v_mfma_f32_16x16x32_bf16 v[22:25], v[186:189], v[210:213], v[22:25]
	v_mfma_f32_16x16x32_bf16 v[14:17], v[178:181], v[218:221], v[14:17]
	v_mfma_f32_16x16x32_bf16 v[6:9], v[186:189], v[218:221], v[6:9]
	v_mfma_f32_16x16x32_bf16 v[66:69], v[182:185], v[198:201], v[66:69]
	v_mfma_f32_16x16x32_bf16 v[54:57], v[190:193], v[198:201], v[54:57]
	v_mfma_f32_16x16x32_bf16 v[46:49], v[182:185], v[206:209], v[46:49]
	v_mfma_f32_16x16x32_bf16 v[38:41], v[190:193], v[206:209], v[38:41]
	v_mfma_f32_16x16x32_bf16 v[30:33], v[182:185], v[214:217], v[30:33]
	v_mfma_f32_16x16x32_bf16 v[22:25], v[190:193], v[214:217], v[22:25]
	v_mfma_f32_16x16x32_bf16 v[14:17], v[182:185], v[222:225], v[14:17]
	v_mfma_f32_16x16x32_bf16 v[6:9], v[190:193], v[222:225], v[6:9]
	s_barrier
	s_add_i32 s68, s68, 2
	s_add_u32 s24, s24, 0x100
	s_addc_u32 s25, s25, 0
	s_add_u32 s66, s66, 0x100
	s_addc_u32 s67, s67, 0
	s_cmp_gt_u32 s68, 61
	s_cbranch_scc0 .LBB0_1126


; #define PG8_BAR __builtin_amdgcn_s_barrier()
; template <class Epi, class Sched, bool ALIGN_EPI = false, bool SP2 = false>
; __device__ __forceinline__ void gemm_phase(PG8_LAS unsigned char* lds, const Gemm g, const Sched& S, const Epi& E) {
;     ...
;         if constexpr (ALIGN_EPI) { if (wr == 0) PG8_BAR; }
;         if constexpr (!Epi::AFTER_DRAIN) { E(acc, cur, wr, wc, fr, fq); S.done(cur); }
;         if (!has_next) break;
	s_and_b64 vcc, exec, s[8:9]
	s_cbranch_vccz .LBB0_1129
	s_barrier

; #define PG8_STAGE(bufoff, gbase, voff) do { _Pragma("unroll") for (int _i = 0; _i < 2; ++_i) \
;         __builtin_amdgcn_global_load_lds((const unsigned*)((const char*)(gbase) + (voff)[_i]), (PG8_LAS unsigned*)(lds + (bufoff) + ldsw + _i * 8192), 16, 0, 0); } while (0)
; #define PG8_LDA(dst, b, h) do { _Pragma("unroll") for (int m = 0; m < 4; ++m) _Pragma("unroll") for (int k = 0; k < 2; ++k) dst[m][k] = *(const PG8_LAS bf16x8*)(lds + PG8_SA(b, h) + aoff + m * 2048 + k * 1024); } while (0)
; #define PG8_LDB(dst, b, h) do { _Pragma("unroll") for (int n = 0; n < 2; ++n) _Pragma("unroll") for (int k = 0; k < 2; ++k) dst[n][k] = *(const PG8_LAS bf16x8*)(lds + PG8_SB(b, h) + boff + n * 2048 + k * 1024); } while (0)
; #define PG8_MMA(ai, bj, At, Bt) do { __builtin_amdgcn_s_setprio(1); _Pragma("unroll") for (int m = 0; m < 4; ++m) _Pragma("unroll") for (int n = 0; n < 2; ++n) _Pragma("unroll") for (int k = 0; k < 2; ++k) \
;         acc[ai][bj][m][n] = __builtin_amdgcn_mfma_f32_16x16x32_bf16(Bt[n][k], At[m][k], acc[ai][bj][m][n], 0, 0, 0); __builtin_amdgcn_s_setprio(0); } while (0)
; #define PG8_WAIT_V(n) asm volatile("s_waitcnt vmcnt(" #n ")" ::: "memory")
; #define PG8_WAIT_L(n) asm volatile("s_waitcnt lgkmcnt(" #n ")" ::: "memory")
; template <class Epi, class Sched, bool ALIGN_EPI = false, bool SP2 = false>
; __device__ __forceinline__ void gemm_phase(PG8_LAS unsigned char* lds, const Gemm g, const Sched& S, const Epi& E) {
;     ...
;             const bool last = (t == nt - 2);
;             const char* a1 = cA + (size_t)(t + 1) * kstep;
;             const char* a2 = last ? nA : cA + (size_t)(t + 2) * kstep; const char* b2 = last ? nB : cB + (size_t)(t + 2) * kstep;
;             const char* a3 = a2 + kstep; const char* b3 = b2 + kstep;
;             if (last && has_next) S.a_ready(nxt);
;             if constexpr (SP2) {
;             PG8_LDB(B0, 0, 0); PG8_LDB(B1, 0, 1); PG8_SCHED; PG8_LDA(At, 0, 0); PG8_STAGE(PG8_SA(1, 1), a1 + hstep, voffA);
;             PG8_WAIT_V(8); PG8_WAIT_L(0); PG8_BAR; PG8_MMA(0, 0, At, B0); PG8_MMA(0, 1, At, B1); PG8_BAR; PG8_SCHED;
;             PG8_LDA(At, 0, 1); PG8_STAGE(PG8_SB(0, 0), b2, voffB); PG8_STAGE(PG8_SB(0, 1), b2 + hstep, voffB); PG8_STAGE(PG8_SA(0, 0), a2, voffA);
;             PG8_WAIT_V(8); PG8_WAIT_L(0); PG8_BAR; PG8_MMA(1, 0, At, B0); PG8_MMA(1, 1, At, B1); PG8_BAR; PG8_SCHED;
.LBB0_1245:
	ds_read_b128 v[130:133], v241 offset:0
	ds_read_b128 v[134:137], v241 offset:1024
	ds_read_b128 v[138:141], v241 offset:2048
	ds_read_b128 v[142:145], v241 offset:3072
	ds_read_b128 v[146:149], v241 offset:16384
	ds_read_b128 v[150:153], v241 offset:17408
	ds_read_b128 v[172:175], v241 offset:18432
	ds_read_b128 v[176:179], v241 offset:19456
	s_add_u32 s16, s18, 0xffd50080
	s_addc_u32 s17, s19, -1
	s_cmpk_eq_i32 s64, 0xa8
	s_cselect_b32 s21, s5, s17
	s_cselect_b32 s20, s4, s16
	s_cselect_b32 s17, s15, s63
	s_cselect_b32 s16, s14, s62
	s_add_i32 m0, s25, 0xc000
	ds_read_b128 v[180:183], v185
	ds_read_b128 v[188:191], v185 offset:1024
	ds_read_b128 v[192:195], v185 offset:2048
	ds_read_b128 v[196:199], v185 offset:3072
	ds_read_b128 v[200:203], v185 offset:4096
	ds_read_b128 v[204:207], v185 offset:5120
	ds_read_b128 v[208:211], v185 offset:6144
	ds_read_b128 v[212:215], v185 offset:7168
	global_load_lds_dwordx4 v162, s[18:19]
	s_add_i32 m0, s25, 0xe000
	s_nop 0
	global_load_lds_dwordx4 v166, s[18:19]
	s_waitcnt vmcnt(8)
	s_waitcnt lgkmcnt(0)
	s_barrier
	s_waitcnt lgkmcnt(0)
	v_mfma_f32_16x16x32_bf16 v[114:117], v[130:133], v[180:183], v[114:117]
	v_mfma_f32_16x16x32_bf16 v[118:121], v[138:141], v[180:183], v[118:121]
	v_mfma_f32_16x16x32_bf16 v[106:109], v[130:133], v[192:195], v[106:109]
	v_mfma_f32_16x16x32_bf16 v[98:101], v[138:141], v[192:195], v[98:101]
	v_mfma_f32_16x16x32_bf16 v[90:93], v[130:133], v[200:203], v[90:93]
	v_mfma_f32_16x16x32_bf16 v[82:85], v[138:141], v[200:203], v[82:85]
	v_mfma_f32_16x16x32_bf16 v[74:77], v[130:133], v[208:211], v[74:77]
	v_mfma_f32_16x16x32_bf16 v[66:69], v[138:141], v[208:211], v[66:69]
	v_mfma_f32_16x16x32_bf16 v[114:117], v[134:137], v[188:191], v[114:117]
	v_mfma_f32_16x16x32_bf16 v[118:121], v[142:145], v[188:191], v[118:121]
	v_mfma_f32_16x16x32_bf16 v[106:109], v[134:137], v[196:199], v[106:109]
	v_mfma_f32_16x16x32_bf16 v[98:101], v[142:145], v[196:199], v[98:101]
	v_mfma_f32_16x16x32_bf16 v[90:93], v[134:137], v[204:207], v[90:93]
	v_mfma_f32_16x16x32_bf16 v[82:85], v[142:145], v[204:207], v[82:85]
	v_mfma_f32_16x16x32_bf16 v[74:77], v[134:137], v[212:215], v[74:77]
	v_mfma_f32_16x16x32_bf16 v[66:69], v[142:145], v[212:215], v[66:69]
	v_mfma_f32_16x16x32_bf16 v[122:125], v[146:149], v[180:183], v[122:125]
	v_mfma_f32_16x16x32_bf16 v[126:129], v[172:175], v[180:183], v[126:129]
	v_mfma_f32_16x16x32_bf16 v[110:113], v[146:149], v[192:195], v[110:113]
	v_mfma_f32_16x16x32_bf16 v[102:105], v[172:175], v[192:195], v[102:105]
	v_mfma_f32_16x16x32_bf16 v[94:97], v[146:149], v[200:203], v[94:97]
	v_mfma_f32_16x16x32_bf16 v[86:89], v[172:175], v[200:203], v[86:89]
	v_mfma_f32_16x16x32_bf16 v[78:81], v[146:149], v[208:211], v[78:81]
	v_mfma_f32_16x16x32_bf16 v[70:73], v[172:175], v[208:211], v[70:73]
	v_mfma_f32_16x16x32_bf16 v[122:125], v[150:153], v[188:191], v[122:125]
	v_mfma_f32_16x16x32_bf16 v[126:129], v[176:179], v[188:191], v[126:129]
	v_mfma_f32_16x16x32_bf16 v[110:113], v[150:153], v[196:199], v[110:113]
	v_mfma_f32_16x16x32_bf16 v[102:105], v[176:179], v[196:199], v[102:105]
	v_mfma_f32_16x16x32_bf16 v[94:97], v[150:153], v[204:207], v[94:97]
	v_mfma_f32_16x16x32_bf16 v[86:89], v[176:179], v[204:207], v[86:89]
	v_mfma_f32_16x16x32_bf16 v[78:81], v[150:153], v[212:215], v[78:81]
	v_mfma_f32_16x16x32_bf16 v[70:73], v[176:179], v[212:215], v[70:73]
	s_barrier
	s_add_i32 s33, s40, s24
	s_mov_b32 m0, s33
	ds_read_b128 v[180:183], v185 offset:16384
	ds_read_b128 v[188:191], v185 offset:17408
	ds_read_b128 v[192:195], v185 offset:18432
	ds_read_b128 v[196:199], v185 offset:19456
	ds_read_b128 v[200:203], v185 offset:20480
	ds_read_b128 v[204:207], v185 offset:21504
	ds_read_b128 v[208:211], v185 offset:22528
	ds_read_b128 v[212:215], v185 offset:23552
	global_load_lds_dwordx4 v156, s[16:17]
	s_add_i32 m0, s33, 0x2000
	s_add_u32 s66, s16, 0x2b0000
	s_addc_u32 s67, s17, 0
	s_add_i32 s33, s41, s24
	global_load_lds_dwordx4 v160, s[16:17]
	s_mov_b32 m0, s33
	s_add_u32 s100, s20, 0x80
	s_addc_u32 s101, s21, 0
	global_load_lds_dwordx4 v156, s[66:67]
	s_add_i32 m0, s33, 0x2000
	s_nop 0
	global_load_lds_dwordx4 v160, s[66:67]
	s_mov_b32 m0, s25
	s_nop 0
	global_load_lds_dwordx4 v154, s[20:21]
	s_mov_b32 m0, s26
	s_nop 0
	global_load_lds_dwordx4 v158, s[20:21]
	s_waitcnt vmcnt(8)
	s_waitcnt lgkmcnt(0)
	s_barrier
	s_waitcnt lgkmcnt(0)
	v_mfma_f32_16x16x32_bf16 v[58:61], v[130:133], v[180:183], v[58:61]
	v_mfma_f32_16x16x32_bf16 v[54:57], v[138:141], v[180:183], v[54:57]
	v_mfma_f32_16x16x32_bf16 v[42:45], v[130:133], v[192:195], v[42:45]
	v_mfma_f32_16x16x32_bf16 v[34:37], v[138:141], v[192:195], v[34:37]
	v_mfma_f32_16x16x32_bf16 v[26:29], v[130:133], v[200:203], v[26:29]
	v_mfma_f32_16x16x32_bf16 v[18:21], v[138:141], v[200:203], v[18:21]
	v_mfma_f32_16x16x32_bf16 v[6:9], v[130:133], v[208:211], v[6:9]
	v_mfma_f32_16x16x32_bf16 v[2:5], v[138:141], v[208:211], v[2:5]
	v_mfma_f32_16x16x32_bf16 v[58:61], v[134:137], v[188:191], v[58:61]
	v_mfma_f32_16x16x32_bf16 v[54:57], v[142:145], v[188:191], v[54:57]
	v_mfma_f32_16x16x32_bf16 v[42:45], v[134:137], v[196:199], v[42:45]
	v_mfma_f32_16x16x32_bf16 v[34:37], v[142:145], v[196:199], v[34:37]
	v_mfma_f32_16x16x32_bf16 v[26:29], v[134:137], v[204:207], v[26:29]
	v_mfma_f32_16x16x32_bf16 v[18:21], v[142:145], v[204:207], v[18:21]
	v_mfma_f32_16x16x32_bf16 v[6:9], v[134:137], v[212:215], v[6:9]
	v_mfma_f32_16x16x32_bf16 v[2:5], v[142:145], v[212:215], v[2:5]
	v_mfma_f32_16x16x32_bf16 v[62:65], v[146:149], v[180:183], v[62:65]
	v_mfma_f32_16x16x32_bf16 v[50:53], v[172:175], v[180:183], v[50:53]
	v_mfma_f32_16x16x32_bf16 v[46:49], v[146:149], v[192:195], v[46:49]
	v_mfma_f32_16x16x32_bf16 v[38:41], v[172:175], v[192:195], v[38:41]
	v_mfma_f32_16x16x32_bf16 v[30:33], v[146:149], v[200:203], v[30:33]
	v_mfma_f32_16x16x32_bf16 v[22:25], v[172:175], v[200:203], v[22:25]
	v_mfma_f32_16x16x32_bf16 v[10:13], v[146:149], v[208:211], v[10:13]
	v_mfma_f32_16x16x32_bf16 v[14:17], v[172:175], v[208:211], v[14:17]
	v_mfma_f32_16x16x32_bf16 v[62:65], v[150:153], v[188:191], v[62:65]
	v_mfma_f32_16x16x32_bf16 v[50:53], v[176:179], v[188:191], v[50:53]
	v_mfma_f32_16x16x32_bf16 v[46:49], v[150:153], v[196:199], v[46:49]
	v_mfma_f32_16x16x32_bf16 v[38:41], v[176:179], v[196:199], v[38:41]
	v_mfma_f32_16x16x32_bf16 v[30:33], v[150:153], v[204:207], v[30:33]
	v_mfma_f32_16x16x32_bf16 v[22:25], v[176:179], v[204:207], v[22:25]
	v_mfma_f32_16x16x32_bf16 v[10:13], v[150:153], v[212:215], v[10:13]
	v_mfma_f32_16x16x32_bf16 v[14:17], v[176:179], v[212:215], v[14:17]
	s_barrier
; #define PG8_STAGE(bufoff, gbase, voff) do { _Pragma("unroll") for (int _i = 0; _i < 2; ++_i) \
;         __builtin_amdgcn_global_load_lds((const unsigned*)((const char*)(gbase) + (voff)[_i]), (PG8_LAS unsigned*)(lds + (bufoff) + ldsw + _i * 8192), 16, 0, 0); } while (0)
; #define PG8_LDA(dst, b, h) do { _Pragma("unroll") for (int m = 0; m < 4; ++m) _Pragma("unroll") for (int k = 0; k < 2; ++k) dst[m][k] = *(const PG8_LAS bf16x8*)(lds + PG8_SA(b, h) + aoff + m * 2048 + k * 1024); } while (0)
; #define PG8_LDB(dst, b, h) do { _Pragma("unroll") for (int n = 0; n < 2; ++n) _Pragma("unroll") for (int k = 0; k < 2; ++k) dst[n][k] = *(const PG8_LAS bf16x8*)(lds + PG8_SB(b, h) + boff + n * 2048 + k * 1024); } while (0)
; #define PG8_MMA(ai, bj, At, Bt) do { __builtin_amdgcn_s_setprio(1); _Pragma("unroll") for (int m = 0; m < 4; ++m) _Pragma("unroll") for (int n = 0; n < 2; ++n) _Pragma("unroll") for (int k = 0; k < 2; ++k) \
;         acc[ai][bj][m][n] = __builtin_amdgcn_mfma_f32_16x16x32_bf16(Bt[n][k], At[m][k], acc[ai][bj][m][n], 0, 0, 0); __builtin_amdgcn_s_setprio(0); } while (0)
; #define PG8_WAIT_V(n) asm volatile("s_waitcnt vmcnt(" #n ")" ::: "memory")
; #define PG8_WAIT_L(n) asm volatile("s_waitcnt lgkmcnt(" #n ")" ::: "memory")
; #define PG8_BAR __builtin_amdgcn_s_barrier()
; #define PG8_SCHED __builtin_amdgcn_sched_barrier(0)
; template <class Epi, class Sched, bool ALIGN_EPI = false, bool SP2 = false>
; __device__ __forceinline__ void gemm_phase(PG8_LAS unsigned char* lds, const Gemm g, const Sched& S, const Epi& E) {
;     ...
;         for (int t = 0; t < nt; t += 2) {
;             const bool last = (t == nt - 2);
;     ...
;             PG8_LDB(B0, 1, 0); PG8_LDB(B1, 1, 1); PG8_SCHED; PG8_LDA(At, 1, 0); PG8_STAGE(PG8_SA(0, 1), a2 + hstep, voffA);
;             PG8_WAIT_V(8); PG8_WAIT_L(0); PG8_BAR; PG8_MMA(0, 0, At, B0); PG8_MMA(0, 1, At, B1); PG8_BAR; PG8_SCHED;
;             PG8_LDA(At, 1, 1); PG8_STAGE(PG8_SB(1, 0), b3, voffB); PG8_STAGE(PG8_SB(1, 1), b3 + hstep, voffB); PG8_STAGE(PG8_SA(1, 0), a3, voffA);
;             PG8_WAIT_V(8); PG8_WAIT_L(0); PG8_BAR; PG8_MMA(1, 0, At, B0); PG8_MMA(1, 1, At, B1); PG8_BAR; PG8_SCHED;
	s_add_i32 s33, 0, 0x18000
	s_add_i32 s42, 0, 0x1c000
	ds_read_b128 v[130:133], v241 offset:32768
	ds_read_b128 v[134:137], v241 offset:33792
	ds_read_b128 v[138:141], v241 offset:34816
	ds_read_b128 v[142:145], v241 offset:35840
	ds_read_b128 v[146:149], v241 offset:49152
	ds_read_b128 v[150:153], v241 offset:50176
	ds_read_b128 v[172:175], v241 offset:51200
	ds_read_b128 v[176:179], v241 offset:52224
	s_add_u32 s20, s20, 0x2b0000
	s_addc_u32 s21, s21, 0
	s_mov_b32 m0, s27
	ds_read_b128 v[180:183], v185 offset:32768
	ds_read_b128 v[188:191], v185 offset:33792
	ds_read_b128 v[192:195], v185 offset:34816
	ds_read_b128 v[196:199], v185 offset:35840
	ds_read_b128 v[200:203], v185 offset:36864
	ds_read_b128 v[204:207], v185 offset:37888
	ds_read_b128 v[208:211], v185 offset:38912
	ds_read_b128 v[212:215], v185 offset:39936
	global_load_lds_dwordx4 v154, s[20:21]
	s_mov_b32 m0, s28
	s_nop 0
	global_load_lds_dwordx4 v158, s[20:21]
	s_waitcnt vmcnt(8)
	s_waitcnt lgkmcnt(0)
	s_barrier
	s_waitcnt lgkmcnt(0)
	v_mfma_f32_16x16x32_bf16 v[114:117], v[130:133], v[180:183], v[114:117]
	v_mfma_f32_16x16x32_bf16 v[118:121], v[138:141], v[180:183], v[118:121]
	v_mfma_f32_16x16x32_bf16 v[106:109], v[130:133], v[192:195], v[106:109]
	v_mfma_f32_16x16x32_bf16 v[98:101], v[138:141], v[192:195], v[98:101]
	v_mfma_f32_16x16x32_bf16 v[90:93], v[130:133], v[200:203], v[90:93]
	v_mfma_f32_16x16x32_bf16 v[82:85], v[138:141], v[200:203], v[82:85]
	v_mfma_f32_16x16x32_bf16 v[74:77], v[130:133], v[208:211], v[74:77]
	v_mfma_f32_16x16x32_bf16 v[66:69], v[138:141], v[208:211], v[66:69]
	v_mfma_f32_16x16x32_bf16 v[114:117], v[134:137], v[188:191], v[114:117]
	v_mfma_f32_16x16x32_bf16 v[118:121], v[142:145], v[188:191], v[118:121]
	v_mfma_f32_16x16x32_bf16 v[106:109], v[134:137], v[196:199], v[106:109]
	v_mfma_f32_16x16x32_bf16 v[98:101], v[142:145], v[196:199], v[98:101]
	v_mfma_f32_16x16x32_bf16 v[90:93], v[134:137], v[204:207], v[90:93]
	v_mfma_f32_16x16x32_bf16 v[82:85], v[142:145], v[204:207], v[82:85]
	v_mfma_f32_16x16x32_bf16 v[74:77], v[134:137], v[212:215], v[74:77]
	v_mfma_f32_16x16x32_bf16 v[66:69], v[142:145], v[212:215], v[66:69]
	v_mfma_f32_16x16x32_bf16 v[122:125], v[146:149], v[180:183], v[122:125]
	v_mfma_f32_16x16x32_bf16 v[126:129], v[172:175], v[180:183], v[126:129]
	v_mfma_f32_16x16x32_bf16 v[110:113], v[146:149], v[192:195], v[110:113]
	v_mfma_f32_16x16x32_bf16 v[102:105], v[172:175], v[192:195], v[102:105]
	v_mfma_f32_16x16x32_bf16 v[94:97], v[146:149], v[200:203], v[94:97]
	v_mfma_f32_16x16x32_bf16 v[86:89], v[172:175], v[200:203], v[86:89]
	v_mfma_f32_16x16x32_bf16 v[78:81], v[146:149], v[208:211], v[78:81]
	v_mfma_f32_16x16x32_bf16 v[70:73], v[172:175], v[208:211], v[70:73]
	v_mfma_f32_16x16x32_bf16 v[122:125], v[150:153], v[188:191], v[122:125]
	v_mfma_f32_16x16x32_bf16 v[126:129], v[176:179], v[188:191], v[126:129]
	v_mfma_f32_16x16x32_bf16 v[110:113], v[150:153], v[196:199], v[110:113]
	v_mfma_f32_16x16x32_bf16 v[102:105], v[176:179], v[196:199], v[102:105]
	v_mfma_f32_16x16x32_bf16 v[94:97], v[150:153], v[204:207], v[94:97]
	v_mfma_f32_16x16x32_bf16 v[86:89], v[176:179], v[204:207], v[86:89]
	v_mfma_f32_16x16x32_bf16 v[78:81], v[150:153], v[212:215], v[78:81]
	v_mfma_f32_16x16x32_bf16 v[70:73], v[176:179], v[212:215], v[70:73]
	s_barrier
	s_add_i32 s20, s33, s24
	s_add_i32 m0, s20, 0xffffff80
	ds_read_b128 v[180:183], v185 offset:49152
	ds_read_b128 v[188:191], v185 offset:50176
	ds_read_b128 v[192:195], v185 offset:51200
	ds_read_b128 v[196:199], v185 offset:52224
	ds_read_b128 v[200:203], v185 offset:53248
	ds_read_b128 v[204:207], v185 offset:54272
	ds_read_b128 v[208:211], v185 offset:55296
	ds_read_b128 v[212:215], v185 offset:56320
	global_load_lds_dwordx4 v156, s[16:17] offset:128
	s_add_i32 m0, s20, 0x1f80
	s_add_i32 s20, s42, s24
	global_load_lds_dwordx4 v160, s[16:17] offset:128
	s_add_u32 s16, s16, 0x2b0080
	s_addc_u32 s17, s17, 0
	s_mov_b32 m0, s20
	s_nop 0
	global_load_lds_dwordx4 v156, s[16:17]
	s_add_i32 m0, s20, 0x2000
	s_nop 0
	global_load_lds_dwordx4 v160, s[16:17]
	s_mov_b32 m0, s34
	s_nop 0
	global_load_lds_dwordx4 v154, s[100:101]
	s_mov_b32 m0, s35
	s_nop 0
	global_load_lds_dwordx4 v158, s[100:101]
	s_waitcnt vmcnt(8)
	s_waitcnt lgkmcnt(0)
	s_barrier
	s_waitcnt lgkmcnt(0)
	v_mfma_f32_16x16x32_bf16 v[58:61], v[130:133], v[180:183], v[58:61]
	v_mfma_f32_16x16x32_bf16 v[54:57], v[138:141], v[180:183], v[54:57]
	v_mfma_f32_16x16x32_bf16 v[42:45], v[130:133], v[192:195], v[42:45]
	v_mfma_f32_16x16x32_bf16 v[34:37], v[138:141], v[192:195], v[34:37]
	v_mfma_f32_16x16x32_bf16 v[26:29], v[130:133], v[200:203], v[26:29]
	v_mfma_f32_16x16x32_bf16 v[18:21], v[138:141], v[200:203], v[18:21]
	v_mfma_f32_16x16x32_bf16 v[6:9], v[130:133], v[208:211], v[6:9]
	v_mfma_f32_16x16x32_bf16 v[2:5], v[138:141], v[208:211], v[2:5]
	v_mfma_f32_16x16x32_bf16 v[58:61], v[134:137], v[188:191], v[58:61]
	v_mfma_f32_16x16x32_bf16 v[54:57], v[142:145], v[188:191], v[54:57]
	v_mfma_f32_16x16x32_bf16 v[42:45], v[134:137], v[196:199], v[42:45]
	v_mfma_f32_16x16x32_bf16 v[34:37], v[142:145], v[196:199], v[34:37]
	v_mfma_f32_16x16x32_bf16 v[26:29], v[134:137], v[204:207], v[26:29]
	v_mfma_f32_16x16x32_bf16 v[18:21], v[142:145], v[204:207], v[18:21]
	v_mfma_f32_16x16x32_bf16 v[6:9], v[134:137], v[212:215], v[6:9]
	v_mfma_f32_16x16x32_bf16 v[2:5], v[142:145], v[212:215], v[2:5]
	v_mfma_f32_16x16x32_bf16 v[62:65], v[146:149], v[180:183], v[62:65]
	v_mfma_f32_16x16x32_bf16 v[50:53], v[172:175], v[180:183], v[50:53]
	v_mfma_f32_16x16x32_bf16 v[46:49], v[146:149], v[192:195], v[46:49]
	v_mfma_f32_16x16x32_bf16 v[38:41], v[172:175], v[192:195], v[38:41]
	v_mfma_f32_16x16x32_bf16 v[30:33], v[146:149], v[200:203], v[30:33]
	v_mfma_f32_16x16x32_bf16 v[22:25], v[172:175], v[200:203], v[22:25]
	v_mfma_f32_16x16x32_bf16 v[10:13], v[146:149], v[208:211], v[10:13]
	v_mfma_f32_16x16x32_bf16 v[14:17], v[172:175], v[208:211], v[14:17]
	v_mfma_f32_16x16x32_bf16 v[62:65], v[150:153], v[188:191], v[62:65]
	v_mfma_f32_16x16x32_bf16 v[50:53], v[176:179], v[188:191], v[50:53]
	v_mfma_f32_16x16x32_bf16 v[46:49], v[150:153], v[196:199], v[46:49]
	v_mfma_f32_16x16x32_bf16 v[38:41], v[176:179], v[196:199], v[38:41]
	v_mfma_f32_16x16x32_bf16 v[30:33], v[150:153], v[204:207], v[30:33]
	v_mfma_f32_16x16x32_bf16 v[22:25], v[176:179], v[204:207], v[22:25]
	v_mfma_f32_16x16x32_bf16 v[10:13], v[150:153], v[212:215], v[10:13]
	v_mfma_f32_16x16x32_bf16 v[14:17], v[176:179], v[212:215], v[14:17]
	s_barrier
	s_add_i32 s64, s64, 2
	s_add_u32 s18, s18, 0x100
	s_addc_u32 s19, s19, 0
	s_add_u32 s62, s62, 0x100
	s_addc_u32 s63, s63, 0
	s_cmpk_gt_u32 s64, 0xa9
	s_cbranch_scc0 .LBB0_1245


; #define PG8_BAR __builtin_amdgcn_s_barrier()
; template <class Epi, class Sched, bool ALIGN_EPI = false, bool SP2 = false>
; __device__ __forceinline__ void gemm_phase(PG8_LAS unsigned char* lds, const Gemm g, const Sched& S, const Epi& E) {
;     ...
;         if constexpr (ALIGN_EPI) { if (wr == 0) PG8_BAR; }
;         if constexpr (!Epi::AFTER_DRAIN) { E(acc, cur, wr, wc, fr, fq); S.done(cur); }
;         if (!has_next) break;
	s_and_b64 vcc, exec, s[12:13]
	s_cbranch_vccz .LBB0_1248
	s_barrier

; #define PG8_STAGE(bufoff, gbase, voff) do { _Pragma("unroll") for (int _i = 0; _i < 2; ++_i) \
;         __builtin_amdgcn_global_load_lds((const unsigned*)((const char*)(gbase) + (voff)[_i]), (PG8_LAS unsigned*)(lds + (bufoff) + ldsw + _i * 8192), 16, 0, 0); } while (0)
; #define PG8_LDA(dst, b, h) do { _Pragma("unroll") for (int m = 0; m < 4; ++m) _Pragma("unroll") for (int k = 0; k < 2; ++k) dst[m][k] = *(const PG8_LAS bf16x8*)(lds + PG8_SA(b, h) + aoff + m * 2048 + k * 1024); } while (0)
; #define PG8_LDB(dst, b, h) do { _Pragma("unroll") for (int n = 0; n < 2; ++n) _Pragma("unroll") for (int k = 0; k < 2; ++k) dst[n][k] = *(const PG8_LAS bf16x8*)(lds + PG8_SB(b, h) + boff + n * 2048 + k * 1024); } while (0)
; #define PG8_MMA(ai, bj, At, Bt) do { __builtin_amdgcn_s_setprio(1); _Pragma("unroll") for (int m = 0; m < 4; ++m) _Pragma("unroll") for (int n = 0; n < 2; ++n) _Pragma("unroll") for (int k = 0; k < 2; ++k) \
;         acc[ai][bj][m][n] = __builtin_amdgcn_mfma_f32_16x16x32_bf16(Bt[n][k], At[m][k], acc[ai][bj][m][n], 0, 0, 0); __builtin_amdgcn_s_setprio(0); } while (0)
; #define PG8_WAIT_V(n) asm volatile("s_waitcnt vmcnt(" #n ")" ::: "memory")
; #define PG8_WAIT_L(n) asm volatile("s_waitcnt lgkmcnt(" #n ")" ::: "memory")
; template <class Epi, class Sched, bool ALIGN_EPI = false, bool SP2 = false>
; __device__ __forceinline__ void gemm_phase(PG8_LAS unsigned char* lds, const Gemm g, const Sched& S, const Epi& E) {
;     ...
;             const bool last = (t == nt - 2);
;             const char* a1 = cA + (size_t)(t + 1) * kstep;
;             const char* a2 = last ? nA : cA + (size_t)(t + 2) * kstep; const char* b2 = last ? nB : cB + (size_t)(t + 2) * kstep;
;             const char* a3 = a2 + kstep; const char* b3 = b2 + kstep;
;             if (last && has_next) S.a_ready(nxt);
;             if constexpr (SP2) {
;             PG8_LDB(B0, 0, 0); PG8_LDB(B1, 0, 1); PG8_SCHED; PG8_LDA(At, 0, 0); PG8_STAGE(PG8_SA(1, 1), a1 + hstep, voffA);
;             PG8_WAIT_V(8); PG8_WAIT_L(0); PG8_BAR; PG8_MMA(0, 0, At, B0); PG8_MMA(0, 1, At, B1); PG8_BAR; PG8_SCHED;
;             PG8_LDA(At, 0, 1); PG8_STAGE(PG8_SB(0, 0), b2, voffB); PG8_STAGE(PG8_SB(0, 1), b2 + hstep, voffB); PG8_STAGE(PG8_SA(0, 0), a2, voffA);
;             PG8_WAIT_V(8); PG8_WAIT_L(0); PG8_BAR; PG8_MMA(1, 0, At, B0); PG8_MMA(1, 1, At, B1); PG8_BAR; PG8_SCHED;
.LBB0_1332:
	ds_read_b128 v[148:151], v241 offset:0
	ds_read_b128 v[156:159], v241 offset:1024
	ds_read_b128 v[166:169], v241 offset:2048
	ds_read_b128 v[170:173], v241 offset:3072
	ds_read_b128 v[174:177], v241 offset:16384
	ds_read_b128 v[178:181], v241 offset:17408
	ds_read_b128 v[182:185], v241 offset:18432
	ds_read_b128 v[186:189], v241 offset:19456
	s_add_u32 s20, s22, 0xfff00080
	s_addc_u32 s21, s23, -1
	s_cmp_eq_u32 s67, 60
	s_cselect_b32 s25, s13, s21
	s_cselect_b32 s24, s63, s20
	s_cselect_b32 s21, s11, s66
	s_cselect_b32 s20, s64, s65
	s_add_i32 m0, s19, 0xc000
	ds_read_b128 v[190:193], v155
	ds_read_b128 v[194:197], v155 offset:1024
	ds_read_b128 v[198:201], v155 offset:2048
	ds_read_b128 v[202:205], v155 offset:3072
	ds_read_b128 v[206:209], v155 offset:4096
	ds_read_b128 v[210:213], v155 offset:5120
	ds_read_b128 v[214:217], v155 offset:6144
	ds_read_b128 v[218:221], v155 offset:7168
	global_load_lds_dwordx4 v138, s[22:23]
	s_add_i32 m0, s19, 0xe000
	s_nop 0
	global_load_lds_dwordx4 v140, s[22:23]
	s_waitcnt vmcnt(8)
	s_waitcnt lgkmcnt(0)
	s_barrier
	s_waitcnt lgkmcnt(0)
	v_mfma_f32_16x16x32_bf16 v[118:121], v[148:151], v[190:193], v[118:121]
	v_mfma_f32_16x16x32_bf16 v[114:117], v[166:169], v[190:193], v[114:117]
	v_mfma_f32_16x16x32_bf16 v[102:105], v[148:151], v[198:201], v[102:105]
	v_mfma_f32_16x16x32_bf16 v[98:101], v[166:169], v[198:201], v[98:101]
	v_mfma_f32_16x16x32_bf16 v[86:89], v[148:151], v[206:209], v[86:89]
	v_mfma_f32_16x16x32_bf16 v[82:85], v[166:169], v[206:209], v[82:85]
	v_mfma_f32_16x16x32_bf16 v[70:73], v[148:151], v[214:217], v[70:73]
	v_mfma_f32_16x16x32_bf16 v[66:69], v[166:169], v[214:217], v[66:69]
	v_mfma_f32_16x16x32_bf16 v[118:121], v[156:159], v[194:197], v[118:121]
	v_mfma_f32_16x16x32_bf16 v[114:117], v[170:173], v[194:197], v[114:117]
	v_mfma_f32_16x16x32_bf16 v[102:105], v[156:159], v[202:205], v[102:105]
	v_mfma_f32_16x16x32_bf16 v[98:101], v[170:173], v[202:205], v[98:101]
	v_mfma_f32_16x16x32_bf16 v[86:89], v[156:159], v[210:213], v[86:89]
	v_mfma_f32_16x16x32_bf16 v[82:85], v[170:173], v[210:213], v[82:85]
	v_mfma_f32_16x16x32_bf16 v[70:73], v[156:159], v[218:221], v[70:73]
	v_mfma_f32_16x16x32_bf16 v[66:69], v[170:173], v[218:221], v[66:69]
	v_mfma_f32_16x16x32_bf16 v[126:129], v[174:177], v[190:193], v[126:129]
	v_mfma_f32_16x16x32_bf16 v[122:125], v[182:185], v[190:193], v[122:125]
	v_mfma_f32_16x16x32_bf16 v[110:113], v[174:177], v[198:201], v[110:113]
	v_mfma_f32_16x16x32_bf16 v[106:109], v[182:185], v[198:201], v[106:109]
	v_mfma_f32_16x16x32_bf16 v[94:97], v[174:177], v[206:209], v[94:97]
	v_mfma_f32_16x16x32_bf16 v[90:93], v[182:185], v[206:209], v[90:93]
	v_mfma_f32_16x16x32_bf16 v[78:81], v[174:177], v[214:217], v[78:81]
	v_mfma_f32_16x16x32_bf16 v[74:77], v[182:185], v[214:217], v[74:77]
	v_mfma_f32_16x16x32_bf16 v[126:129], v[178:181], v[194:197], v[126:129]
	v_mfma_f32_16x16x32_bf16 v[122:125], v[186:189], v[194:197], v[122:125]
	v_mfma_f32_16x16x32_bf16 v[110:113], v[178:181], v[202:205], v[110:113]
	v_mfma_f32_16x16x32_bf16 v[106:109], v[186:189], v[202:205], v[106:109]
	v_mfma_f32_16x16x32_bf16 v[94:97], v[178:181], v[210:213], v[94:97]
	v_mfma_f32_16x16x32_bf16 v[90:93], v[186:189], v[210:213], v[90:93]
	v_mfma_f32_16x16x32_bf16 v[78:81], v[178:181], v[218:221], v[78:81]
	v_mfma_f32_16x16x32_bf16 v[74:77], v[186:189], v[218:221], v[74:77]
	s_barrier
	s_add_i32 s33, s47, s28
	s_mov_b32 m0, s33
	ds_read_b128 v[190:193], v155 offset:16384
	ds_read_b128 v[194:197], v155 offset:17408
	ds_read_b128 v[198:201], v155 offset:18432
	ds_read_b128 v[202:205], v155 offset:19456
	ds_read_b128 v[206:209], v155 offset:20480
	ds_read_b128 v[210:213], v155 offset:21504
	ds_read_b128 v[214:217], v155 offset:22528
	ds_read_b128 v[218:221], v155 offset:23552
	global_load_lds_dwordx4 v132, s[20:21]
	s_add_i32 m0, s33, 0x2000
	s_add_u32 s68, s20, 0x100000
	s_addc_u32 s69, s21, 0
	s_add_i32 s33, s52, s28
	global_load_lds_dwordx4 v136, s[20:21]
	s_mov_b32 m0, s33
	s_add_u32 s100, s24, 0x80
	s_addc_u32 s101, s25, 0
	global_load_lds_dwordx4 v132, s[68:69]
	s_add_i32 m0, s33, 0x2000
	s_nop 0
	global_load_lds_dwordx4 v136, s[68:69]
	s_mov_b32 m0, s19
	s_nop 0
	global_load_lds_dwordx4 v130, s[24:25]
	s_mov_b32 m0, s35
	s_nop 0
	global_load_lds_dwordx4 v134, s[24:25]
	s_waitcnt vmcnt(8)
	s_waitcnt lgkmcnt(0)
	s_barrier
	s_waitcnt lgkmcnt(0)
	v_mfma_f32_16x16x32_bf16 v[54:57], v[148:151], v[190:193], v[54:57]
	v_mfma_f32_16x16x32_bf16 v[50:53], v[166:169], v[190:193], v[50:53]
	v_mfma_f32_16x16x32_bf16 v[38:41], v[148:151], v[198:201], v[38:41]
	v_mfma_f32_16x16x32_bf16 v[34:37], v[166:169], v[198:201], v[34:37]
	v_mfma_f32_16x16x32_bf16 v[22:25], v[148:151], v[206:209], v[22:25]
	v_mfma_f32_16x16x32_bf16 v[18:21], v[166:169], v[206:209], v[18:21]
	v_mfma_f32_16x16x32_bf16 v[6:9], v[148:151], v[214:217], v[6:9]
	v_mfma_f32_16x16x32_bf16 v[2:5], v[166:169], v[214:217], v[2:5]
	v_mfma_f32_16x16x32_bf16 v[54:57], v[156:159], v[194:197], v[54:57]
	v_mfma_f32_16x16x32_bf16 v[50:53], v[170:173], v[194:197], v[50:53]
	v_mfma_f32_16x16x32_bf16 v[38:41], v[156:159], v[202:205], v[38:41]
	v_mfma_f32_16x16x32_bf16 v[34:37], v[170:173], v[202:205], v[34:37]
	v_mfma_f32_16x16x32_bf16 v[22:25], v[156:159], v[210:213], v[22:25]
	v_mfma_f32_16x16x32_bf16 v[18:21], v[170:173], v[210:213], v[18:21]
	v_mfma_f32_16x16x32_bf16 v[6:9], v[156:159], v[218:221], v[6:9]
	v_mfma_f32_16x16x32_bf16 v[2:5], v[170:173], v[218:221], v[2:5]
	v_mfma_f32_16x16x32_bf16 v[62:65], v[174:177], v[190:193], v[62:65]
	v_mfma_f32_16x16x32_bf16 v[58:61], v[182:185], v[190:193], v[58:61]
	v_mfma_f32_16x16x32_bf16 v[46:49], v[174:177], v[198:201], v[46:49]
	v_mfma_f32_16x16x32_bf16 v[42:45], v[182:185], v[198:201], v[42:45]
	v_mfma_f32_16x16x32_bf16 v[30:33], v[174:177], v[206:209], v[30:33]
	v_mfma_f32_16x16x32_bf16 v[26:29], v[182:185], v[206:209], v[26:29]
	v_mfma_f32_16x16x32_bf16 v[10:13], v[174:177], v[214:217], v[10:13]
	v_mfma_f32_16x16x32_bf16 v[14:17], v[182:185], v[214:217], v[14:17]
	v_mfma_f32_16x16x32_bf16 v[62:65], v[178:181], v[194:197], v[62:65]
	v_mfma_f32_16x16x32_bf16 v[58:61], v[186:189], v[194:197], v[58:61]
	v_mfma_f32_16x16x32_bf16 v[46:49], v[178:181], v[202:205], v[46:49]
	v_mfma_f32_16x16x32_bf16 v[42:45], v[186:189], v[202:205], v[42:45]
	v_mfma_f32_16x16x32_bf16 v[30:33], v[178:181], v[210:213], v[30:33]
	v_mfma_f32_16x16x32_bf16 v[26:29], v[186:189], v[210:213], v[26:29]
	v_mfma_f32_16x16x32_bf16 v[10:13], v[178:181], v[218:221], v[10:13]
	v_mfma_f32_16x16x32_bf16 v[14:17], v[186:189], v[218:221], v[14:17]
	s_barrier
; #define PG8_STAGE(bufoff, gbase, voff) do { _Pragma("unroll") for (int _i = 0; _i < 2; ++_i) \
;         __builtin_amdgcn_global_load_lds((const unsigned*)((const char*)(gbase) + (voff)[_i]), (PG8_LAS unsigned*)(lds + (bufoff) + ldsw + _i * 8192), 16, 0, 0); } while (0)
; #define PG8_LDA(dst, b, h) do { _Pragma("unroll") for (int m = 0; m < 4; ++m) _Pragma("unroll") for (int k = 0; k < 2; ++k) dst[m][k] = *(const PG8_LAS bf16x8*)(lds + PG8_SA(b, h) + aoff + m * 2048 + k * 1024); } while (0)
; #define PG8_LDB(dst, b, h) do { _Pragma("unroll") for (int n = 0; n < 2; ++n) _Pragma("unroll") for (int k = 0; k < 2; ++k) dst[n][k] = *(const PG8_LAS bf16x8*)(lds + PG8_SB(b, h) + boff + n * 2048 + k * 1024); } while (0)
; #define PG8_MMA(ai, bj, At, Bt) do { __builtin_amdgcn_s_setprio(1); _Pragma("unroll") for (int m = 0; m < 4; ++m) _Pragma("unroll") for (int n = 0; n < 2; ++n) _Pragma("unroll") for (int k = 0; k < 2; ++k) \
;         acc[ai][bj][m][n] = __builtin_amdgcn_mfma_f32_16x16x32_bf16(Bt[n][k], At[m][k], acc[ai][bj][m][n], 0, 0, 0); __builtin_amdgcn_s_setprio(0); } while (0)
; #define PG8_WAIT_V(n) asm volatile("s_waitcnt vmcnt(" #n ")" ::: "memory")
; #define PG8_WAIT_L(n) asm volatile("s_waitcnt lgkmcnt(" #n ")" ::: "memory")
; #define PG8_BAR __builtin_amdgcn_s_barrier()
; #define PG8_SCHED __builtin_amdgcn_sched_barrier(0)
; template <class Epi, class Sched, bool ALIGN_EPI = false, bool SP2 = false>
; __device__ __forceinline__ void gemm_phase(PG8_LAS unsigned char* lds, const Gemm g, const Sched& S, const Epi& E) {
;     ...
;         for (int t = 0; t < nt; t += 2) {
;             const bool last = (t == nt - 2);
;     ...
;             PG8_LDB(B0, 1, 0); PG8_LDB(B1, 1, 1); PG8_SCHED; PG8_LDA(At, 1, 0); PG8_STAGE(PG8_SA(0, 1), a2 + hstep, voffA);
;             PG8_WAIT_V(8); PG8_WAIT_L(0); PG8_BAR; PG8_MMA(0, 0, At, B0); PG8_MMA(0, 1, At, B1); PG8_BAR; PG8_SCHED;
;             PG8_LDA(At, 1, 1); PG8_STAGE(PG8_SB(1, 0), b3, voffB); PG8_STAGE(PG8_SB(1, 1), b3 + hstep, voffB); PG8_STAGE(PG8_SA(1, 0), a3, voffA);
;             PG8_WAIT_V(8); PG8_WAIT_L(0); PG8_BAR; PG8_MMA(1, 0, At, B0); PG8_MMA(1, 1, At, B1); PG8_BAR; PG8_SCHED;
	s_add_i32 s33, 0, 0x18000
	s_add_i32 s42, 0, 0x1c000
	ds_read_b128 v[148:151], v241 offset:32768
	ds_read_b128 v[156:159], v241 offset:33792
	ds_read_b128 v[166:169], v241 offset:34816
	ds_read_b128 v[170:173], v241 offset:35840
	ds_read_b128 v[174:177], v241 offset:49152
	ds_read_b128 v[178:181], v241 offset:50176
	ds_read_b128 v[182:185], v241 offset:51200
	ds_read_b128 v[186:189], v241 offset:52224
	s_add_u32 s24, s24, 0x100000
	s_addc_u32 s25, s25, 0
	s_mov_b32 m0, s36
	ds_read_b128 v[190:193], v155 offset:32768
	ds_read_b128 v[194:197], v155 offset:33792
	ds_read_b128 v[198:201], v155 offset:34816
	ds_read_b128 v[202:205], v155 offset:35840
	ds_read_b128 v[206:209], v155 offset:36864
	ds_read_b128 v[210:213], v155 offset:37888
	ds_read_b128 v[214:217], v155 offset:38912
	ds_read_b128 v[218:221], v155 offset:39936
	global_load_lds_dwordx4 v130, s[24:25]
	s_mov_b32 m0, s37
	s_nop 0
	global_load_lds_dwordx4 v134, s[24:25]
	s_waitcnt vmcnt(8)
	s_waitcnt lgkmcnt(0)
	s_barrier
	s_waitcnt lgkmcnt(0)
	v_mfma_f32_16x16x32_bf16 v[118:121], v[148:151], v[190:193], v[118:121]
	v_mfma_f32_16x16x32_bf16 v[114:117], v[166:169], v[190:193], v[114:117]
	v_mfma_f32_16x16x32_bf16 v[102:105], v[148:151], v[198:201], v[102:105]
	v_mfma_f32_16x16x32_bf16 v[98:101], v[166:169], v[198:201], v[98:101]
	v_mfma_f32_16x16x32_bf16 v[86:89], v[148:151], v[206:209], v[86:89]
	v_mfma_f32_16x16x32_bf16 v[82:85], v[166:169], v[206:209], v[82:85]
	v_mfma_f32_16x16x32_bf16 v[70:73], v[148:151], v[214:217], v[70:73]
	v_mfma_f32_16x16x32_bf16 v[66:69], v[166:169], v[214:217], v[66:69]
	v_mfma_f32_16x16x32_bf16 v[118:121], v[156:159], v[194:197], v[118:121]
	v_mfma_f32_16x16x32_bf16 v[114:117], v[170:173], v[194:197], v[114:117]
	v_mfma_f32_16x16x32_bf16 v[102:105], v[156:159], v[202:205], v[102:105]
	v_mfma_f32_16x16x32_bf16 v[98:101], v[170:173], v[202:205], v[98:101]
	v_mfma_f32_16x16x32_bf16 v[86:89], v[156:159], v[210:213], v[86:89]
	v_mfma_f32_16x16x32_bf16 v[82:85], v[170:173], v[210:213], v[82:85]
	v_mfma_f32_16x16x32_bf16 v[70:73], v[156:159], v[218:221], v[70:73]
	v_mfma_f32_16x16x32_bf16 v[66:69], v[170:173], v[218:221], v[66:69]
	v_mfma_f32_16x16x32_bf16 v[126:129], v[174:177], v[190:193], v[126:129]
	v_mfma_f32_16x16x32_bf16 v[122:125], v[182:185], v[190:193], v[122:125]
	v_mfma_f32_16x16x32_bf16 v[110:113], v[174:177], v[198:201], v[110:113]
	v_mfma_f32_16x16x32_bf16 v[106:109], v[182:185], v[198:201], v[106:109]
	v_mfma_f32_16x16x32_bf16 v[94:97], v[174:177], v[206:209], v[94:97]
	v_mfma_f32_16x16x32_bf16 v[90:93], v[182:185], v[206:209], v[90:93]
	v_mfma_f32_16x16x32_bf16 v[78:81], v[174:177], v[214:217], v[78:81]
	v_mfma_f32_16x16x32_bf16 v[74:77], v[182:185], v[214:217], v[74:77]
	v_mfma_f32_16x16x32_bf16 v[126:129], v[178:181], v[194:197], v[126:129]
	v_mfma_f32_16x16x32_bf16 v[122:125], v[186:189], v[194:197], v[122:125]
	v_mfma_f32_16x16x32_bf16 v[110:113], v[178:181], v[202:205], v[110:113]
	v_mfma_f32_16x16x32_bf16 v[106:109], v[186:189], v[202:205], v[106:109]
	v_mfma_f32_16x16x32_bf16 v[94:97], v[178:181], v[210:213], v[94:97]
	v_mfma_f32_16x16x32_bf16 v[90:93], v[186:189], v[210:213], v[90:93]
	v_mfma_f32_16x16x32_bf16 v[78:81], v[178:181], v[218:221], v[78:81]
	v_mfma_f32_16x16x32_bf16 v[74:77], v[186:189], v[218:221], v[74:77]
	s_barrier
	s_add_i32 s24, s33, s28
	s_add_i32 m0, s24, 0xffffff80
	ds_read_b128 v[190:193], v155 offset:49152
	ds_read_b128 v[194:197], v155 offset:50176
	ds_read_b128 v[198:201], v155 offset:51200
	ds_read_b128 v[202:205], v155 offset:52224
	ds_read_b128 v[206:209], v155 offset:53248
	ds_read_b128 v[210:213], v155 offset:54272
	ds_read_b128 v[214:217], v155 offset:55296
	ds_read_b128 v[218:221], v155 offset:56320
	global_load_lds_dwordx4 v132, s[20:21] offset:128
	s_add_i32 m0, s24, 0x1f80
	s_add_i32 s24, s42, s28
	global_load_lds_dwordx4 v136, s[20:21] offset:128
	s_add_u32 s20, s20, 0x100080
	s_addc_u32 s21, s21, 0
	s_mov_b32 m0, s24
	s_nop 0
	global_load_lds_dwordx4 v132, s[20:21]
	s_add_i32 m0, s24, 0x2000
	s_nop 0
	global_load_lds_dwordx4 v136, s[20:21]
	s_mov_b32 m0, s43
	s_nop 0
	global_load_lds_dwordx4 v130, s[100:101]
	s_mov_b32 m0, s46
	s_nop 0
	global_load_lds_dwordx4 v134, s[100:101]
	s_waitcnt vmcnt(8)
	s_waitcnt lgkmcnt(0)
	s_barrier
	s_waitcnt lgkmcnt(0)
	v_mfma_f32_16x16x32_bf16 v[54:57], v[148:151], v[190:193], v[54:57]
	v_mfma_f32_16x16x32_bf16 v[50:53], v[166:169], v[190:193], v[50:53]
	v_mfma_f32_16x16x32_bf16 v[38:41], v[148:151], v[198:201], v[38:41]
	v_mfma_f32_16x16x32_bf16 v[34:37], v[166:169], v[198:201], v[34:37]
	v_mfma_f32_16x16x32_bf16 v[22:25], v[148:151], v[206:209], v[22:25]
	v_mfma_f32_16x16x32_bf16 v[18:21], v[166:169], v[206:209], v[18:21]
	v_mfma_f32_16x16x32_bf16 v[6:9], v[148:151], v[214:217], v[6:9]
	v_mfma_f32_16x16x32_bf16 v[2:5], v[166:169], v[214:217], v[2:5]
	v_mfma_f32_16x16x32_bf16 v[54:57], v[156:159], v[194:197], v[54:57]
	v_mfma_f32_16x16x32_bf16 v[50:53], v[170:173], v[194:197], v[50:53]
	v_mfma_f32_16x16x32_bf16 v[38:41], v[156:159], v[202:205], v[38:41]
	v_mfma_f32_16x16x32_bf16 v[34:37], v[170:173], v[202:205], v[34:37]
	v_mfma_f32_16x16x32_bf16 v[22:25], v[156:159], v[210:213], v[22:25]
	v_mfma_f32_16x16x32_bf16 v[18:21], v[170:173], v[210:213], v[18:21]
	v_mfma_f32_16x16x32_bf16 v[6:9], v[156:159], v[218:221], v[6:9]
	v_mfma_f32_16x16x32_bf16 v[2:5], v[170:173], v[218:221], v[2:5]
	v_mfma_f32_16x16x32_bf16 v[62:65], v[174:177], v[190:193], v[62:65]
	v_mfma_f32_16x16x32_bf16 v[58:61], v[182:185], v[190:193], v[58:61]
	v_mfma_f32_16x16x32_bf16 v[46:49], v[174:177], v[198:201], v[46:49]
	v_mfma_f32_16x16x32_bf16 v[42:45], v[182:185], v[198:201], v[42:45]
	v_mfma_f32_16x16x32_bf16 v[30:33], v[174:177], v[206:209], v[30:33]
	v_mfma_f32_16x16x32_bf16 v[26:29], v[182:185], v[206:209], v[26:29]
	v_mfma_f32_16x16x32_bf16 v[10:13], v[174:177], v[214:217], v[10:13]
	v_mfma_f32_16x16x32_bf16 v[14:17], v[182:185], v[214:217], v[14:17]
	v_mfma_f32_16x16x32_bf16 v[62:65], v[178:181], v[194:197], v[62:65]
	v_mfma_f32_16x16x32_bf16 v[58:61], v[186:189], v[194:197], v[58:61]
	v_mfma_f32_16x16x32_bf16 v[46:49], v[178:181], v[202:205], v[46:49]
	v_mfma_f32_16x16x32_bf16 v[42:45], v[186:189], v[202:205], v[42:45]
	v_mfma_f32_16x16x32_bf16 v[30:33], v[178:181], v[210:213], v[30:33]
	v_mfma_f32_16x16x32_bf16 v[26:29], v[186:189], v[210:213], v[26:29]
	v_mfma_f32_16x16x32_bf16 v[10:13], v[178:181], v[218:221], v[10:13]
	v_mfma_f32_16x16x32_bf16 v[14:17], v[186:189], v[218:221], v[14:17]
	s_barrier
	s_add_i32 s67, s67, 2
	s_add_u32 s22, s22, 0x100
	s_addc_u32 s23, s23, 0
	s_add_u32 s65, s65, 0x100
	s_addc_u32 s66, s66, 0
	s_cmp_gt_u32 s67, 61
	s_cbranch_scc0 .LBB0_1332


; #define PG8_BAR __builtin_amdgcn_s_barrier()
; template <class Epi, class Sched, bool ALIGN_EPI = false, bool SP2 = false>
; __device__ __forceinline__ void gemm_phase(PG8_LAS unsigned char* lds, const Gemm g, const Sched& S, const Epi& E) {
;     ...
;         if constexpr (ALIGN_EPI) { if (wr == 0) PG8_BAR; }
;         if constexpr (!Epi::AFTER_DRAIN) { E(acc, cur, wr, wc, fr, fq); S.done(cur); }
;         if (!has_next) break;
	s_and_b64 vcc, exec, s[8:9]
	s_cbranch_vccz .LBB0_1335
	s_barrier

; #define PG8_STAGE(bufoff, gbase, voff) do { _Pragma("unroll") for (int _i = 0; _i < 2; ++_i) \
;         __builtin_amdgcn_global_load_lds((const unsigned*)((const char*)(gbase) + (voff)[_i]), (PG8_LAS unsigned*)(lds + (bufoff) + ldsw + _i * 8192), 16, 0, 0); } while (0)
; #define PG8_LDA(dst, b, h) do { _Pragma("unroll") for (int m = 0; m < 4; ++m) _Pragma("unroll") for (int k = 0; k < 2; ++k) dst[m][k] = *(const PG8_LAS bf16x8*)(lds + PG8_SA(b, h) + aoff + m * 2048 + k * 1024); } while (0)
; #define PG8_LDB(dst, b, h) do { _Pragma("unroll") for (int n = 0; n < 2; ++n) _Pragma("unroll") for (int k = 0; k < 2; ++k) dst[n][k] = *(const PG8_LAS bf16x8*)(lds + PG8_SB(b, h) + boff + n * 2048 + k * 1024); } while (0)
; #define PG8_MMA(ai, bj, At, Bt) do { __builtin_amdgcn_s_setprio(1); _Pragma("unroll") for (int m = 0; m < 4; ++m) _Pragma("unroll") for (int n = 0; n < 2; ++n) _Pragma("unroll") for (int k = 0; k < 2; ++k) \
;         acc[ai][bj][m][n] = __builtin_amdgcn_mfma_f32_16x16x32_bf16(Bt[n][k], At[m][k], acc[ai][bj][m][n], 0, 0, 0); __builtin_amdgcn_s_setprio(0); } while (0)
; #define PG8_WAIT_V(n) asm volatile("s_waitcnt vmcnt(" #n ")" ::: "memory")
; #define PG8_WAIT_L(n) asm volatile("s_waitcnt lgkmcnt(" #n ")" ::: "memory")
; template <class Epi, class Sched, bool ALIGN_EPI = false, bool SP2 = false>
; __device__ __forceinline__ void gemm_phase(PG8_LAS unsigned char* lds, const Gemm g, const Sched& S, const Epi& E) {
;     ...
;             const bool last = (t == nt - 2);
;             const char* a1 = cA + (size_t)(t + 1) * kstep;
;             const char* a2 = last ? nA : cA + (size_t)(t + 2) * kstep; const char* b2 = last ? nB : cB + (size_t)(t + 2) * kstep;
;             const char* a3 = a2 + kstep; const char* b3 = b2 + kstep;
;             if (last && has_next) S.a_ready(nxt);
;             if constexpr (SP2) {
;             PG8_LDB(B0, 0, 0); PG8_LDB(B1, 0, 1); PG8_SCHED; PG8_LDA(At, 0, 0); PG8_STAGE(PG8_SA(1, 1), a1 + hstep, voffA);
;             PG8_WAIT_V(8); PG8_WAIT_L(0); PG8_BAR; PG8_MMA(0, 0, At, B0); PG8_MMA(0, 1, At, B1); PG8_BAR; PG8_SCHED;
;             PG8_LDA(At, 0, 1); PG8_STAGE(PG8_SB(0, 0), b2, voffB); PG8_STAGE(PG8_SB(0, 1), b2 + hstep, voffB); PG8_STAGE(PG8_SA(0, 0), a2, voffA);
;             PG8_WAIT_V(8); PG8_WAIT_L(0); PG8_BAR; PG8_MMA(1, 0, At, B0); PG8_MMA(1, 1, At, B1); PG8_BAR; PG8_SCHED;
.LBB0_1595:
	ds_read_b128 v[130:133], v241 offset:0
	ds_read_b128 v[134:137], v241 offset:1024
	ds_read_b128 v[138:141], v241 offset:2048
	ds_read_b128 v[142:145], v241 offset:3072
	ds_read_b128 v[146:149], v241 offset:16384
	ds_read_b128 v[150:153], v241 offset:17408
	ds_read_b128 v[172:175], v241 offset:18432
	ds_read_b128 v[176:179], v241 offset:19456
	s_add_u32 s24, s26, 0xfff00080
	s_addc_u32 s25, s27, -1
	s_cmp_eq_u32 s62, 60
	s_cselect_b32 s29, s15, s25
	s_cselect_b32 s28, s21, s24
	s_cselect_b32 s25, s13, s53
	s_cselect_b32 s24, s51, s52
	s_add_i32 m0, s23, 0xc000
	ds_read_b128 v[180:183], v185
	ds_read_b128 v[188:191], v185 offset:1024
	ds_read_b128 v[192:195], v185 offset:2048
	ds_read_b128 v[196:199], v185 offset:3072
	ds_read_b128 v[200:203], v185 offset:4096
	ds_read_b128 v[204:207], v185 offset:5120
	ds_read_b128 v[208:211], v185 offset:6144
	ds_read_b128 v[212:215], v185 offset:7168
	global_load_lds_dwordx4 v162, s[26:27]
	s_add_i32 m0, s23, 0xe000
	s_nop 0
	global_load_lds_dwordx4 v166, s[26:27]
	s_waitcnt vmcnt(8)
	s_waitcnt lgkmcnt(0)
	s_barrier
	s_waitcnt lgkmcnt(0)
	v_mfma_f32_16x16x32_bf16 v[114:117], v[130:133], v[180:183], v[114:117]
	v_mfma_f32_16x16x32_bf16 v[118:121], v[138:141], v[180:183], v[118:121]
	v_mfma_f32_16x16x32_bf16 v[106:109], v[130:133], v[192:195], v[106:109]
	v_mfma_f32_16x16x32_bf16 v[98:101], v[138:141], v[192:195], v[98:101]
	v_mfma_f32_16x16x32_bf16 v[90:93], v[130:133], v[200:203], v[90:93]
	v_mfma_f32_16x16x32_bf16 v[82:85], v[138:141], v[200:203], v[82:85]
	v_mfma_f32_16x16x32_bf16 v[74:77], v[130:133], v[208:211], v[74:77]
	v_mfma_f32_16x16x32_bf16 v[66:69], v[138:141], v[208:211], v[66:69]
	v_mfma_f32_16x16x32_bf16 v[114:117], v[134:137], v[188:191], v[114:117]
	v_mfma_f32_16x16x32_bf16 v[118:121], v[142:145], v[188:191], v[118:121]
	v_mfma_f32_16x16x32_bf16 v[106:109], v[134:137], v[196:199], v[106:109]
	v_mfma_f32_16x16x32_bf16 v[98:101], v[142:145], v[196:199], v[98:101]
	v_mfma_f32_16x16x32_bf16 v[90:93], v[134:137], v[204:207], v[90:93]
	v_mfma_f32_16x16x32_bf16 v[82:85], v[142:145], v[204:207], v[82:85]
	v_mfma_f32_16x16x32_bf16 v[74:77], v[134:137], v[212:215], v[74:77]
	v_mfma_f32_16x16x32_bf16 v[66:69], v[142:145], v[212:215], v[66:69]
	v_mfma_f32_16x16x32_bf16 v[122:125], v[146:149], v[180:183], v[122:125]
	v_mfma_f32_16x16x32_bf16 v[126:129], v[172:175], v[180:183], v[126:129]
	v_mfma_f32_16x16x32_bf16 v[110:113], v[146:149], v[192:195], v[110:113]
	v_mfma_f32_16x16x32_bf16 v[102:105], v[172:175], v[192:195], v[102:105]
	v_mfma_f32_16x16x32_bf16 v[94:97], v[146:149], v[200:203], v[94:97]
	v_mfma_f32_16x16x32_bf16 v[86:89], v[172:175], v[200:203], v[86:89]
	v_mfma_f32_16x16x32_bf16 v[78:81], v[146:149], v[208:211], v[78:81]
	v_mfma_f32_16x16x32_bf16 v[70:73], v[172:175], v[208:211], v[70:73]
	v_mfma_f32_16x16x32_bf16 v[122:125], v[150:153], v[188:191], v[122:125]
	v_mfma_f32_16x16x32_bf16 v[126:129], v[176:179], v[188:191], v[126:129]
	v_mfma_f32_16x16x32_bf16 v[110:113], v[150:153], v[196:199], v[110:113]
	v_mfma_f32_16x16x32_bf16 v[102:105], v[176:179], v[196:199], v[102:105]
	v_mfma_f32_16x16x32_bf16 v[94:97], v[150:153], v[204:207], v[94:97]
	v_mfma_f32_16x16x32_bf16 v[86:89], v[176:179], v[204:207], v[86:89]
	v_mfma_f32_16x16x32_bf16 v[78:81], v[150:153], v[212:215], v[78:81]
	v_mfma_f32_16x16x32_bf16 v[70:73], v[176:179], v[212:215], v[70:73]
	s_barrier
	s_add_i32 s33, s48, s36
	s_mov_b32 m0, s33
	ds_read_b128 v[180:183], v185 offset:16384
	ds_read_b128 v[188:191], v185 offset:17408
	ds_read_b128 v[192:195], v185 offset:18432
	ds_read_b128 v[196:199], v185 offset:19456
	ds_read_b128 v[200:203], v185 offset:20480
	ds_read_b128 v[204:207], v185 offset:21504
	ds_read_b128 v[208:211], v185 offset:22528
	ds_read_b128 v[212:215], v185 offset:23552
	global_load_lds_dwordx4 v156, s[24:25]
	s_add_i32 m0, s33, 0x2000
	s_add_u32 s64, s24, 0x100000
	s_addc_u32 s65, s25, 0
	s_add_i32 s33, s49, s36
	global_load_lds_dwordx4 v160, s[24:25]
	s_mov_b32 m0, s33
	s_add_u32 s100, s28, 0x80
	s_addc_u32 s101, s29, 0
	global_load_lds_dwordx4 v156, s[64:65]
	s_add_i32 m0, s33, 0x2000
	s_nop 0
	global_load_lds_dwordx4 v160, s[64:65]
	s_mov_b32 m0, s23
	s_nop 0
	global_load_lds_dwordx4 v154, s[28:29]
	s_mov_b32 m0, s37
	s_nop 0
	global_load_lds_dwordx4 v158, s[28:29]
	s_waitcnt vmcnt(8)
	s_waitcnt lgkmcnt(0)
	s_barrier
	s_waitcnt lgkmcnt(0)
	v_mfma_f32_16x16x32_bf16 v[58:61], v[130:133], v[180:183], v[58:61]
	v_mfma_f32_16x16x32_bf16 v[54:57], v[138:141], v[180:183], v[54:57]
	v_mfma_f32_16x16x32_bf16 v[42:45], v[130:133], v[192:195], v[42:45]
	v_mfma_f32_16x16x32_bf16 v[34:37], v[138:141], v[192:195], v[34:37]
	v_mfma_f32_16x16x32_bf16 v[26:29], v[130:133], v[200:203], v[26:29]
	v_mfma_f32_16x16x32_bf16 v[18:21], v[138:141], v[200:203], v[18:21]
	v_mfma_f32_16x16x32_bf16 v[6:9], v[130:133], v[208:211], v[6:9]
	v_mfma_f32_16x16x32_bf16 v[2:5], v[138:141], v[208:211], v[2:5]
	v_mfma_f32_16x16x32_bf16 v[58:61], v[134:137], v[188:191], v[58:61]
	v_mfma_f32_16x16x32_bf16 v[54:57], v[142:145], v[188:191], v[54:57]
	v_mfma_f32_16x16x32_bf16 v[42:45], v[134:137], v[196:199], v[42:45]
	v_mfma_f32_16x16x32_bf16 v[34:37], v[142:145], v[196:199], v[34:37]
	v_mfma_f32_16x16x32_bf16 v[26:29], v[134:137], v[204:207], v[26:29]
	v_mfma_f32_16x16x32_bf16 v[18:21], v[142:145], v[204:207], v[18:21]
	v_mfma_f32_16x16x32_bf16 v[6:9], v[134:137], v[212:215], v[6:9]
	v_mfma_f32_16x16x32_bf16 v[2:5], v[142:145], v[212:215], v[2:5]
	v_mfma_f32_16x16x32_bf16 v[62:65], v[146:149], v[180:183], v[62:65]
	v_mfma_f32_16x16x32_bf16 v[50:53], v[172:175], v[180:183], v[50:53]
	v_mfma_f32_16x16x32_bf16 v[46:49], v[146:149], v[192:195], v[46:49]
	v_mfma_f32_16x16x32_bf16 v[38:41], v[172:175], v[192:195], v[38:41]
	v_mfma_f32_16x16x32_bf16 v[30:33], v[146:149], v[200:203], v[30:33]
	v_mfma_f32_16x16x32_bf16 v[22:25], v[172:175], v[200:203], v[22:25]
	v_mfma_f32_16x16x32_bf16 v[10:13], v[146:149], v[208:211], v[10:13]
	v_mfma_f32_16x16x32_bf16 v[14:17], v[172:175], v[208:211], v[14:17]
	v_mfma_f32_16x16x32_bf16 v[62:65], v[150:153], v[188:191], v[62:65]
	v_mfma_f32_16x16x32_bf16 v[50:53], v[176:179], v[188:191], v[50:53]
	v_mfma_f32_16x16x32_bf16 v[46:49], v[150:153], v[196:199], v[46:49]
	v_mfma_f32_16x16x32_bf16 v[38:41], v[176:179], v[196:199], v[38:41]
	v_mfma_f32_16x16x32_bf16 v[30:33], v[150:153], v[204:207], v[30:33]
	v_mfma_f32_16x16x32_bf16 v[22:25], v[176:179], v[204:207], v[22:25]
	v_mfma_f32_16x16x32_bf16 v[10:13], v[150:153], v[212:215], v[10:13]
	v_mfma_f32_16x16x32_bf16 v[14:17], v[176:179], v[212:215], v[14:17]
	s_barrier
; #define PG8_STAGE(bufoff, gbase, voff) do { _Pragma("unroll") for (int _i = 0; _i < 2; ++_i) \
;         __builtin_amdgcn_global_load_lds((const unsigned*)((const char*)(gbase) + (voff)[_i]), (PG8_LAS unsigned*)(lds + (bufoff) + ldsw + _i * 8192), 16, 0, 0); } while (0)
; #define PG8_LDA(dst, b, h) do { _Pragma("unroll") for (int m = 0; m < 4; ++m) _Pragma("unroll") for (int k = 0; k < 2; ++k) dst[m][k] = *(const PG8_LAS bf16x8*)(lds + PG8_SA(b, h) + aoff + m * 2048 + k * 1024); } while (0)
; #define PG8_LDB(dst, b, h) do { _Pragma("unroll") for (int n = 0; n < 2; ++n) _Pragma("unroll") for (int k = 0; k < 2; ++k) dst[n][k] = *(const PG8_LAS bf16x8*)(lds + PG8_SB(b, h) + boff + n * 2048 + k * 1024); } while (0)
; #define PG8_MMA(ai, bj, At, Bt) do { __builtin_amdgcn_s_setprio(1); _Pragma("unroll") for (int m = 0; m < 4; ++m) _Pragma("unroll") for (int n = 0; n < 2; ++n) _Pragma("unroll") for (int k = 0; k < 2; ++k) \
;         acc[ai][bj][m][n] = __builtin_amdgcn_mfma_f32_16x16x32_bf16(Bt[n][k], At[m][k], acc[ai][bj][m][n], 0, 0, 0); __builtin_amdgcn_s_setprio(0); } while (0)
; #define PG8_WAIT_V(n) asm volatile("s_waitcnt vmcnt(" #n ")" ::: "memory")
; #define PG8_WAIT_L(n) asm volatile("s_waitcnt lgkmcnt(" #n ")" ::: "memory")
; #define PG8_BAR __builtin_amdgcn_s_barrier()
; #define PG8_SCHED __builtin_amdgcn_sched_barrier(0)
; template <class Epi, class Sched, bool ALIGN_EPI = false, bool SP2 = false>
; __device__ __forceinline__ void gemm_phase(PG8_LAS unsigned char* lds, const Gemm g, const Sched& S, const Epi& E) {
;     ...
;         for (int t = 0; t < nt; t += 2) {
;             const bool last = (t == nt - 2);
;     ...
;             PG8_LDB(B0, 1, 0); PG8_LDB(B1, 1, 1); PG8_SCHED; PG8_LDA(At, 1, 0); PG8_STAGE(PG8_SA(0, 1), a2 + hstep, voffA);
;             PG8_WAIT_V(8); PG8_WAIT_L(0); PG8_BAR; PG8_MMA(0, 0, At, B0); PG8_MMA(0, 1, At, B1); PG8_BAR; PG8_SCHED;
;             PG8_LDA(At, 1, 1); PG8_STAGE(PG8_SB(1, 0), b3, voffB); PG8_STAGE(PG8_SB(1, 1), b3 + hstep, voffB); PG8_STAGE(PG8_SA(1, 0), a3, voffA);
;             PG8_WAIT_V(8); PG8_WAIT_L(0); PG8_BAR; PG8_MMA(1, 0, At, B0); PG8_MMA(1, 1, At, B1); PG8_BAR; PG8_SCHED;
	s_add_i32 s33, 0, 0x18000
	s_add_i32 s42, 0, 0x1c000
	ds_read_b128 v[130:133], v241 offset:32768
	ds_read_b128 v[134:137], v241 offset:33792
	ds_read_b128 v[138:141], v241 offset:34816
	ds_read_b128 v[142:145], v241 offset:35840
	ds_read_b128 v[146:149], v241 offset:49152
	ds_read_b128 v[150:153], v241 offset:50176
	ds_read_b128 v[172:175], v241 offset:51200
	ds_read_b128 v[176:179], v241 offset:52224
	s_add_u32 s28, s28, 0x100000
	s_addc_u32 s29, s29, 0
	s_mov_b32 m0, s40
	ds_read_b128 v[180:183], v185 offset:32768
	ds_read_b128 v[188:191], v185 offset:33792
	ds_read_b128 v[192:195], v185 offset:34816
	ds_read_b128 v[196:199], v185 offset:35840
	ds_read_b128 v[200:203], v185 offset:36864
	ds_read_b128 v[204:207], v185 offset:37888
	ds_read_b128 v[208:211], v185 offset:38912
	ds_read_b128 v[212:215], v185 offset:39936
	global_load_lds_dwordx4 v154, s[28:29]
	s_mov_b32 m0, s41
	s_nop 0
	global_load_lds_dwordx4 v158, s[28:29]
	s_waitcnt vmcnt(8)
	s_waitcnt lgkmcnt(0)
	s_barrier
	s_waitcnt lgkmcnt(0)
	v_mfma_f32_16x16x32_bf16 v[114:117], v[130:133], v[180:183], v[114:117]
	v_mfma_f32_16x16x32_bf16 v[118:121], v[138:141], v[180:183], v[118:121]
	v_mfma_f32_16x16x32_bf16 v[106:109], v[130:133], v[192:195], v[106:109]
	v_mfma_f32_16x16x32_bf16 v[98:101], v[138:141], v[192:195], v[98:101]
	v_mfma_f32_16x16x32_bf16 v[90:93], v[130:133], v[200:203], v[90:93]
	v_mfma_f32_16x16x32_bf16 v[82:85], v[138:141], v[200:203], v[82:85]
	v_mfma_f32_16x16x32_bf16 v[74:77], v[130:133], v[208:211], v[74:77]
	v_mfma_f32_16x16x32_bf16 v[66:69], v[138:141], v[208:211], v[66:69]
	v_mfma_f32_16x16x32_bf16 v[114:117], v[134:137], v[188:191], v[114:117]
	v_mfma_f32_16x16x32_bf16 v[118:121], v[142:145], v[188:191], v[118:121]
	v_mfma_f32_16x16x32_bf16 v[106:109], v[134:137], v[196:199], v[106:109]
	v_mfma_f32_16x16x32_bf16 v[98:101], v[142:145], v[196:199], v[98:101]
	v_mfma_f32_16x16x32_bf16 v[90:93], v[134:137], v[204:207], v[90:93]
	v_mfma_f32_16x16x32_bf16 v[82:85], v[142:145], v[204:207], v[82:85]
	v_mfma_f32_16x16x32_bf16 v[74:77], v[134:137], v[212:215], v[74:77]
	v_mfma_f32_16x16x32_bf16 v[66:69], v[142:145], v[212:215], v[66:69]
	v_mfma_f32_16x16x32_bf16 v[122:125], v[146:149], v[180:183], v[122:125]
	v_mfma_f32_16x16x32_bf16 v[126:129], v[172:175], v[180:183], v[126:129]
	v_mfma_f32_16x16x32_bf16 v[110:113], v[146:149], v[192:195], v[110:113]
	v_mfma_f32_16x16x32_bf16 v[102:105], v[172:175], v[192:195], v[102:105]
	v_mfma_f32_16x16x32_bf16 v[94:97], v[146:149], v[200:203], v[94:97]
	v_mfma_f32_16x16x32_bf16 v[86:89], v[172:175], v[200:203], v[86:89]
	v_mfma_f32_16x16x32_bf16 v[78:81], v[146:149], v[208:211], v[78:81]
	v_mfma_f32_16x16x32_bf16 v[70:73], v[172:175], v[208:211], v[70:73]
	v_mfma_f32_16x16x32_bf16 v[122:125], v[150:153], v[188:191], v[122:125]
	v_mfma_f32_16x16x32_bf16 v[126:129], v[176:179], v[188:191], v[126:129]
	v_mfma_f32_16x16x32_bf16 v[110:113], v[150:153], v[196:199], v[110:113]
	v_mfma_f32_16x16x32_bf16 v[102:105], v[176:179], v[196:199], v[102:105]
	v_mfma_f32_16x16x32_bf16 v[94:97], v[150:153], v[204:207], v[94:97]
	v_mfma_f32_16x16x32_bf16 v[86:89], v[176:179], v[204:207], v[86:89]
	v_mfma_f32_16x16x32_bf16 v[78:81], v[150:153], v[212:215], v[78:81]
	v_mfma_f32_16x16x32_bf16 v[70:73], v[176:179], v[212:215], v[70:73]
	s_barrier
	s_add_i32 s28, s33, s36
	s_add_i32 m0, s28, 0xffffff80
	ds_read_b128 v[180:183], v185 offset:49152
	ds_read_b128 v[188:191], v185 offset:50176
	ds_read_b128 v[192:195], v185 offset:51200
	ds_read_b128 v[196:199], v185 offset:52224
	ds_read_b128 v[200:203], v185 offset:53248
	ds_read_b128 v[204:207], v185 offset:54272
	ds_read_b128 v[208:211], v185 offset:55296
	ds_read_b128 v[212:215], v185 offset:56320
	global_load_lds_dwordx4 v156, s[24:25] offset:128
	s_add_i32 m0, s28, 0x1f80
	s_add_i32 s28, s42, s36
	global_load_lds_dwordx4 v160, s[24:25] offset:128
	s_add_u32 s24, s24, 0x100080
	s_addc_u32 s25, s25, 0
	s_mov_b32 m0, s28
	s_nop 0
	global_load_lds_dwordx4 v156, s[24:25]
	s_add_i32 m0, s28, 0x2000
	s_nop 0
	global_load_lds_dwordx4 v160, s[24:25]
	s_mov_b32 m0, s44
	s_nop 0
	global_load_lds_dwordx4 v154, s[100:101]
	s_mov_b32 m0, s45
	s_nop 0
	global_load_lds_dwordx4 v158, s[100:101]
	s_waitcnt vmcnt(8)
	s_waitcnt lgkmcnt(0)
	s_barrier
	s_waitcnt lgkmcnt(0)
	v_mfma_f32_16x16x32_bf16 v[58:61], v[130:133], v[180:183], v[58:61]
	v_mfma_f32_16x16x32_bf16 v[54:57], v[138:141], v[180:183], v[54:57]
	v_mfma_f32_16x16x32_bf16 v[42:45], v[130:133], v[192:195], v[42:45]
	v_mfma_f32_16x16x32_bf16 v[34:37], v[138:141], v[192:195], v[34:37]
	v_mfma_f32_16x16x32_bf16 v[26:29], v[130:133], v[200:203], v[26:29]
	v_mfma_f32_16x16x32_bf16 v[18:21], v[138:141], v[200:203], v[18:21]
	v_mfma_f32_16x16x32_bf16 v[6:9], v[130:133], v[208:211], v[6:9]
	v_mfma_f32_16x16x32_bf16 v[2:5], v[138:141], v[208:211], v[2:5]
	v_mfma_f32_16x16x32_bf16 v[58:61], v[134:137], v[188:191], v[58:61]
	v_mfma_f32_16x16x32_bf16 v[54:57], v[142:145], v[188:191], v[54:57]
	v_mfma_f32_16x16x32_bf16 v[42:45], v[134:137], v[196:199], v[42:45]
	v_mfma_f32_16x16x32_bf16 v[34:37], v[142:145], v[196:199], v[34:37]
	v_mfma_f32_16x16x32_bf16 v[26:29], v[134:137], v[204:207], v[26:29]
	v_mfma_f32_16x16x32_bf16 v[18:21], v[142:145], v[204:207], v[18:21]
	v_mfma_f32_16x16x32_bf16 v[6:9], v[134:137], v[212:215], v[6:9]
	v_mfma_f32_16x16x32_bf16 v[2:5], v[142:145], v[212:215], v[2:5]
	v_mfma_f32_16x16x32_bf16 v[62:65], v[146:149], v[180:183], v[62:65]
	v_mfma_f32_16x16x32_bf16 v[50:53], v[172:175], v[180:183], v[50:53]
	v_mfma_f32_16x16x32_bf16 v[46:49], v[146:149], v[192:195], v[46:49]
	v_mfma_f32_16x16x32_bf16 v[38:41], v[172:175], v[192:195], v[38:41]
	v_mfma_f32_16x16x32_bf16 v[30:33], v[146:149], v[200:203], v[30:33]
	v_mfma_f32_16x16x32_bf16 v[22:25], v[172:175], v[200:203], v[22:25]
	v_mfma_f32_16x16x32_bf16 v[10:13], v[146:149], v[208:211], v[10:13]
	v_mfma_f32_16x16x32_bf16 v[14:17], v[172:175], v[208:211], v[14:17]
	v_mfma_f32_16x16x32_bf16 v[62:65], v[150:153], v[188:191], v[62:65]
	v_mfma_f32_16x16x32_bf16 v[50:53], v[176:179], v[188:191], v[50:53]
	v_mfma_f32_16x16x32_bf16 v[46:49], v[150:153], v[196:199], v[46:49]
	v_mfma_f32_16x16x32_bf16 v[38:41], v[176:179], v[196:199], v[38:41]
	v_mfma_f32_16x16x32_bf16 v[30:33], v[150:153], v[204:207], v[30:33]
	v_mfma_f32_16x16x32_bf16 v[22:25], v[176:179], v[204:207], v[22:25]
	v_mfma_f32_16x16x32_bf16 v[10:13], v[150:153], v[212:215], v[10:13]
	v_mfma_f32_16x16x32_bf16 v[14:17], v[176:179], v[212:215], v[14:17]
	s_barrier
	s_add_i32 s62, s62, 2
	s_add_u32 s26, s26, 0x100
	s_addc_u32 s27, s27, 0
	s_add_u32 s52, s52, 0x100
	s_addc_u32 s53, s53, 0
	s_cmp_gt_u32 s62, 61
	s_cbranch_scc0 .LBB0_1595


; #define PG8_BAR __builtin_amdgcn_s_barrier()
; template <class Epi, class Sched, bool ALIGN_EPI = false, bool SP2 = false>
; __device__ __forceinline__ void gemm_phase(PG8_LAS unsigned char* lds, const Gemm g, const Sched& S, const Epi& E) {
;     ...
;         if constexpr (ALIGN_EPI) { if (wr == 0) PG8_BAR; }
;         if constexpr (!Epi::AFTER_DRAIN) { E(acc, cur, wr, wc, fr, fq); S.done(cur); }
;         if (!has_next) break;
	s_and_b64 vcc, exec, s[10:11]
	s_cbranch_vccz .LBB0_1598
	s_barrier

; #define PG8_STAGE(bufoff, gbase, voff) do { _Pragma("unroll") for (int _i = 0; _i < 2; ++_i) \
;         __builtin_amdgcn_global_load_lds((const unsigned*)((const char*)(gbase) + (voff)[_i]), (PG8_LAS unsigned*)(lds + (bufoff) + ldsw + _i * 8192), 16, 0, 0); } while (0)
; #define PG8_LDA(dst, b, h) do { _Pragma("unroll") for (int m = 0; m < 4; ++m) _Pragma("unroll") for (int k = 0; k < 2; ++k) dst[m][k] = *(const PG8_LAS bf16x8*)(lds + PG8_SA(b, h) + aoff + m * 2048 + k * 1024); } while (0)
; #define PG8_LDB(dst, b, h) do { _Pragma("unroll") for (int n = 0; n < 2; ++n) _Pragma("unroll") for (int k = 0; k < 2; ++k) dst[n][k] = *(const PG8_LAS bf16x8*)(lds + PG8_SB(b, h) + boff + n * 2048 + k * 1024); } while (0)
; #define PG8_MMA(ai, bj, At, Bt) do { __builtin_amdgcn_s_setprio(1); _Pragma("unroll") for (int m = 0; m < 4; ++m) _Pragma("unroll") for (int n = 0; n < 2; ++n) _Pragma("unroll") for (int k = 0; k < 2; ++k) \
;         acc[ai][bj][m][n] = __builtin_amdgcn_mfma_f32_16x16x32_bf16(Bt[n][k], At[m][k], acc[ai][bj][m][n], 0, 0, 0); __builtin_amdgcn_s_setprio(0); } while (0)
; #define PG8_WAIT_V(n) asm volatile("s_waitcnt vmcnt(" #n ")" ::: "memory")
; #define PG8_WAIT_L(n) asm volatile("s_waitcnt lgkmcnt(" #n ")" ::: "memory")
; template <class Epi, class Sched, bool ALIGN_EPI = false, bool SP2 = false>
; __device__ __forceinline__ void gemm_phase(PG8_LAS unsigned char* lds, const Gemm g, const Sched& S, const Epi& E) {
;     ...
;             const bool last = (t == nt - 2);
;             const char* a1 = cA + (size_t)(t + 1) * kstep;
;             const char* a2 = last ? nA : cA + (size_t)(t + 2) * kstep; const char* b2 = last ? nB : cB + (size_t)(t + 2) * kstep;
;             const char* a3 = a2 + kstep; const char* b3 = b2 + kstep;
;             if (last && has_next) S.a_ready(nxt);
;             if constexpr (SP2) {
;             PG8_LDB(B0, 0, 0); PG8_LDB(B1, 0, 1); PG8_SCHED; PG8_LDA(At, 0, 0); PG8_STAGE(PG8_SA(1, 1), a1 + hstep, voffA);
;             PG8_WAIT_V(8); PG8_WAIT_L(0); PG8_BAR; PG8_MMA(0, 0, At, B0); PG8_MMA(0, 1, At, B1); PG8_BAR; PG8_SCHED;
;             PG8_LDA(At, 0, 1); PG8_STAGE(PG8_SB(0, 0), b2, voffB); PG8_STAGE(PG8_SB(0, 1), b2 + hstep, voffB); PG8_STAGE(PG8_SA(0, 0), a2, voffA);
;             PG8_WAIT_V(8); PG8_WAIT_L(0); PG8_BAR; PG8_MMA(1, 0, At, B0); PG8_MMA(1, 1, At, B1); PG8_BAR; PG8_SCHED;
.LBB0_1681:
	ds_read_b128 v[160:163], v241 offset:0
	ds_read_b128 v[166:169], v241 offset:1024
	ds_read_b128 v[170:173], v241 offset:2048
	ds_read_b128 v[174:177], v241 offset:3072
	ds_read_b128 v[178:181], v241 offset:16384
	ds_read_b128 v[182:185], v241 offset:17408
	ds_read_b128 v[186:189], v241 offset:18432
	ds_read_b128 v[190:193], v241 offset:19456
	s_add_u32 s22, s24, 0xfff00080
	s_addc_u32 s23, s25, -1
	s_cmp_eq_u32 s52, 60
	s_cselect_b32 s27, s15, s23
	s_cselect_b32 s26, s48, s22
	s_cselect_b32 s23, s13, s51
	s_cselect_b32 s22, s49, s50
	s_add_i32 m0, s21, 0xc000
	ds_read_b128 v[194:197], v155
	ds_read_b128 v[198:201], v155 offset:1024
	ds_read_b128 v[202:205], v155 offset:2048
	ds_read_b128 v[206:209], v155 offset:3072
	ds_read_b128 v[210:213], v155 offset:4096
	ds_read_b128 v[214:217], v155 offset:5120
	ds_read_b128 v[218:221], v155 offset:6144
	ds_read_b128 v[222:225], v155 offset:7168
	global_load_lds_dwordx4 v138, s[24:25]
	s_add_i32 m0, s21, 0xe000
	s_nop 0
	global_load_lds_dwordx4 v140, s[24:25]
	s_waitcnt vmcnt(8)
	s_waitcnt lgkmcnt(0)
	s_barrier
	s_waitcnt lgkmcnt(0)
	v_mfma_f32_16x16x32_bf16 v[122:125], v[160:163], v[194:197], v[122:125]
	v_mfma_f32_16x16x32_bf16 v[114:117], v[170:173], v[194:197], v[114:117]
	v_mfma_f32_16x16x32_bf16 v[106:109], v[160:163], v[202:205], v[106:109]
	v_mfma_f32_16x16x32_bf16 v[98:101], v[170:173], v[202:205], v[98:101]
	v_mfma_f32_16x16x32_bf16 v[90:93], v[160:163], v[210:213], v[90:93]
	v_mfma_f32_16x16x32_bf16 v[82:85], v[170:173], v[210:213], v[82:85]
	v_mfma_f32_16x16x32_bf16 v[74:77], v[160:163], v[218:221], v[74:77]
	v_mfma_f32_16x16x32_bf16 v[62:65], v[170:173], v[218:221], v[62:65]
	v_mfma_f32_16x16x32_bf16 v[122:125], v[166:169], v[198:201], v[122:125]
	v_mfma_f32_16x16x32_bf16 v[114:117], v[174:177], v[198:201], v[114:117]
	v_mfma_f32_16x16x32_bf16 v[106:109], v[166:169], v[206:209], v[106:109]
	v_mfma_f32_16x16x32_bf16 v[98:101], v[174:177], v[206:209], v[98:101]
	v_mfma_f32_16x16x32_bf16 v[90:93], v[166:169], v[214:217], v[90:93]
	v_mfma_f32_16x16x32_bf16 v[82:85], v[174:177], v[214:217], v[82:85]
	v_mfma_f32_16x16x32_bf16 v[74:77], v[166:169], v[222:225], v[74:77]
	v_mfma_f32_16x16x32_bf16 v[62:65], v[174:177], v[222:225], v[62:65]
	v_mfma_f32_16x16x32_bf16 v[126:129], v[178:181], v[194:197], v[126:129]
	v_mfma_f32_16x16x32_bf16 v[118:121], v[186:189], v[194:197], v[118:121]
	v_mfma_f32_16x16x32_bf16 v[110:113], v[178:181], v[202:205], v[110:113]
	v_mfma_f32_16x16x32_bf16 v[102:105], v[186:189], v[202:205], v[102:105]
	v_mfma_f32_16x16x32_bf16 v[94:97], v[178:181], v[210:213], v[94:97]
	v_mfma_f32_16x16x32_bf16 v[86:89], v[186:189], v[210:213], v[86:89]
	v_mfma_f32_16x16x32_bf16 v[78:81], v[178:181], v[218:221], v[78:81]
	v_mfma_f32_16x16x32_bf16 v[70:73], v[186:189], v[218:221], v[70:73]
	v_mfma_f32_16x16x32_bf16 v[126:129], v[182:185], v[198:201], v[126:129]
	v_mfma_f32_16x16x32_bf16 v[118:121], v[190:193], v[198:201], v[118:121]
	v_mfma_f32_16x16x32_bf16 v[110:113], v[182:185], v[206:209], v[110:113]
	v_mfma_f32_16x16x32_bf16 v[102:105], v[190:193], v[206:209], v[102:105]
	v_mfma_f32_16x16x32_bf16 v[94:97], v[182:185], v[214:217], v[94:97]
	v_mfma_f32_16x16x32_bf16 v[86:89], v[190:193], v[214:217], v[86:89]
	v_mfma_f32_16x16x32_bf16 v[78:81], v[182:185], v[222:225], v[78:81]
	v_mfma_f32_16x16x32_bf16 v[70:73], v[190:193], v[222:225], v[70:73]
	s_barrier
	s_add_i32 s33, s44, s29
	s_mov_b32 m0, s33
	ds_read_b128 v[194:197], v155 offset:16384
	ds_read_b128 v[198:201], v155 offset:17408
	ds_read_b128 v[202:205], v155 offset:18432
	ds_read_b128 v[206:209], v155 offset:19456
	ds_read_b128 v[210:213], v155 offset:20480
	ds_read_b128 v[214:217], v155 offset:21504
	ds_read_b128 v[218:221], v155 offset:22528
	ds_read_b128 v[222:225], v155 offset:23552
	global_load_lds_dwordx4 v132, s[22:23]
	s_add_i32 m0, s33, 0x2000
	s_add_u32 s62, s22, 0x100000
	s_addc_u32 s63, s23, 0
	s_add_i32 s33, s45, s29
	global_load_lds_dwordx4 v136, s[22:23]
	s_mov_b32 m0, s33
	s_add_u32 s100, s26, 0x80
	s_addc_u32 s101, s27, 0
	global_load_lds_dwordx4 v132, s[62:63]
	s_add_i32 m0, s33, 0x2000
	s_nop 0
	global_load_lds_dwordx4 v136, s[62:63]
	s_mov_b32 m0, s21
	s_nop 0
	global_load_lds_dwordx4 v130, s[26:27]
	s_mov_b32 m0, s34
	s_nop 0
	global_load_lds_dwordx4 v134, s[26:27]
	s_waitcnt vmcnt(8)
	s_waitcnt lgkmcnt(0)
	s_barrier
	s_waitcnt lgkmcnt(0)
	v_mfma_f32_16x16x32_bf16 v[58:61], v[160:163], v[194:197], v[58:61]
	v_mfma_f32_16x16x32_bf16 v[50:53], v[170:173], v[194:197], v[50:53]
	v_mfma_f32_16x16x32_bf16 v[42:45], v[160:163], v[202:205], v[42:45]
	v_mfma_f32_16x16x32_bf16 v[34:37], v[170:173], v[202:205], v[34:37]
	v_mfma_f32_16x16x32_bf16 v[26:29], v[160:163], v[210:213], v[26:29]
	v_mfma_f32_16x16x32_bf16 v[18:21], v[170:173], v[210:213], v[18:21]
	v_mfma_f32_16x16x32_bf16 v[10:13], v[160:163], v[218:221], v[10:13]
	v_mfma_f32_16x16x32_bf16 v[2:5], v[170:173], v[218:221], v[2:5]
	v_mfma_f32_16x16x32_bf16 v[58:61], v[166:169], v[198:201], v[58:61]
	v_mfma_f32_16x16x32_bf16 v[50:53], v[174:177], v[198:201], v[50:53]
	v_mfma_f32_16x16x32_bf16 v[42:45], v[166:169], v[206:209], v[42:45]
	v_mfma_f32_16x16x32_bf16 v[34:37], v[174:177], v[206:209], v[34:37]
	v_mfma_f32_16x16x32_bf16 v[26:29], v[166:169], v[214:217], v[26:29]
	v_mfma_f32_16x16x32_bf16 v[18:21], v[174:177], v[214:217], v[18:21]
	v_mfma_f32_16x16x32_bf16 v[10:13], v[166:169], v[222:225], v[10:13]
	v_mfma_f32_16x16x32_bf16 v[2:5], v[174:177], v[222:225], v[2:5]
	v_mfma_f32_16x16x32_bf16 v[66:69], v[178:181], v[194:197], v[66:69]
	v_mfma_f32_16x16x32_bf16 v[54:57], v[186:189], v[194:197], v[54:57]
	v_mfma_f32_16x16x32_bf16 v[46:49], v[178:181], v[202:205], v[46:49]
	v_mfma_f32_16x16x32_bf16 v[38:41], v[186:189], v[202:205], v[38:41]
	v_mfma_f32_16x16x32_bf16 v[30:33], v[178:181], v[210:213], v[30:33]
	v_mfma_f32_16x16x32_bf16 v[22:25], v[186:189], v[210:213], v[22:25]
	v_mfma_f32_16x16x32_bf16 v[14:17], v[178:181], v[218:221], v[14:17]
	v_mfma_f32_16x16x32_bf16 v[6:9], v[186:189], v[218:221], v[6:9]
	v_mfma_f32_16x16x32_bf16 v[66:69], v[182:185], v[198:201], v[66:69]
	v_mfma_f32_16x16x32_bf16 v[54:57], v[190:193], v[198:201], v[54:57]
	v_mfma_f32_16x16x32_bf16 v[46:49], v[182:185], v[206:209], v[46:49]
	v_mfma_f32_16x16x32_bf16 v[38:41], v[190:193], v[206:209], v[38:41]
	v_mfma_f32_16x16x32_bf16 v[30:33], v[182:185], v[214:217], v[30:33]
	v_mfma_f32_16x16x32_bf16 v[22:25], v[190:193], v[214:217], v[22:25]
	v_mfma_f32_16x16x32_bf16 v[14:17], v[182:185], v[222:225], v[14:17]
	v_mfma_f32_16x16x32_bf16 v[6:9], v[190:193], v[222:225], v[6:9]
	s_barrier
; #define PG8_STAGE(bufoff, gbase, voff) do { _Pragma("unroll") for (int _i = 0; _i < 2; ++_i) \
;         __builtin_amdgcn_global_load_lds((const unsigned*)((const char*)(gbase) + (voff)[_i]), (PG8_LAS unsigned*)(lds + (bufoff) + ldsw + _i * 8192), 16, 0, 0); } while (0)
; #define PG8_LDA(dst, b, h) do { _Pragma("unroll") for (int m = 0; m < 4; ++m) _Pragma("unroll") for (int k = 0; k < 2; ++k) dst[m][k] = *(const PG8_LAS bf16x8*)(lds + PG8_SA(b, h) + aoff + m * 2048 + k * 1024); } while (0)
; #define PG8_LDB(dst, b, h) do { _Pragma("unroll") for (int n = 0; n < 2; ++n) _Pragma("unroll") for (int k = 0; k < 2; ++k) dst[n][k] = *(const PG8_LAS bf16x8*)(lds + PG8_SB(b, h) + boff + n * 2048 + k * 1024); } while (0)
; #define PG8_MMA(ai, bj, At, Bt) do { __builtin_amdgcn_s_setprio(1); _Pragma("unroll") for (int m = 0; m < 4; ++m) _Pragma("unroll") for (int n = 0; n < 2; ++n) _Pragma("unroll") for (int k = 0; k < 2; ++k) \
;         acc[ai][bj][m][n] = __builtin_amdgcn_mfma_f32_16x16x32_bf16(Bt[n][k], At[m][k], acc[ai][bj][m][n], 0, 0, 0); __builtin_amdgcn_s_setprio(0); } while (0)
; #define PG8_WAIT_V(n) asm volatile("s_waitcnt vmcnt(" #n ")" ::: "memory")
; #define PG8_WAIT_L(n) asm volatile("s_waitcnt lgkmcnt(" #n ")" ::: "memory")
; #define PG8_BAR __builtin_amdgcn_s_barrier()
; #define PG8_SCHED __builtin_amdgcn_sched_barrier(0)
; template <class Epi, class Sched, bool ALIGN_EPI = false, bool SP2 = false>
; __device__ __forceinline__ void gemm_phase(PG8_LAS unsigned char* lds, const Gemm g, const Sched& S, const Epi& E) {
;     ...
;         for (int t = 0; t < nt; t += 2) {
;             const bool last = (t == nt - 2);
;     ...
;             PG8_LDB(B0, 1, 0); PG8_LDB(B1, 1, 1); PG8_SCHED; PG8_LDA(At, 1, 0); PG8_STAGE(PG8_SA(0, 1), a2 + hstep, voffA);
;             PG8_WAIT_V(8); PG8_WAIT_L(0); PG8_BAR; PG8_MMA(0, 0, At, B0); PG8_MMA(0, 1, At, B1); PG8_BAR; PG8_SCHED;
;             PG8_LDA(At, 1, 1); PG8_STAGE(PG8_SB(1, 0), b3, voffB); PG8_STAGE(PG8_SB(1, 1), b3 + hstep, voffB); PG8_STAGE(PG8_SA(1, 0), a3, voffA);
;             PG8_WAIT_V(8); PG8_WAIT_L(0); PG8_BAR; PG8_MMA(1, 0, At, B0); PG8_MMA(1, 1, At, B1); PG8_BAR; PG8_SCHED;
	s_add_i32 s33, 0, 0x18000
	s_add_i32 s42, 0, 0x1c000
	ds_read_b128 v[160:163], v241 offset:32768
	ds_read_b128 v[166:169], v241 offset:33792
	ds_read_b128 v[170:173], v241 offset:34816
	ds_read_b128 v[174:177], v241 offset:35840
	ds_read_b128 v[178:181], v241 offset:49152
	ds_read_b128 v[182:185], v241 offset:50176
	ds_read_b128 v[186:189], v241 offset:51200
	ds_read_b128 v[190:193], v241 offset:52224
	s_add_u32 s26, s26, 0x100000
	s_addc_u32 s27, s27, 0
	s_mov_b32 m0, s35
	ds_read_b128 v[194:197], v155 offset:32768
	ds_read_b128 v[198:201], v155 offset:33792
	ds_read_b128 v[202:205], v155 offset:34816
	ds_read_b128 v[206:209], v155 offset:35840
	ds_read_b128 v[210:213], v155 offset:36864
	ds_read_b128 v[214:217], v155 offset:37888
	ds_read_b128 v[218:221], v155 offset:38912
	ds_read_b128 v[222:225], v155 offset:39936
	global_load_lds_dwordx4 v130, s[26:27]
	s_mov_b32 m0, s36
	s_nop 0
	global_load_lds_dwordx4 v134, s[26:27]
	s_waitcnt vmcnt(8)
	s_waitcnt lgkmcnt(0)
	s_barrier
	s_waitcnt lgkmcnt(0)
	v_mfma_f32_16x16x32_bf16 v[122:125], v[160:163], v[194:197], v[122:125]
	v_mfma_f32_16x16x32_bf16 v[114:117], v[170:173], v[194:197], v[114:117]
	v_mfma_f32_16x16x32_bf16 v[106:109], v[160:163], v[202:205], v[106:109]
	v_mfma_f32_16x16x32_bf16 v[98:101], v[170:173], v[202:205], v[98:101]
	v_mfma_f32_16x16x32_bf16 v[90:93], v[160:163], v[210:213], v[90:93]
	v_mfma_f32_16x16x32_bf16 v[82:85], v[170:173], v[210:213], v[82:85]
	v_mfma_f32_16x16x32_bf16 v[74:77], v[160:163], v[218:221], v[74:77]
	v_mfma_f32_16x16x32_bf16 v[62:65], v[170:173], v[218:221], v[62:65]
	v_mfma_f32_16x16x32_bf16 v[122:125], v[166:169], v[198:201], v[122:125]
	v_mfma_f32_16x16x32_bf16 v[114:117], v[174:177], v[198:201], v[114:117]
	v_mfma_f32_16x16x32_bf16 v[106:109], v[166:169], v[206:209], v[106:109]
	v_mfma_f32_16x16x32_bf16 v[98:101], v[174:177], v[206:209], v[98:101]
	v_mfma_f32_16x16x32_bf16 v[90:93], v[166:169], v[214:217], v[90:93]
	v_mfma_f32_16x16x32_bf16 v[82:85], v[174:177], v[214:217], v[82:85]
	v_mfma_f32_16x16x32_bf16 v[74:77], v[166:169], v[222:225], v[74:77]
	v_mfma_f32_16x16x32_bf16 v[62:65], v[174:177], v[222:225], v[62:65]
	v_mfma_f32_16x16x32_bf16 v[126:129], v[178:181], v[194:197], v[126:129]
	v_mfma_f32_16x16x32_bf16 v[118:121], v[186:189], v[194:197], v[118:121]
	v_mfma_f32_16x16x32_bf16 v[110:113], v[178:181], v[202:205], v[110:113]
	v_mfma_f32_16x16x32_bf16 v[102:105], v[186:189], v[202:205], v[102:105]
	v_mfma_f32_16x16x32_bf16 v[94:97], v[178:181], v[210:213], v[94:97]
	v_mfma_f32_16x16x32_bf16 v[86:89], v[186:189], v[210:213], v[86:89]
	v_mfma_f32_16x16x32_bf16 v[78:81], v[178:181], v[218:221], v[78:81]
	v_mfma_f32_16x16x32_bf16 v[70:73], v[186:189], v[218:221], v[70:73]
	v_mfma_f32_16x16x32_bf16 v[126:129], v[182:185], v[198:201], v[126:129]
	v_mfma_f32_16x16x32_bf16 v[118:121], v[190:193], v[198:201], v[118:121]
	v_mfma_f32_16x16x32_bf16 v[110:113], v[182:185], v[206:209], v[110:113]
	v_mfma_f32_16x16x32_bf16 v[102:105], v[190:193], v[206:209], v[102:105]
	v_mfma_f32_16x16x32_bf16 v[94:97], v[182:185], v[214:217], v[94:97]
	v_mfma_f32_16x16x32_bf16 v[86:89], v[190:193], v[214:217], v[86:89]
	v_mfma_f32_16x16x32_bf16 v[78:81], v[182:185], v[222:225], v[78:81]
	v_mfma_f32_16x16x32_bf16 v[70:73], v[190:193], v[222:225], v[70:73]
	s_barrier
	s_add_i32 s26, s33, s29
	s_add_i32 m0, s26, 0xffffff80
	ds_read_b128 v[194:197], v155 offset:49152
	ds_read_b128 v[198:201], v155 offset:50176
	ds_read_b128 v[202:205], v155 offset:51200
	ds_read_b128 v[206:209], v155 offset:52224
	ds_read_b128 v[210:213], v155 offset:53248
	ds_read_b128 v[214:217], v155 offset:54272
	ds_read_b128 v[218:221], v155 offset:55296
	ds_read_b128 v[222:225], v155 offset:56320
	global_load_lds_dwordx4 v132, s[22:23] offset:128
	s_add_i32 m0, s26, 0x1f80
	s_add_i32 s26, s42, s29
	global_load_lds_dwordx4 v136, s[22:23] offset:128
	s_add_u32 s22, s22, 0x100080
	s_addc_u32 s23, s23, 0
	s_mov_b32 m0, s26
	s_nop 0
	global_load_lds_dwordx4 v132, s[22:23]
	s_add_i32 m0, s26, 0x2000
	s_nop 0
	global_load_lds_dwordx4 v136, s[22:23]
	s_mov_b32 m0, s41
	s_nop 0
	global_load_lds_dwordx4 v130, s[100:101]
	s_mov_b32 m0, s43
	s_nop 0
	global_load_lds_dwordx4 v134, s[100:101]
	s_waitcnt vmcnt(8)
	s_waitcnt lgkmcnt(0)
	s_barrier
	s_waitcnt lgkmcnt(0)
	v_mfma_f32_16x16x32_bf16 v[58:61], v[160:163], v[194:197], v[58:61]
	v_mfma_f32_16x16x32_bf16 v[50:53], v[170:173], v[194:197], v[50:53]
	v_mfma_f32_16x16x32_bf16 v[42:45], v[160:163], v[202:205], v[42:45]
	v_mfma_f32_16x16x32_bf16 v[34:37], v[170:173], v[202:205], v[34:37]
	v_mfma_f32_16x16x32_bf16 v[26:29], v[160:163], v[210:213], v[26:29]
	v_mfma_f32_16x16x32_bf16 v[18:21], v[170:173], v[210:213], v[18:21]
	v_mfma_f32_16x16x32_bf16 v[10:13], v[160:163], v[218:221], v[10:13]
	v_mfma_f32_16x16x32_bf16 v[2:5], v[170:173], v[218:221], v[2:5]
	v_mfma_f32_16x16x32_bf16 v[58:61], v[166:169], v[198:201], v[58:61]
	v_mfma_f32_16x16x32_bf16 v[50:53], v[174:177], v[198:201], v[50:53]
	v_mfma_f32_16x16x32_bf16 v[42:45], v[166:169], v[206:209], v[42:45]
	v_mfma_f32_16x16x32_bf16 v[34:37], v[174:177], v[206:209], v[34:37]
	v_mfma_f32_16x16x32_bf16 v[26:29], v[166:169], v[214:217], v[26:29]
	v_mfma_f32_16x16x32_bf16 v[18:21], v[174:177], v[214:217], v[18:21]
	v_mfma_f32_16x16x32_bf16 v[10:13], v[166:169], v[222:225], v[10:13]
	v_mfma_f32_16x16x32_bf16 v[2:5], v[174:177], v[222:225], v[2:5]
	v_mfma_f32_16x16x32_bf16 v[66:69], v[178:181], v[194:197], v[66:69]
	v_mfma_f32_16x16x32_bf16 v[54:57], v[186:189], v[194:197], v[54:57]
	v_mfma_f32_16x16x32_bf16 v[46:49], v[178:181], v[202:205], v[46:49]
	v_mfma_f32_16x16x32_bf16 v[38:41], v[186:189], v[202:205], v[38:41]
	v_mfma_f32_16x16x32_bf16 v[30:33], v[178:181], v[210:213], v[30:33]
	v_mfma_f32_16x16x32_bf16 v[22:25], v[186:189], v[210:213], v[22:25]
	v_mfma_f32_16x16x32_bf16 v[14:17], v[178:181], v[218:221], v[14:17]
	v_mfma_f32_16x16x32_bf16 v[6:9], v[186:189], v[218:221], v[6:9]
	v_mfma_f32_16x16x32_bf16 v[66:69], v[182:185], v[198:201], v[66:69]
	v_mfma_f32_16x16x32_bf16 v[54:57], v[190:193], v[198:201], v[54:57]
	v_mfma_f32_16x16x32_bf16 v[46:49], v[182:185], v[206:209], v[46:49]
	v_mfma_f32_16x16x32_bf16 v[38:41], v[190:193], v[206:209], v[38:41]
	v_mfma_f32_16x16x32_bf16 v[30:33], v[182:185], v[214:217], v[30:33]
	v_mfma_f32_16x16x32_bf16 v[22:25], v[190:193], v[214:217], v[22:25]
	v_mfma_f32_16x16x32_bf16 v[14:17], v[182:185], v[222:225], v[14:17]
	v_mfma_f32_16x16x32_bf16 v[6:9], v[190:193], v[222:225], v[6:9]
	s_barrier
	s_add_i32 s52, s52, 2
	s_add_u32 s24, s24, 0x100
	s_addc_u32 s25, s25, 0
	s_add_u32 s50, s50, 0x100
	s_addc_u32 s51, s51, 0
	s_cmp_gt_u32 s52, 61
	s_cbranch_scc0 .LBB0_1681


; #define PG8_BAR __builtin_amdgcn_s_barrier()
; template <class Epi, class Sched, bool ALIGN_EPI = false, bool SP2 = false>
; __device__ __forceinline__ void gemm_phase(PG8_LAS unsigned char* lds, const Gemm g, const Sched& S, const Epi& E) {
;     ...
;         if constexpr (ALIGN_EPI) { if (wr == 0) PG8_BAR; }
;         if constexpr (!Epi::AFTER_DRAIN) { E(acc, cur, wr, wc, fr, fq); S.done(cur); }
;         if (!has_next) break;
	s_and_b64 vcc, exec, s[8:9]
	s_cbranch_vccz .LBB0_1684
	s_barrier

; #define PG8_STAGE(bufoff, gbase, voff) do { _Pragma("unroll") for (int _i = 0; _i < 2; ++_i) \
;         __builtin_amdgcn_global_load_lds((const unsigned*)((const char*)(gbase) + (voff)[_i]), (PG8_LAS unsigned*)(lds + (bufoff) + ldsw + _i * 8192), 16, 0, 0); } while (0)
; #define PG8_LDA(dst, b, h) do { _Pragma("unroll") for (int m = 0; m < 4; ++m) _Pragma("unroll") for (int k = 0; k < 2; ++k) dst[m][k] = *(const PG8_LAS bf16x8*)(lds + PG8_SA(b, h) + aoff + m * 2048 + k * 1024); } while (0)
; #define PG8_LDB(dst, b, h) do { _Pragma("unroll") for (int n = 0; n < 2; ++n) _Pragma("unroll") for (int k = 0; k < 2; ++k) dst[n][k] = *(const PG8_LAS bf16x8*)(lds + PG8_SB(b, h) + boff + n * 2048 + k * 1024); } while (0)
; #define PG8_MMA(ai, bj, At, Bt) do { __builtin_amdgcn_s_setprio(1); _Pragma("unroll") for (int m = 0; m < 4; ++m) _Pragma("unroll") for (int n = 0; n < 2; ++n) _Pragma("unroll") for (int k = 0; k < 2; ++k) \
;         acc[ai][bj][m][n] = __builtin_amdgcn_mfma_f32_16x16x32_bf16(Bt[n][k], At[m][k], acc[ai][bj][m][n], 0, 0, 0); __builtin_amdgcn_s_setprio(0); } while (0)
; #define PG8_WAIT_V(n) asm volatile("s_waitcnt vmcnt(" #n ")" ::: "memory")
; #define PG8_WAIT_L(n) asm volatile("s_waitcnt lgkmcnt(" #n ")" ::: "memory")
; template <class Epi, class Sched, bool ALIGN_EPI = false, bool SP2 = false>
; __device__ __forceinline__ void gemm_phase(PG8_LAS unsigned char* lds, const Gemm g, const Sched& S, const Epi& E) {
;     ...
;             const bool last = (t == nt - 2);
;             const char* a1 = cA + (size_t)(t + 1) * kstep;
;             const char* a2 = last ? nA : cA + (size_t)(t + 2) * kstep; const char* b2 = last ? nB : cB + (size_t)(t + 2) * kstep;
;             const char* a3 = a2 + kstep; const char* b3 = b2 + kstep;
;             if (last && has_next) S.a_ready(nxt);
;             if constexpr (SP2) {
;             PG8_LDB(B0, 0, 0); PG8_LDB(B1, 0, 1); PG8_SCHED; PG8_LDA(At, 0, 0); PG8_STAGE(PG8_SA(1, 1), a1 + hstep, voffA);
;             PG8_WAIT_V(8); PG8_WAIT_L(0); PG8_BAR; PG8_MMA(0, 0, At, B0); PG8_MMA(0, 1, At, B1); PG8_BAR; PG8_SCHED;
;             PG8_LDA(At, 0, 1); PG8_STAGE(PG8_SB(0, 0), b2, voffB); PG8_STAGE(PG8_SB(0, 1), b2 + hstep, voffB); PG8_STAGE(PG8_SA(0, 0), a2, voffA);
;             PG8_WAIT_V(8); PG8_WAIT_L(0); PG8_BAR; PG8_MMA(1, 0, At, B0); PG8_MMA(1, 1, At, B1); PG8_BAR; PG8_SCHED;
.LBB0_1801:
	ds_read_b128 v[130:133], v241 offset:0
	ds_read_b128 v[134:137], v241 offset:1024
	ds_read_b128 v[138:141], v241 offset:2048
	ds_read_b128 v[142:145], v241 offset:3072
	ds_read_b128 v[146:149], v241 offset:16384
	ds_read_b128 v[150:153], v241 offset:17408
	ds_read_b128 v[170:173], v241 offset:18432
	ds_read_b128 v[174:177], v241 offset:19456
	s_add_u32 s16, s18, 0xffd50080
	s_addc_u32 s17, s19, -1
	s_cmpk_eq_i32 s48, 0xa8
	s_cselect_b32 s21, s5, s17
	s_cselect_b32 s20, s4, s16
	s_cselect_b32 s17, s15, s47
	s_cselect_b32 s16, s14, s46
	s_add_i32 m0, s25, 0xc000
	ds_read_b128 v[178:181], v184
	ds_read_b128 v[186:189], v184 offset:1024
	ds_read_b128 v[190:193], v184 offset:2048
	ds_read_b128 v[194:197], v184 offset:3072
	ds_read_b128 v[198:201], v184 offset:4096
	ds_read_b128 v[202:205], v184 offset:5120
	ds_read_b128 v[206:209], v184 offset:6144
	ds_read_b128 v[210:213], v184 offset:7168
	global_load_lds_dwordx4 v0, s[18:19]
	s_add_i32 m0, s25, 0xe000
	s_nop 0
	global_load_lds_dwordx4 v162, s[18:19]
	s_waitcnt vmcnt(8)
	s_waitcnt lgkmcnt(0)
	s_barrier
	s_waitcnt lgkmcnt(0)
	v_mfma_f32_16x16x32_bf16 v[114:117], v[130:133], v[178:181], v[114:117]
	v_mfma_f32_16x16x32_bf16 v[118:121], v[138:141], v[178:181], v[118:121]
	v_mfma_f32_16x16x32_bf16 v[106:109], v[130:133], v[190:193], v[106:109]
	v_mfma_f32_16x16x32_bf16 v[98:101], v[138:141], v[190:193], v[98:101]
	v_mfma_f32_16x16x32_bf16 v[90:93], v[130:133], v[198:201], v[90:93]
	v_mfma_f32_16x16x32_bf16 v[82:85], v[138:141], v[198:201], v[82:85]
	v_mfma_f32_16x16x32_bf16 v[74:77], v[130:133], v[206:209], v[74:77]
	v_mfma_f32_16x16x32_bf16 v[66:69], v[138:141], v[206:209], v[66:69]
	v_mfma_f32_16x16x32_bf16 v[114:117], v[134:137], v[186:189], v[114:117]
	v_mfma_f32_16x16x32_bf16 v[118:121], v[142:145], v[186:189], v[118:121]
	v_mfma_f32_16x16x32_bf16 v[106:109], v[134:137], v[194:197], v[106:109]
	v_mfma_f32_16x16x32_bf16 v[98:101], v[142:145], v[194:197], v[98:101]
	v_mfma_f32_16x16x32_bf16 v[90:93], v[134:137], v[202:205], v[90:93]
	v_mfma_f32_16x16x32_bf16 v[82:85], v[142:145], v[202:205], v[82:85]
	v_mfma_f32_16x16x32_bf16 v[74:77], v[134:137], v[210:213], v[74:77]
	v_mfma_f32_16x16x32_bf16 v[66:69], v[142:145], v[210:213], v[66:69]
	v_mfma_f32_16x16x32_bf16 v[122:125], v[146:149], v[178:181], v[122:125]
	v_mfma_f32_16x16x32_bf16 v[126:129], v[170:173], v[178:181], v[126:129]
	v_mfma_f32_16x16x32_bf16 v[110:113], v[146:149], v[190:193], v[110:113]
	v_mfma_f32_16x16x32_bf16 v[102:105], v[170:173], v[190:193], v[102:105]
	v_mfma_f32_16x16x32_bf16 v[94:97], v[146:149], v[198:201], v[94:97]
	v_mfma_f32_16x16x32_bf16 v[86:89], v[170:173], v[198:201], v[86:89]
	v_mfma_f32_16x16x32_bf16 v[78:81], v[146:149], v[206:209], v[78:81]
	v_mfma_f32_16x16x32_bf16 v[70:73], v[170:173], v[206:209], v[70:73]
	v_mfma_f32_16x16x32_bf16 v[122:125], v[150:153], v[186:189], v[122:125]
	v_mfma_f32_16x16x32_bf16 v[126:129], v[174:177], v[186:189], v[126:129]
	v_mfma_f32_16x16x32_bf16 v[110:113], v[150:153], v[194:197], v[110:113]
	v_mfma_f32_16x16x32_bf16 v[102:105], v[174:177], v[194:197], v[102:105]
	v_mfma_f32_16x16x32_bf16 v[94:97], v[150:153], v[202:205], v[94:97]
	v_mfma_f32_16x16x32_bf16 v[86:89], v[174:177], v[202:205], v[86:89]
	v_mfma_f32_16x16x32_bf16 v[78:81], v[150:153], v[210:213], v[78:81]
	v_mfma_f32_16x16x32_bf16 v[70:73], v[174:177], v[210:213], v[70:73]
	s_barrier
	s_add_i32 s33, s36, s24
	s_mov_b32 m0, s33
	ds_read_b128 v[178:181], v184 offset:16384
	ds_read_b128 v[186:189], v184 offset:17408
	ds_read_b128 v[190:193], v184 offset:18432
	ds_read_b128 v[194:197], v184 offset:19456
	ds_read_b128 v[198:201], v184 offset:20480
	ds_read_b128 v[202:205], v184 offset:21504
	ds_read_b128 v[206:209], v184 offset:22528
	ds_read_b128 v[210:213], v184 offset:23552
	global_load_lds_dwordx4 v156, s[16:17]
	s_add_i32 m0, s33, 0x2000
	s_add_u32 s50, s16, 0x2b0000
	s_addc_u32 s51, s17, 0
	s_add_i32 s33, s37, s24
	global_load_lds_dwordx4 v160, s[16:17]
	s_mov_b32 m0, s33
	s_add_u32 s100, s20, 0x80
	s_addc_u32 s101, s21, 0
	global_load_lds_dwordx4 v156, s[50:51]
	s_add_i32 m0, s33, 0x2000
	s_nop 0
	global_load_lds_dwordx4 v160, s[50:51]
	s_mov_b32 m0, s25
	s_nop 0
	global_load_lds_dwordx4 v154, s[20:21]
	s_mov_b32 m0, s26
	s_nop 0
	global_load_lds_dwordx4 v158, s[20:21]
	s_waitcnt vmcnt(8)
	s_waitcnt lgkmcnt(0)
	s_barrier
	s_waitcnt lgkmcnt(0)
	v_mfma_f32_16x16x32_bf16 v[58:61], v[130:133], v[178:181], v[58:61]
	v_mfma_f32_16x16x32_bf16 v[54:57], v[138:141], v[178:181], v[54:57]
	v_mfma_f32_16x16x32_bf16 v[42:45], v[130:133], v[190:193], v[42:45]
	v_mfma_f32_16x16x32_bf16 v[34:37], v[138:141], v[190:193], v[34:37]
	v_mfma_f32_16x16x32_bf16 v[26:29], v[130:133], v[198:201], v[26:29]
	v_mfma_f32_16x16x32_bf16 v[18:21], v[138:141], v[198:201], v[18:21]
	v_mfma_f32_16x16x32_bf16 v[6:9], v[130:133], v[206:209], v[6:9]
	v_mfma_f32_16x16x32_bf16 v[2:5], v[138:141], v[206:209], v[2:5]
	v_mfma_f32_16x16x32_bf16 v[58:61], v[134:137], v[186:189], v[58:61]
	v_mfma_f32_16x16x32_bf16 v[54:57], v[142:145], v[186:189], v[54:57]
	v_mfma_f32_16x16x32_bf16 v[42:45], v[134:137], v[194:197], v[42:45]
	v_mfma_f32_16x16x32_bf16 v[34:37], v[142:145], v[194:197], v[34:37]
	v_mfma_f32_16x16x32_bf16 v[26:29], v[134:137], v[202:205], v[26:29]
	v_mfma_f32_16x16x32_bf16 v[18:21], v[142:145], v[202:205], v[18:21]
	v_mfma_f32_16x16x32_bf16 v[6:9], v[134:137], v[210:213], v[6:9]
	v_mfma_f32_16x16x32_bf16 v[2:5], v[142:145], v[210:213], v[2:5]
	v_mfma_f32_16x16x32_bf16 v[62:65], v[146:149], v[178:181], v[62:65]
	v_mfma_f32_16x16x32_bf16 v[50:53], v[170:173], v[178:181], v[50:53]
	v_mfma_f32_16x16x32_bf16 v[46:49], v[146:149], v[190:193], v[46:49]
	v_mfma_f32_16x16x32_bf16 v[38:41], v[170:173], v[190:193], v[38:41]
	v_mfma_f32_16x16x32_bf16 v[30:33], v[146:149], v[198:201], v[30:33]
	v_mfma_f32_16x16x32_bf16 v[22:25], v[170:173], v[198:201], v[22:25]
	v_mfma_f32_16x16x32_bf16 v[10:13], v[146:149], v[206:209], v[10:13]
	v_mfma_f32_16x16x32_bf16 v[14:17], v[170:173], v[206:209], v[14:17]
	v_mfma_f32_16x16x32_bf16 v[62:65], v[150:153], v[186:189], v[62:65]
	v_mfma_f32_16x16x32_bf16 v[50:53], v[174:177], v[186:189], v[50:53]
	v_mfma_f32_16x16x32_bf16 v[46:49], v[150:153], v[194:197], v[46:49]
	v_mfma_f32_16x16x32_bf16 v[38:41], v[174:177], v[194:197], v[38:41]
	v_mfma_f32_16x16x32_bf16 v[30:33], v[150:153], v[202:205], v[30:33]
	v_mfma_f32_16x16x32_bf16 v[22:25], v[174:177], v[202:205], v[22:25]
	v_mfma_f32_16x16x32_bf16 v[10:13], v[150:153], v[210:213], v[10:13]
	v_mfma_f32_16x16x32_bf16 v[14:17], v[174:177], v[210:213], v[14:17]
	s_barrier
; #define PG8_STAGE(bufoff, gbase, voff) do { _Pragma("unroll") for (int _i = 0; _i < 2; ++_i) \
;         __builtin_amdgcn_global_load_lds((const unsigned*)((const char*)(gbase) + (voff)[_i]), (PG8_LAS unsigned*)(lds + (bufoff) + ldsw + _i * 8192), 16, 0, 0); } while (0)
; #define PG8_LDA(dst, b, h) do { _Pragma("unroll") for (int m = 0; m < 4; ++m) _Pragma("unroll") for (int k = 0; k < 2; ++k) dst[m][k] = *(const PG8_LAS bf16x8*)(lds + PG8_SA(b, h) + aoff + m * 2048 + k * 1024); } while (0)
; #define PG8_LDB(dst, b, h) do { _Pragma("unroll") for (int n = 0; n < 2; ++n) _Pragma("unroll") for (int k = 0; k < 2; ++k) dst[n][k] = *(const PG8_LAS bf16x8*)(lds + PG8_SB(b, h) + boff + n * 2048 + k * 1024); } while (0)
; #define PG8_MMA(ai, bj, At, Bt) do { __builtin_amdgcn_s_setprio(1); _Pragma("unroll") for (int m = 0; m < 4; ++m) _Pragma("unroll") for (int n = 0; n < 2; ++n) _Pragma("unroll") for (int k = 0; k < 2; ++k) \
;         acc[ai][bj][m][n] = __builtin_amdgcn_mfma_f32_16x16x32_bf16(Bt[n][k], At[m][k], acc[ai][bj][m][n], 0, 0, 0); __builtin_amdgcn_s_setprio(0); } while (0)
; #define PG8_WAIT_V(n) asm volatile("s_waitcnt vmcnt(" #n ")" ::: "memory")
; #define PG8_WAIT_L(n) asm volatile("s_waitcnt lgkmcnt(" #n ")" ::: "memory")
; #define PG8_BAR __builtin_amdgcn_s_barrier()
; #define PG8_SCHED __builtin_amdgcn_sched_barrier(0)
; template <class Epi, class Sched, bool ALIGN_EPI = false, bool SP2 = false>
; __device__ __forceinline__ void gemm_phase(PG8_LAS unsigned char* lds, const Gemm g, const Sched& S, const Epi& E) {
;     ...
;         for (int t = 0; t < nt; t += 2) {
;             const bool last = (t == nt - 2);
;     ...
;             PG8_LDB(B0, 1, 0); PG8_LDB(B1, 1, 1); PG8_SCHED; PG8_LDA(At, 1, 0); PG8_STAGE(PG8_SA(0, 1), a2 + hstep, voffA);
;             PG8_WAIT_V(8); PG8_WAIT_L(0); PG8_BAR; PG8_MMA(0, 0, At, B0); PG8_MMA(0, 1, At, B1); PG8_BAR; PG8_SCHED;
;             PG8_LDA(At, 1, 1); PG8_STAGE(PG8_SB(1, 0), b3, voffB); PG8_STAGE(PG8_SB(1, 1), b3 + hstep, voffB); PG8_STAGE(PG8_SA(1, 0), a3, voffA);
;             PG8_WAIT_V(8); PG8_WAIT_L(0); PG8_BAR; PG8_MMA(1, 0, At, B0); PG8_MMA(1, 1, At, B1); PG8_BAR; PG8_SCHED;
	s_add_i32 s33, 0, 0x18000
	s_add_i32 s42, 0, 0x1c000
	ds_read_b128 v[130:133], v241 offset:32768
	ds_read_b128 v[134:137], v241 offset:33792
	ds_read_b128 v[138:141], v241 offset:34816
	ds_read_b128 v[142:145], v241 offset:35840
	ds_read_b128 v[146:149], v241 offset:49152
	ds_read_b128 v[150:153], v241 offset:50176
	ds_read_b128 v[170:173], v241 offset:51200
	ds_read_b128 v[174:177], v241 offset:52224
	s_add_u32 s20, s20, 0x2b0000
	s_addc_u32 s21, s21, 0
	s_mov_b32 m0, s27
	ds_read_b128 v[178:181], v184 offset:32768
	ds_read_b128 v[186:189], v184 offset:33792
	ds_read_b128 v[190:193], v184 offset:34816
	ds_read_b128 v[194:197], v184 offset:35840
	ds_read_b128 v[198:201], v184 offset:36864
	ds_read_b128 v[202:205], v184 offset:37888
	ds_read_b128 v[206:209], v184 offset:38912
	ds_read_b128 v[210:213], v184 offset:39936
	global_load_lds_dwordx4 v154, s[20:21]
	s_mov_b32 m0, s28
	s_nop 0
	global_load_lds_dwordx4 v158, s[20:21]
	s_waitcnt vmcnt(8)
	s_waitcnt lgkmcnt(0)
	s_barrier
	s_waitcnt lgkmcnt(0)
	v_mfma_f32_16x16x32_bf16 v[114:117], v[130:133], v[178:181], v[114:117]
	v_mfma_f32_16x16x32_bf16 v[118:121], v[138:141], v[178:181], v[118:121]
	v_mfma_f32_16x16x32_bf16 v[106:109], v[130:133], v[190:193], v[106:109]
	v_mfma_f32_16x16x32_bf16 v[98:101], v[138:141], v[190:193], v[98:101]
	v_mfma_f32_16x16x32_bf16 v[90:93], v[130:133], v[198:201], v[90:93]
	v_mfma_f32_16x16x32_bf16 v[82:85], v[138:141], v[198:201], v[82:85]
	v_mfma_f32_16x16x32_bf16 v[74:77], v[130:133], v[206:209], v[74:77]
	v_mfma_f32_16x16x32_bf16 v[66:69], v[138:141], v[206:209], v[66:69]
	v_mfma_f32_16x16x32_bf16 v[114:117], v[134:137], v[186:189], v[114:117]
	v_mfma_f32_16x16x32_bf16 v[118:121], v[142:145], v[186:189], v[118:121]
	v_mfma_f32_16x16x32_bf16 v[106:109], v[134:137], v[194:197], v[106:109]
	v_mfma_f32_16x16x32_bf16 v[98:101], v[142:145], v[194:197], v[98:101]
	v_mfma_f32_16x16x32_bf16 v[90:93], v[134:137], v[202:205], v[90:93]
	v_mfma_f32_16x16x32_bf16 v[82:85], v[142:145], v[202:205], v[82:85]
	v_mfma_f32_16x16x32_bf16 v[74:77], v[134:137], v[210:213], v[74:77]
	v_mfma_f32_16x16x32_bf16 v[66:69], v[142:145], v[210:213], v[66:69]
	v_mfma_f32_16x16x32_bf16 v[122:125], v[146:149], v[178:181], v[122:125]
	v_mfma_f32_16x16x32_bf16 v[126:129], v[170:173], v[178:181], v[126:129]
	v_mfma_f32_16x16x32_bf16 v[110:113], v[146:149], v[190:193], v[110:113]
	v_mfma_f32_16x16x32_bf16 v[102:105], v[170:173], v[190:193], v[102:105]
	v_mfma_f32_16x16x32_bf16 v[94:97], v[146:149], v[198:201], v[94:97]
	v_mfma_f32_16x16x32_bf16 v[86:89], v[170:173], v[198:201], v[86:89]
	v_mfma_f32_16x16x32_bf16 v[78:81], v[146:149], v[206:209], v[78:81]
	v_mfma_f32_16x16x32_bf16 v[70:73], v[170:173], v[206:209], v[70:73]
	v_mfma_f32_16x16x32_bf16 v[122:125], v[150:153], v[186:189], v[122:125]
	v_mfma_f32_16x16x32_bf16 v[126:129], v[174:177], v[186:189], v[126:129]
	v_mfma_f32_16x16x32_bf16 v[110:113], v[150:153], v[194:197], v[110:113]
	v_mfma_f32_16x16x32_bf16 v[102:105], v[174:177], v[194:197], v[102:105]
	v_mfma_f32_16x16x32_bf16 v[94:97], v[150:153], v[202:205], v[94:97]
	v_mfma_f32_16x16x32_bf16 v[86:89], v[174:177], v[202:205], v[86:89]
	v_mfma_f32_16x16x32_bf16 v[78:81], v[150:153], v[210:213], v[78:81]
	v_mfma_f32_16x16x32_bf16 v[70:73], v[174:177], v[210:213], v[70:73]
	s_barrier
	s_add_i32 s20, s33, s24
	s_add_i32 m0, s20, 0xffffff80
	ds_read_b128 v[178:181], v184 offset:49152
	ds_read_b128 v[186:189], v184 offset:50176
	ds_read_b128 v[190:193], v184 offset:51200
	ds_read_b128 v[194:197], v184 offset:52224
	ds_read_b128 v[198:201], v184 offset:53248
	ds_read_b128 v[202:205], v184 offset:54272
	ds_read_b128 v[206:209], v184 offset:55296
	ds_read_b128 v[210:213], v184 offset:56320
	global_load_lds_dwordx4 v156, s[16:17] offset:128
	s_add_i32 m0, s20, 0x1f80
	s_add_i32 s20, s42, s24
	global_load_lds_dwordx4 v160, s[16:17] offset:128
	s_add_u32 s16, s16, 0x2b0080
	s_addc_u32 s17, s17, 0
	s_mov_b32 m0, s20
	s_nop 0
	global_load_lds_dwordx4 v156, s[16:17]
	s_add_i32 m0, s20, 0x2000
	s_nop 0
	global_load_lds_dwordx4 v160, s[16:17]
	s_mov_b32 m0, s30
	s_nop 0
	global_load_lds_dwordx4 v154, s[100:101]
	s_mov_b32 m0, s31
	s_nop 0
	global_load_lds_dwordx4 v158, s[100:101]
	s_waitcnt vmcnt(8)
	s_waitcnt lgkmcnt(0)
	s_barrier
	s_waitcnt lgkmcnt(0)
	v_mfma_f32_16x16x32_bf16 v[58:61], v[130:133], v[178:181], v[58:61]
	v_mfma_f32_16x16x32_bf16 v[54:57], v[138:141], v[178:181], v[54:57]
	v_mfma_f32_16x16x32_bf16 v[42:45], v[130:133], v[190:193], v[42:45]
	v_mfma_f32_16x16x32_bf16 v[34:37], v[138:141], v[190:193], v[34:37]
	v_mfma_f32_16x16x32_bf16 v[26:29], v[130:133], v[198:201], v[26:29]
	v_mfma_f32_16x16x32_bf16 v[18:21], v[138:141], v[198:201], v[18:21]
	v_mfma_f32_16x16x32_bf16 v[6:9], v[130:133], v[206:209], v[6:9]
	v_mfma_f32_16x16x32_bf16 v[2:5], v[138:141], v[206:209], v[2:5]
	v_mfma_f32_16x16x32_bf16 v[58:61], v[134:137], v[186:189], v[58:61]
	v_mfma_f32_16x16x32_bf16 v[54:57], v[142:145], v[186:189], v[54:57]
	v_mfma_f32_16x16x32_bf16 v[42:45], v[134:137], v[194:197], v[42:45]
	v_mfma_f32_16x16x32_bf16 v[34:37], v[142:145], v[194:197], v[34:37]
	v_mfma_f32_16x16x32_bf16 v[26:29], v[134:137], v[202:205], v[26:29]
	v_mfma_f32_16x16x32_bf16 v[18:21], v[142:145], v[202:205], v[18:21]
	v_mfma_f32_16x16x32_bf16 v[6:9], v[134:137], v[210:213], v[6:9]
	v_mfma_f32_16x16x32_bf16 v[2:5], v[142:145], v[210:213], v[2:5]
	v_mfma_f32_16x16x32_bf16 v[62:65], v[146:149], v[178:181], v[62:65]
	v_mfma_f32_16x16x32_bf16 v[50:53], v[170:173], v[178:181], v[50:53]
	v_mfma_f32_16x16x32_bf16 v[46:49], v[146:149], v[190:193], v[46:49]
	v_mfma_f32_16x16x32_bf16 v[38:41], v[170:173], v[190:193], v[38:41]
	v_mfma_f32_16x16x32_bf16 v[30:33], v[146:149], v[198:201], v[30:33]
	v_mfma_f32_16x16x32_bf16 v[22:25], v[170:173], v[198:201], v[22:25]
	v_mfma_f32_16x16x32_bf16 v[10:13], v[146:149], v[206:209], v[10:13]
	v_mfma_f32_16x16x32_bf16 v[14:17], v[170:173], v[206:209], v[14:17]
	v_mfma_f32_16x16x32_bf16 v[62:65], v[150:153], v[186:189], v[62:65]
	v_mfma_f32_16x16x32_bf16 v[50:53], v[174:177], v[186:189], v[50:53]
	v_mfma_f32_16x16x32_bf16 v[46:49], v[150:153], v[194:197], v[46:49]
	v_mfma_f32_16x16x32_bf16 v[38:41], v[174:177], v[194:197], v[38:41]
	v_mfma_f32_16x16x32_bf16 v[30:33], v[150:153], v[202:205], v[30:33]
	v_mfma_f32_16x16x32_bf16 v[22:25], v[174:177], v[202:205], v[22:25]
	v_mfma_f32_16x16x32_bf16 v[10:13], v[150:153], v[210:213], v[10:13]
	v_mfma_f32_16x16x32_bf16 v[14:17], v[174:177], v[210:213], v[14:17]
	s_barrier
	s_add_i32 s48, s48, 2
	s_add_u32 s18, s18, 0x100
	s_addc_u32 s19, s19, 0
	s_add_u32 s46, s46, 0x100
	s_addc_u32 s47, s47, 0
	s_cmpk_gt_u32 s48, 0xa9
	s_cbranch_scc0 .LBB0_1801


; #define PG8_BAR __builtin_amdgcn_s_barrier()
; template <class Epi, class Sched, bool ALIGN_EPI = false, bool SP2 = false>
; __device__ __forceinline__ void gemm_phase(PG8_LAS unsigned char* lds, const Gemm g, const Sched& S, const Epi& E) {
;     ...
;         if constexpr (ALIGN_EPI) { if (wr == 0) PG8_BAR; }
;         if constexpr (!Epi::AFTER_DRAIN) { E(acc, cur, wr, wc, fr, fq); S.done(cur); }
;         if (!has_next) break;
	s_and_b64 vcc, exec, s[12:13]
	s_cbranch_vccz .LBB0_1804
	s_barrier
